# P2 conv prologue: bias and the first eight row loads issued ahead of the wait for the tap-weight staging loads (two cold latencies overlap)
# baseline (speedup 1.0000x reference)
.Lcv_pre_skip:
	v_readlane_b32 s0, v254, 41
	s_cmpk_gt_i32 s0, 0xfff
	s_cbranch_scc1 .LBB0_280
	v_mov_b32_e32 v86, 0
	v_readlane_b32 s4, v254, 23
	v_lshlrev_b32_e32 v2, 4, v199
	v_mov_b32_e32 v3, v86
	v_readlane_b32 s5, v254, 24
	v_mbcnt_lo_u32_b32 v1, -1, 0
	v_lshl_add_u64 v[88:89], s[64:65], 0, v[2:3]
	v_lshl_add_u64 v[92:93], s[62:63], 0, v[2:3]
	v_lshl_add_u64 v[94:95], s[66:67], 0, v[2:3]
	v_lshl_add_u64 v[96:97], s[4:5], 0, v[2:3]
	v_mbcnt_hi_u32_b32 v2, -1, v1
	v_and_b32_e32 v1, 64, v2
	v_add_u32_e32 v3, 64, v1
	v_xor_b32_e32 v1, 1, v2
	v_cmp_lt_i32_e32 vcc, v1, v3
	v_xor_b32_e32 v6, 2, v2
	v_readlane_b32 s1, v254, 40
	v_cndmask_b32_e32 v1, v2, v1, vcc
	v_cmp_lt_i32_e32 vcc, v6, v3
	s_lshl_b32 s0, s80, 5
	s_lshl_b32 s1, s1, 2
	v_cndmask_b32_e32 v6, v2, v6, vcc
	v_lshlrev_b32_e32 v162, 2, v6
	v_xor_b32_e32 v6, 4, v2
	v_cmp_lt_i32_e32 vcc, v6, v3
	v_lshlrev_b32_e32 v4, 3, v199
	v_mov_b32_e32 v5, v86
	v_cndmask_b32_e32 v6, v2, v6, vcc
	v_lshlrev_b32_e32 v163, 2, v6
	v_xor_b32_e32 v6, 8, v2
	v_cmp_lt_i32_e32 vcc, v6, v3
	v_readlane_b32 s8, v254, 27
	v_readlane_b32 s9, v254, 28
	v_cndmask_b32_e32 v6, v2, v6, vcc
	v_lshlrev_b32_e32 v164, 2, v6
	v_xor_b32_e32 v6, 16, v2
	v_cmp_lt_i32_e32 vcc, v6, v3
	v_readlane_b32 s10, v254, 29
	v_readlane_b32 s11, v254, 30
	v_cndmask_b32_e32 v6, v2, v6, vcc
	v_lshlrev_b32_e32 v165, 2, v6
	v_xor_b32_e32 v6, 32, v2
	v_cmp_lt_i32_e32 vcc, v6, v3
	v_readlane_b32 s12, v254, 31
	v_readlane_b32 s13, v254, 32
	v_readlane_b32 s14, v254, 33
	v_readlane_b32 s15, v254, 34
	v_cndmask_b32_e32 v2, v2, v6, vcc
	s_add_i32 s0, s0, s1
	v_lshl_add_u64 v[90:91], s[38:39], 0, v[4:5]
	v_lshlrev_b32_e32 v1, 2, v1
	v_lshlrev_b32_e32 v166, 2, v2
	v_lshl_add_u64 v[98:99], s[44:45], 0, v[4:5]
	s_sub_i32 s8, s0, 27
	s_lshl_b32 s9, s33, 5
	v_mov_b32_e32 v167, 0x600
	s_movk_i32 s10, 0x1000
	s_movk_i32 s11, 0x2000
	s_movk_i32 s12, 0x3000
	s_movk_i32 s13, 0x4000
	s_movk_i32 s14, 0x5000
	v_mov_b32_e32 v168, 0x3727c5ac
	v_readlane_b32 s15, v254, 41
	v_readlane_b32 s6, v254, 25
	v_readlane_b32 s7, v254, 26
	v_readlane_b32 s16, v254, 35
	v_readlane_b32 s17, v254, 36
	v_readlane_b32 s18, v254, 37
	v_readlane_b32 s19, v254, 38
	v_readlane_b32 s40, v254, 41
	v_readlane_b32 s42, v254, 23
	v_readlane_b32 s43, v254, 24
	v_lshlrev_b32_e32 v2, 4, v199
	v_lshlrev_b32_e32 v3, 3, v199
	s_cmpk_gt_u32 s40, 0x7ff
	s_cbranch_scc1 .Lcv_notask
	s_lshl_b32 s41, s40, 3
	s_mov_b64 s[50:51], s[62:63]
	v_add_u32_e32 v208, 0x10000, v2
	global_load_dwordx4 v[222:225], v2, s[64:65]
	global_load_dwordx4 v[226:229], v2, s[64:65] offset:1024
	global_load_dwordx4 v[230:233], v2, s[64:65] offset:2048
	s_add_i32 s52, s41, -30
	s_max_i32 s52, s52, 0
	s_mulk_i32 s52, 0x600
	v_add_u32_e32 v196, s52, v3
	global_load_dwordx2 v[234:235], v196, s[38:39]
	global_load_dwordx2 v[236:237], v196, s[38:39] offset:512
	global_load_dwordx2 v[238:239], v196, s[38:39] offset:1024
	s_add_i32 s52, s41, -29
	s_max_i32 s52, s52, 0
	s_mulk_i32 s52, 0x600
	v_add_u32_e32 v196, s52, v3
	global_load_dwordx2 v[240:241], v196, s[38:39]
	global_load_dwordx2 v[242:243], v196, s[38:39] offset:512
	global_load_dwordx2 v[244:245], v196, s[38:39] offset:1024
	s_add_i32 s52, s41, -28
	s_max_i32 s52, s52, 0
	s_mulk_i32 s52, 0x600
	v_add_u32_e32 v196, s52, v3
	global_load_dwordx2 v[246:247], v196, s[38:39]
	global_load_dwordx2 v[248:249], v196, s[38:39] offset:512
	global_load_dwordx2 v[250:251], v196, s[38:39] offset:1024
	s_add_i32 s52, s41, -27
	s_max_i32 s52, s52, 0
	s_mulk_i32 s52, 0x600
	v_add_u32_e32 v196, s52, v3
	global_load_dwordx2 v[204:205], v196, s[38:39]
	global_load_dwordx2 v[206:207], v196, s[38:39] offset:512
	global_load_dwordx2 v[252:253], v196, s[38:39] offset:1024
	s_add_i32 s52, s41, -26
	s_max_i32 s52, s52, 0
	s_mulk_i32 s52, 0x600
	v_add_u32_e32 v196, s52, v3
	global_load_dwordx2 v[154:155], v196, s[38:39]
	global_load_dwordx2 v[156:157], v196, s[38:39] offset:512
	global_load_dwordx2 v[158:159], v196, s[38:39] offset:1024
	s_add_i32 s52, s41, -25
	s_max_i32 s52, s52, 0
	s_mulk_i32 s52, 0x600
	v_add_u32_e32 v196, s52, v3
	global_load_dwordx2 v[166:167], v196, s[38:39]
	global_load_dwordx2 v[168:169], v196, s[38:39] offset:512
	global_load_dwordx2 v[170:171], v196, s[38:39] offset:1024
	s_add_i32 s52, s41, -24
	s_max_i32 s52, s52, 0
	s_mulk_i32 s52, 0x600
	v_add_u32_e32 v196, s52, v3
	global_load_dwordx2 v[178:179], v196, s[38:39]
	global_load_dwordx2 v[180:181], v196, s[38:39] offset:512
	global_load_dwordx2 v[182:183], v196, s[38:39] offset:1024
	s_add_i32 s52, s41, -23
	s_max_i32 s52, s52, 0
	s_mulk_i32 s52, 0x600
	v_add_u32_e32 v196, s52, v3
	global_load_dwordx2 v[190:191], v196, s[38:39]
	global_load_dwordx2 v[192:193], v196, s[38:39] offset:512
	global_load_dwordx2 v[194:195], v196, s[38:39] offset:1024
	v_readlane_b32 s4, v254, 40
	s_waitcnt vmcnt(27)
	v_mov_b32_e32 v101, v100
	ds_write_b128 v101, v[104:107]
	v_add_u32_e32 v101, 0x2000, v100
	ds_write_b128 v101, v[108:111]
	v_add_u32_e32 v101, 0x4000, v100
	ds_write_b128 v101, v[112:115]
	v_add_u32_e32 v101, 0x6000, v100
	ds_write_b128 v101, v[116:119]
	v_add_u32_e32 v101, 0x8000, v100
	ds_write_b128 v101, v[120:123]
	v_add_u32_e32 v101, 0xa000, v100
	ds_write_b128 v101, v[124:127]
	v_add_u32_e32 v101, 0xc000, v100
	ds_write_b128 v101, v[128:131]
	v_add_u32_e32 v101, 0xe000, v100
	ds_write_b128 v101, v[132:135]
	v_add_u32_e32 v101, 0x10000, v100
	ds_write_b128 v101, v[136:139]
	v_add_u32_e32 v101, 0x12000, v100
	ds_write_b128 v101, v[140:143]
	v_add_u32_e32 v101, 0x14000, v100
	ds_write_b128 v101, v[144:147]
	s_cmp_lt_u32 s4, 5
	s_cbranch_scc0 .Lcv_pre_skip2_a
	v_add_u32_e32 v101, 0x16000, v100
	ds_write_b128 v101, v[148:151]
.Lcv_pre_skip2_a:
	s_waitcnt lgkmcnt(0)
	s_barrier
	ds_read_b128 v[210:213], v2
	ds_read_b128 v[214:217], v2 offset:1024
	ds_read_b128 v[218:221], v2 offset:2048
	s_waitcnt vmcnt(24)
	v_mov_b32_e32 v4, v222
	v_mov_b32_e32 v5, v223
	v_mov_b32_e32 v6, v224
	v_mov_b32_e32 v7, v225
	v_mov_b32_e32 v8, v226
	v_mov_b32_e32 v9, v227
	v_mov_b32_e32 v10, v228
	v_mov_b32_e32 v11, v229
	v_mov_b32_e32 v12, v230
	v_mov_b32_e32 v13, v231
	v_mov_b32_e32 v14, v232
	v_mov_b32_e32 v15, v233
	v_mov_b32_e32 v16, v222
	v_mov_b32_e32 v17, v223
	v_mov_b32_e32 v18, v224
	v_mov_b32_e32 v19, v225
	v_mov_b32_e32 v20, v226
	v_mov_b32_e32 v21, v227
	v_mov_b32_e32 v22, v228
	v_mov_b32_e32 v23, v229
	v_mov_b32_e32 v24, v230
	v_mov_b32_e32 v25, v231
	v_mov_b32_e32 v26, v232
	v_mov_b32_e32 v27, v233
	v_mov_b32_e32 v28, v222
	v_mov_b32_e32 v29, v223
	v_mov_b32_e32 v30, v224
	v_mov_b32_e32 v31, v225
	v_mov_b32_e32 v32, v226
	v_mov_b32_e32 v33, v227
	v_mov_b32_e32 v34, v228
	v_mov_b32_e32 v35, v229
	v_mov_b32_e32 v36, v230
	v_mov_b32_e32 v37, v231
	v_mov_b32_e32 v38, v232
	v_mov_b32_e32 v39, v233
	v_mov_b32_e32 v40, v222
	v_mov_b32_e32 v41, v223
	v_mov_b32_e32 v42, v224
	v_mov_b32_e32 v43, v225
	v_mov_b32_e32 v44, v226
	v_mov_b32_e32 v45, v227
	v_mov_b32_e32 v46, v228
	v_mov_b32_e32 v47, v229
	v_mov_b32_e32 v48, v230
	v_mov_b32_e32 v49, v231
	v_mov_b32_e32 v50, v232
	v_mov_b32_e32 v51, v233
	v_mov_b32_e32 v52, v222
	v_mov_b32_e32 v53, v223
	v_mov_b32_e32 v54, v224
	v_mov_b32_e32 v55, v225
	v_mov_b32_e32 v56, v226
	v_mov_b32_e32 v57, v227
	v_mov_b32_e32 v58, v228
	v_mov_b32_e32 v59, v229
	v_mov_b32_e32 v60, v230
	v_mov_b32_e32 v61, v231
	v_mov_b32_e32 v62, v232
	v_mov_b32_e32 v63, v233
	v_mov_b32_e32 v64, v222
	v_mov_b32_e32 v65, v223
	v_mov_b32_e32 v66, v224
	v_mov_b32_e32 v67, v225
	v_mov_b32_e32 v68, v226
	v_mov_b32_e32 v69, v227
	v_mov_b32_e32 v70, v228
	v_mov_b32_e32 v71, v229
	v_mov_b32_e32 v72, v230
	v_mov_b32_e32 v73, v231
	v_mov_b32_e32 v74, v232
	v_mov_b32_e32 v75, v233
	v_mov_b32_e32 v76, v222
	v_mov_b32_e32 v77, v223
	v_mov_b32_e32 v78, v224
	v_mov_b32_e32 v79, v225
	v_mov_b32_e32 v80, v226
	v_mov_b32_e32 v81, v227
	v_mov_b32_e32 v82, v228
	v_mov_b32_e32 v83, v229
	v_mov_b32_e32 v84, v230
	v_mov_b32_e32 v85, v231
	v_mov_b32_e32 v86, v232
	v_mov_b32_e32 v87, v233
	v_mov_b32_e32 v88, v222
	v_mov_b32_e32 v89, v223
	v_mov_b32_e32 v90, v224
	v_mov_b32_e32 v91, v225
	v_mov_b32_e32 v92, v226
	v_mov_b32_e32 v93, v227
	v_mov_b32_e32 v94, v228
	v_mov_b32_e32 v95, v229
	v_mov_b32_e32 v96, v230
	v_mov_b32_e32 v97, v231
	v_mov_b32_e32 v98, v232
	v_mov_b32_e32 v99, v233
	ds_read_b128 v[222:225], v2 offset:3072
	ds_read_b128 v[226:229], v2 offset:4096
	ds_read_b128 v[230:233], v2 offset:5120
	s_waitcnt vmcnt(21)
	s_add_i32 s52, s41, -30
	s_cmp_lt_i32 s52, 0
	s_cbranch_scc1 .Lcv_z0_zero
	v_lshlrev_b32_e32 v100, 16, v234
	v_and_b32_e32 v101, 0xffff0000, v234
	v_lshlrev_b32_e32 v102, 16, v235
	v_and_b32_e32 v103, 0xffff0000, v235
	v_lshlrev_b32_e32 v104, 16, v236
	v_and_b32_e32 v105, 0xffff0000, v236
	v_lshlrev_b32_e32 v106, 16, v237
	v_and_b32_e32 v107, 0xffff0000, v237
	v_lshlrev_b32_e32 v108, 16, v238
	v_and_b32_e32 v109, 0xffff0000, v238
	v_lshlrev_b32_e32 v110, 16, v239
	v_and_b32_e32 v111, 0xffff0000, v239
	s_branch .Lcv_z0_done

.Lcv_z29_done:
	s_add_i32 s52, s41, 3
	s_mulk_i32 s52, 0x600
	v_add_u32_e32 v196, s52, v3
	global_load_dwordx2 v[240:241], v196, s[38:39]
	global_load_dwordx2 v[242:243], v196, s[38:39] offset:512
	global_load_dwordx2 v[244:245], v196, s[38:39] offset:1024
	s_waitcnt lgkmcnt(3)
	v_pk_fma_f32 v[4:5], v[172:173], v[210:211], v[4:5]
	v_pk_fma_f32 v[6:7], v[174:175], v[212:213], v[6:7]
	v_pk_fma_f32 v[8:9], v[176:177], v[214:215], v[8:9]
	v_pk_fma_f32 v[10:11], v[178:179], v[216:217], v[10:11]
	v_pk_fma_f32 v[12:13], v[180:181], v[218:219], v[12:13]
	v_pk_fma_f32 v[14:15], v[182:183], v[220:221], v[14:15]
	v_pk_fma_f32 v[16:17], v[184:185], v[210:211], v[16:17]
	v_pk_fma_f32 v[18:19], v[186:187], v[212:213], v[18:19]
	v_pk_fma_f32 v[20:21], v[188:189], v[214:215], v[20:21]
	v_pk_fma_f32 v[22:23], v[190:191], v[216:217], v[22:23]
	v_pk_fma_f32 v[24:25], v[192:193], v[218:219], v[24:25]
	v_pk_fma_f32 v[26:27], v[194:195], v[220:221], v[26:27]
	v_pk_fma_f32 v[28:29], v[100:101], v[210:211], v[28:29]
	v_pk_fma_f32 v[30:31], v[102:103], v[212:213], v[30:31]
	v_pk_fma_f32 v[32:33], v[104:105], v[214:215], v[32:33]
	v_pk_fma_f32 v[34:35], v[106:107], v[216:217], v[34:35]
	v_pk_fma_f32 v[36:37], v[108:109], v[218:219], v[36:37]
	v_pk_fma_f32 v[38:39], v[110:111], v[220:221], v[38:39]
	v_pk_fma_f32 v[40:41], v[112:113], v[210:211], v[40:41]
	v_pk_fma_f32 v[42:43], v[114:115], v[212:213], v[42:43]
	v_pk_fma_f32 v[44:45], v[116:117], v[214:215], v[44:45]
	v_pk_fma_f32 v[46:47], v[118:119], v[216:217], v[46:47]
	v_pk_fma_f32 v[48:49], v[120:121], v[218:219], v[48:49]
	v_pk_fma_f32 v[50:51], v[122:123], v[220:221], v[50:51]
	v_pk_fma_f32 v[52:53], v[124:125], v[210:211], v[52:53]
	v_pk_fma_f32 v[54:55], v[126:127], v[212:213], v[54:55]
	v_pk_fma_f32 v[56:57], v[128:129], v[214:215], v[56:57]
	v_pk_fma_f32 v[58:59], v[130:131], v[216:217], v[58:59]
	v_pk_fma_f32 v[60:61], v[132:133], v[218:219], v[60:61]
	v_pk_fma_f32 v[62:63], v[134:135], v[220:221], v[62:63]
	v_pk_fma_f32 v[64:65], v[136:137], v[210:211], v[64:65]
	v_pk_fma_f32 v[66:67], v[138:139], v[212:213], v[66:67]
	v_pk_fma_f32 v[68:69], v[140:141], v[214:215], v[68:69]
	v_pk_fma_f32 v[70:71], v[142:143], v[216:217], v[70:71]
	v_pk_fma_f32 v[72:73], v[144:145], v[218:219], v[72:73]
	v_pk_fma_f32 v[74:75], v[146:147], v[220:221], v[74:75]
	v_pk_fma_f32 v[76:77], v[148:149], v[210:211], v[76:77]
	v_pk_fma_f32 v[78:79], v[150:151], v[212:213], v[78:79]
	v_pk_fma_f32 v[80:81], v[152:153], v[214:215], v[80:81]
	v_pk_fma_f32 v[82:83], v[154:155], v[216:217], v[82:83]
	v_pk_fma_f32 v[84:85], v[156:157], v[218:219], v[84:85]
	v_pk_fma_f32 v[86:87], v[158:159], v[220:221], v[86:87]
	v_pk_fma_f32 v[88:89], v[160:161], v[210:211], v[88:89]
	v_pk_fma_f32 v[90:91], v[162:163], v[212:213], v[90:91]
	v_pk_fma_f32 v[92:93], v[164:165], v[214:215], v[92:93]
	v_pk_fma_f32 v[94:95], v[166:167], v[216:217], v[94:95]
	v_pk_fma_f32 v[96:97], v[168:169], v[218:219], v[96:97]
	v_pk_fma_f32 v[98:99], v[170:171], v[220:221], v[98:99]
	ds_read_b128 v[210:213], v208 offset:8192
	ds_read_b128 v[214:217], v208 offset:9216
	ds_read_b128 v[218:221], v208 offset:10240
	s_waitcnt vmcnt(9)
	v_lshlrev_b32_e32 v172, 16, v246
	v_and_b32_e32 v173, 0xffff0000, v246
	v_lshlrev_b32_e32 v174, 16, v247
	v_and_b32_e32 v175, 0xffff0000, v247
	v_lshlrev_b32_e32 v176, 16, v248
	v_and_b32_e32 v177, 0xffff0000, v248
	v_lshlrev_b32_e32 v178, 16, v249
	v_and_b32_e32 v179, 0xffff0000, v249
	v_lshlrev_b32_e32 v180, 16, v250
	v_and_b32_e32 v181, 0xffff0000, v250
	v_lshlrev_b32_e32 v182, 16, v251
	v_and_b32_e32 v183, 0xffff0000, v251
	s_add_i32 s52, s41, 4
	s_mulk_i32 s52, 0x600
	v_add_u32_e32 v196, s52, v3
	global_load_dwordx2 v[246:247], v196, s[38:39]
	global_load_dwordx2 v[248:249], v196, s[38:39] offset:512
	global_load_dwordx2 v[250:251], v196, s[38:39] offset:1024
	s_waitcnt lgkmcnt(3)
	v_pk_fma_f32 v[4:5], v[184:185], v[222:223], v[4:5]
	v_pk_fma_f32 v[6:7], v[186:187], v[224:225], v[6:7]
	v_pk_fma_f32 v[8:9], v[188:189], v[226:227], v[8:9]
	v_pk_fma_f32 v[10:11], v[190:191], v[228:229], v[10:11]
	v_pk_fma_f32 v[12:13], v[192:193], v[230:231], v[12:13]
	v_pk_fma_f32 v[14:15], v[194:195], v[232:233], v[14:15]
	v_pk_fma_f32 v[16:17], v[100:101], v[222:223], v[16:17]
	v_pk_fma_f32 v[18:19], v[102:103], v[224:225], v[18:19]
	v_pk_fma_f32 v[20:21], v[104:105], v[226:227], v[20:21]
	v_pk_fma_f32 v[22:23], v[106:107], v[228:229], v[22:23]
	v_pk_fma_f32 v[24:25], v[108:109], v[230:231], v[24:25]
	v_pk_fma_f32 v[26:27], v[110:111], v[232:233], v[26:27]
	v_pk_fma_f32 v[28:29], v[112:113], v[222:223], v[28:29]
	v_pk_fma_f32 v[30:31], v[114:115], v[224:225], v[30:31]
	v_pk_fma_f32 v[32:33], v[116:117], v[226:227], v[32:33]
	v_pk_fma_f32 v[34:35], v[118:119], v[228:229], v[34:35]
	v_pk_fma_f32 v[36:37], v[120:121], v[230:231], v[36:37]
	v_pk_fma_f32 v[38:39], v[122:123], v[232:233], v[38:39]
	v_pk_fma_f32 v[40:41], v[124:125], v[222:223], v[40:41]
	v_pk_fma_f32 v[42:43], v[126:127], v[224:225], v[42:43]
	v_pk_fma_f32 v[44:45], v[128:129], v[226:227], v[44:45]
	v_pk_fma_f32 v[46:47], v[130:131], v[228:229], v[46:47]
	v_pk_fma_f32 v[48:49], v[132:133], v[230:231], v[48:49]
	v_pk_fma_f32 v[50:51], v[134:135], v[232:233], v[50:51]
	v_pk_fma_f32 v[52:53], v[136:137], v[222:223], v[52:53]
	v_pk_fma_f32 v[54:55], v[138:139], v[224:225], v[54:55]
	v_pk_fma_f32 v[56:57], v[140:141], v[226:227], v[56:57]
	v_pk_fma_f32 v[58:59], v[142:143], v[228:229], v[58:59]
	v_pk_fma_f32 v[60:61], v[144:145], v[230:231], v[60:61]
	v_pk_fma_f32 v[62:63], v[146:147], v[232:233], v[62:63]
	v_pk_fma_f32 v[64:65], v[148:149], v[222:223], v[64:65]
	v_pk_fma_f32 v[66:67], v[150:151], v[224:225], v[66:67]
	v_pk_fma_f32 v[68:69], v[152:153], v[226:227], v[68:69]
	v_pk_fma_f32 v[70:71], v[154:155], v[228:229], v[70:71]
	v_pk_fma_f32 v[72:73], v[156:157], v[230:231], v[72:73]
	v_pk_fma_f32 v[74:75], v[158:159], v[232:233], v[74:75]
	v_pk_fma_f32 v[76:77], v[160:161], v[222:223], v[76:77]
	v_pk_fma_f32 v[78:79], v[162:163], v[224:225], v[78:79]
	v_pk_fma_f32 v[80:81], v[164:165], v[226:227], v[80:81]
	v_pk_fma_f32 v[82:83], v[166:167], v[228:229], v[82:83]
	v_pk_fma_f32 v[84:85], v[168:169], v[230:231], v[84:85]
	v_pk_fma_f32 v[86:87], v[170:171], v[232:233], v[86:87]
	v_pk_fma_f32 v[88:89], v[172:173], v[222:223], v[88:89]
	v_pk_fma_f32 v[90:91], v[174:175], v[224:225], v[90:91]
	v_pk_fma_f32 v[92:93], v[176:177], v[226:227], v[92:93]
	v_pk_fma_f32 v[94:95], v[178:179], v[228:229], v[94:95]
	v_pk_fma_f32 v[96:97], v[180:181], v[230:231], v[96:97]
	v_pk_fma_f32 v[98:99], v[182:183], v[232:233], v[98:99]
	ds_read_b128 v[222:225], v208 offset:11264
	ds_read_b128 v[226:229], v208 offset:12288
	ds_read_b128 v[230:233], v208 offset:13312
	s_waitcnt vmcnt(9)
	v_lshlrev_b32_e32 v184, 16, v204
	v_and_b32_e32 v185, 0xffff0000, v204
	v_lshlrev_b32_e32 v186, 16, v205
	v_and_b32_e32 v187, 0xffff0000, v205
	v_lshlrev_b32_e32 v188, 16, v206
	v_and_b32_e32 v189, 0xffff0000, v206
	v_lshlrev_b32_e32 v190, 16, v207
	v_and_b32_e32 v191, 0xffff0000, v207
	v_lshlrev_b32_e32 v192, 16, v252
	v_and_b32_e32 v193, 0xffff0000, v252
	v_lshlrev_b32_e32 v194, 16, v253
	v_and_b32_e32 v195, 0xffff0000, v253
	s_add_i32 s52, s41, 5
	s_mulk_i32 s52, 0x600
	v_add_u32_e32 v196, s52, v3
	global_load_dwordx2 v[204:205], v196, s[38:39]
	global_load_dwordx2 v[206:207], v196, s[38:39] offset:512
	global_load_dwordx2 v[252:253], v196, s[38:39] offset:1024
	s_waitcnt lgkmcnt(3)
	v_pk_fma_f32 v[4:5], v[100:101], v[210:211], v[4:5]
	v_pk_fma_f32 v[6:7], v[102:103], v[212:213], v[6:7]
	v_pk_fma_f32 v[8:9], v[104:105], v[214:215], v[8:9]
	v_pk_fma_f32 v[10:11], v[106:107], v[216:217], v[10:11]
	v_pk_fma_f32 v[12:13], v[108:109], v[218:219], v[12:13]
	v_pk_fma_f32 v[14:15], v[110:111], v[220:221], v[14:15]
	v_pk_fma_f32 v[16:17], v[112:113], v[210:211], v[16:17]
	v_pk_fma_f32 v[18:19], v[114:115], v[212:213], v[18:19]
	v_pk_fma_f32 v[20:21], v[116:117], v[214:215], v[20:21]
	v_pk_fma_f32 v[22:23], v[118:119], v[216:217], v[22:23]
	v_pk_fma_f32 v[24:25], v[120:121], v[218:219], v[24:25]
	v_pk_fma_f32 v[26:27], v[122:123], v[220:221], v[26:27]
	v_pk_fma_f32 v[28:29], v[124:125], v[210:211], v[28:29]
	v_pk_fma_f32 v[30:31], v[126:127], v[212:213], v[30:31]
	v_pk_fma_f32 v[32:33], v[128:129], v[214:215], v[32:33]
	v_pk_fma_f32 v[34:35], v[130:131], v[216:217], v[34:35]
	v_pk_fma_f32 v[36:37], v[132:133], v[218:219], v[36:37]
	v_pk_fma_f32 v[38:39], v[134:135], v[220:221], v[38:39]
	v_pk_fma_f32 v[40:41], v[136:137], v[210:211], v[40:41]
	v_pk_fma_f32 v[42:43], v[138:139], v[212:213], v[42:43]
	v_pk_fma_f32 v[44:45], v[140:141], v[214:215], v[44:45]
	v_pk_fma_f32 v[46:47], v[142:143], v[216:217], v[46:47]
	v_pk_fma_f32 v[48:49], v[144:145], v[218:219], v[48:49]
	v_pk_fma_f32 v[50:51], v[146:147], v[220:221], v[50:51]
	v_pk_fma_f32 v[52:53], v[148:149], v[210:211], v[52:53]
	v_pk_fma_f32 v[54:55], v[150:151], v[212:213], v[54:55]
	v_pk_fma_f32 v[56:57], v[152:153], v[214:215], v[56:57]
	v_pk_fma_f32 v[58:59], v[154:155], v[216:217], v[58:59]
	v_pk_fma_f32 v[60:61], v[156:157], v[218:219], v[60:61]
	v_pk_fma_f32 v[62:63], v[158:159], v[220:221], v[62:63]
	v_pk_fma_f32 v[64:65], v[160:161], v[210:211], v[64:65]
	v_pk_fma_f32 v[66:67], v[162:163], v[212:213], v[66:67]
	v_pk_fma_f32 v[68:69], v[164:165], v[214:215], v[68:69]
	v_pk_fma_f32 v[70:71], v[166:167], v[216:217], v[70:71]
	v_pk_fma_f32 v[72:73], v[168:169], v[218:219], v[72:73]
	v_pk_fma_f32 v[74:75], v[170:171], v[220:221], v[74:75]
	v_pk_fma_f32 v[76:77], v[172:173], v[210:211], v[76:77]
	v_pk_fma_f32 v[78:79], v[174:175], v[212:213], v[78:79]
	v_pk_fma_f32 v[80:81], v[176:177], v[214:215], v[80:81]
	v_pk_fma_f32 v[82:83], v[178:179], v[216:217], v[82:83]
	v_pk_fma_f32 v[84:85], v[180:181], v[218:219], v[84:85]
	v_pk_fma_f32 v[86:87], v[182:183], v[220:221], v[86:87]
	v_pk_fma_f32 v[88:89], v[184:185], v[210:211], v[88:89]
	v_pk_fma_f32 v[90:91], v[186:187], v[212:213], v[90:91]
	v_pk_fma_f32 v[92:93], v[188:189], v[214:215], v[92:93]
	v_pk_fma_f32 v[94:95], v[190:191], v[216:217], v[94:95]
	v_pk_fma_f32 v[96:97], v[192:193], v[218:219], v[96:97]
	v_pk_fma_f32 v[98:99], v[194:195], v[220:221], v[98:99]
	ds_read_b128 v[210:213], v208 offset:14336
	ds_read_b128 v[214:217], v208 offset:15360
	ds_read_b128 v[218:221], v208 offset:16384
	s_waitcnt vmcnt(9)
	v_lshlrev_b32_e32 v100, 16, v234
	v_and_b32_e32 v101, 0xffff0000, v234
	v_lshlrev_b32_e32 v102, 16, v235
	v_and_b32_e32 v103, 0xffff0000, v235
	v_lshlrev_b32_e32 v104, 16, v236
	v_and_b32_e32 v105, 0xffff0000, v236
	v_lshlrev_b32_e32 v106, 16, v237
	v_and_b32_e32 v107, 0xffff0000, v237
	v_lshlrev_b32_e32 v108, 16, v238
	v_and_b32_e32 v109, 0xffff0000, v238
	v_lshlrev_b32_e32 v110, 16, v239
	v_and_b32_e32 v111, 0xffff0000, v239
	s_add_i32 s52, s41, 6
	s_mulk_i32 s52, 0x600
	v_add_u32_e32 v196, s52, v3
	global_load_dwordx2 v[234:235], v196, s[38:39]
	global_load_dwordx2 v[236:237], v196, s[38:39] offset:512
	global_load_dwordx2 v[238:239], v196, s[38:39] offset:1024
	s_waitcnt lgkmcnt(3)
	v_pk_fma_f32 v[4:5], v[112:113], v[222:223], v[4:5]
	v_pk_fma_f32 v[6:7], v[114:115], v[224:225], v[6:7]
	v_pk_fma_f32 v[8:9], v[116:117], v[226:227], v[8:9]
	v_pk_fma_f32 v[10:11], v[118:119], v[228:229], v[10:11]
	v_pk_fma_f32 v[12:13], v[120:121], v[230:231], v[12:13]
	v_pk_fma_f32 v[14:15], v[122:123], v[232:233], v[14:15]
	v_pk_fma_f32 v[16:17], v[124:125], v[222:223], v[16:17]
	v_pk_fma_f32 v[18:19], v[126:127], v[224:225], v[18:19]
	v_pk_fma_f32 v[20:21], v[128:129], v[226:227], v[20:21]
	v_pk_fma_f32 v[22:23], v[130:131], v[228:229], v[22:23]
	v_pk_fma_f32 v[24:25], v[132:133], v[230:231], v[24:25]
	v_pk_fma_f32 v[26:27], v[134:135], v[232:233], v[26:27]
	v_pk_fma_f32 v[28:29], v[136:137], v[222:223], v[28:29]
	v_pk_fma_f32 v[30:31], v[138:139], v[224:225], v[30:31]
	v_pk_fma_f32 v[32:33], v[140:141], v[226:227], v[32:33]
	v_pk_fma_f32 v[34:35], v[142:143], v[228:229], v[34:35]
	v_pk_fma_f32 v[36:37], v[144:145], v[230:231], v[36:37]
	v_pk_fma_f32 v[38:39], v[146:147], v[232:233], v[38:39]
	v_pk_fma_f32 v[40:41], v[148:149], v[222:223], v[40:41]
	v_pk_fma_f32 v[42:43], v[150:151], v[224:225], v[42:43]
	v_pk_fma_f32 v[44:45], v[152:153], v[226:227], v[44:45]
	v_pk_fma_f32 v[46:47], v[154:155], v[228:229], v[46:47]
	v_pk_fma_f32 v[48:49], v[156:157], v[230:231], v[48:49]
	v_pk_fma_f32 v[50:51], v[158:159], v[232:233], v[50:51]
	v_pk_fma_f32 v[52:53], v[160:161], v[222:223], v[52:53]
	v_pk_fma_f32 v[54:55], v[162:163], v[224:225], v[54:55]
	v_pk_fma_f32 v[56:57], v[164:165], v[226:227], v[56:57]
	v_pk_fma_f32 v[58:59], v[166:167], v[228:229], v[58:59]
	v_pk_fma_f32 v[60:61], v[168:169], v[230:231], v[60:61]
	v_pk_fma_f32 v[62:63], v[170:171], v[232:233], v[62:63]
	v_pk_fma_f32 v[64:65], v[172:173], v[222:223], v[64:65]
	v_pk_fma_f32 v[66:67], v[174:175], v[224:225], v[66:67]
	v_pk_fma_f32 v[68:69], v[176:177], v[226:227], v[68:69]
	v_pk_fma_f32 v[70:71], v[178:179], v[228:229], v[70:71]
	v_pk_fma_f32 v[72:73], v[180:181], v[230:231], v[72:73]
	v_pk_fma_f32 v[74:75], v[182:183], v[232:233], v[74:75]
	v_pk_fma_f32 v[76:77], v[184:185], v[222:223], v[76:77]
	v_pk_fma_f32 v[78:79], v[186:187], v[224:225], v[78:79]
	v_pk_fma_f32 v[80:81], v[188:189], v[226:227], v[80:81]
	v_pk_fma_f32 v[82:83], v[190:191], v[228:229], v[82:83]
	v_pk_fma_f32 v[84:85], v[192:193], v[230:231], v[84:85]
	v_pk_fma_f32 v[86:87], v[194:195], v[232:233], v[86:87]
	v_pk_fma_f32 v[88:89], v[100:101], v[222:223], v[88:89]
	v_pk_fma_f32 v[90:91], v[102:103], v[224:225], v[90:91]
	v_pk_fma_f32 v[92:93], v[104:105], v[226:227], v[92:93]
	v_pk_fma_f32 v[94:95], v[106:107], v[228:229], v[94:95]
	v_pk_fma_f32 v[96:97], v[108:109], v[230:231], v[96:97]
	v_pk_fma_f32 v[98:99], v[110:111], v[232:233], v[98:99]
	ds_read_b128 v[222:225], v208 offset:17408
	ds_read_b128 v[226:229], v208 offset:18432
	ds_read_b128 v[230:233], v208 offset:19456
	s_waitcnt vmcnt(9)
	v_lshlrev_b32_e32 v112, 16, v240
	v_and_b32_e32 v113, 0xffff0000, v240
	v_lshlrev_b32_e32 v114, 16, v241
	v_and_b32_e32 v115, 0xffff0000, v241
	v_lshlrev_b32_e32 v116, 16, v242
	v_and_b32_e32 v117, 0xffff0000, v242
	v_lshlrev_b32_e32 v118, 16, v243
	v_and_b32_e32 v119, 0xffff0000, v243
	v_lshlrev_b32_e32 v120, 16, v244
	v_and_b32_e32 v121, 0xffff0000, v244
	v_lshlrev_b32_e32 v122, 16, v245
	v_and_b32_e32 v123, 0xffff0000, v245
	s_add_i32 s52, s41, 7
	s_mulk_i32 s52, 0x600
	v_add_u32_e32 v196, s52, v3
	global_load_dwordx2 v[240:241], v196, s[38:39]
	global_load_dwordx2 v[242:243], v196, s[38:39] offset:512
	global_load_dwordx2 v[244:245], v196, s[38:39] offset:1024
	s_waitcnt lgkmcnt(3)
	v_pk_fma_f32 v[4:5], v[124:125], v[210:211], v[4:5]
	v_pk_fma_f32 v[6:7], v[126:127], v[212:213], v[6:7]
	v_pk_fma_f32 v[8:9], v[128:129], v[214:215], v[8:9]
	v_pk_fma_f32 v[10:11], v[130:131], v[216:217], v[10:11]
	v_pk_fma_f32 v[12:13], v[132:133], v[218:219], v[12:13]
	v_pk_fma_f32 v[14:15], v[134:135], v[220:221], v[14:15]
	v_pk_fma_f32 v[16:17], v[136:137], v[210:211], v[16:17]
	v_pk_fma_f32 v[18:19], v[138:139], v[212:213], v[18:19]
	v_pk_fma_f32 v[20:21], v[140:141], v[214:215], v[20:21]
	v_pk_fma_f32 v[22:23], v[142:143], v[216:217], v[22:23]
	v_pk_fma_f32 v[24:25], v[144:145], v[218:219], v[24:25]
	v_pk_fma_f32 v[26:27], v[146:147], v[220:221], v[26:27]
	v_pk_fma_f32 v[28:29], v[148:149], v[210:211], v[28:29]
	v_pk_fma_f32 v[30:31], v[150:151], v[212:213], v[30:31]
	v_pk_fma_f32 v[32:33], v[152:153], v[214:215], v[32:33]
	v_pk_fma_f32 v[34:35], v[154:155], v[216:217], v[34:35]
	v_pk_fma_f32 v[36:37], v[156:157], v[218:219], v[36:37]
	v_pk_fma_f32 v[38:39], v[158:159], v[220:221], v[38:39]
	v_pk_fma_f32 v[40:41], v[160:161], v[210:211], v[40:41]
	v_pk_fma_f32 v[42:43], v[162:163], v[212:213], v[42:43]
	v_pk_fma_f32 v[44:45], v[164:165], v[214:215], v[44:45]
	v_pk_fma_f32 v[46:47], v[166:167], v[216:217], v[46:47]
	v_pk_fma_f32 v[48:49], v[168:169], v[218:219], v[48:49]
	v_pk_fma_f32 v[50:51], v[170:171], v[220:221], v[50:51]
	v_pk_fma_f32 v[52:53], v[172:173], v[210:211], v[52:53]
	v_pk_fma_f32 v[54:55], v[174:175], v[212:213], v[54:55]
	v_pk_fma_f32 v[56:57], v[176:177], v[214:215], v[56:57]
	v_pk_fma_f32 v[58:59], v[178:179], v[216:217], v[58:59]
	v_pk_fma_f32 v[60:61], v[180:181], v[218:219], v[60:61]
	v_pk_fma_f32 v[62:63], v[182:183], v[220:221], v[62:63]
	v_pk_fma_f32 v[64:65], v[184:185], v[210:211], v[64:65]
	v_pk_fma_f32 v[66:67], v[186:187], v[212:213], v[66:67]
	v_pk_fma_f32 v[68:69], v[188:189], v[214:215], v[68:69]
	v_pk_fma_f32 v[70:71], v[190:191], v[216:217], v[70:71]
	v_pk_fma_f32 v[72:73], v[192:193], v[218:219], v[72:73]
	v_pk_fma_f32 v[74:75], v[194:195], v[220:221], v[74:75]
	v_pk_fma_f32 v[76:77], v[100:101], v[210:211], v[76:77]
	v_pk_fma_f32 v[78:79], v[102:103], v[212:213], v[78:79]
	v_pk_fma_f32 v[80:81], v[104:105], v[214:215], v[80:81]
	v_pk_fma_f32 v[82:83], v[106:107], v[216:217], v[82:83]
	v_pk_fma_f32 v[84:85], v[108:109], v[218:219], v[84:85]
	v_pk_fma_f32 v[86:87], v[110:111], v[220:221], v[86:87]
	v_pk_fma_f32 v[88:89], v[112:113], v[210:211], v[88:89]
	v_pk_fma_f32 v[90:91], v[114:115], v[212:213], v[90:91]
	v_pk_fma_f32 v[92:93], v[116:117], v[214:215], v[92:93]
	v_pk_fma_f32 v[94:95], v[118:119], v[216:217], v[94:95]
	v_pk_fma_f32 v[96:97], v[120:121], v[218:219], v[96:97]
	v_pk_fma_f32 v[98:99], v[122:123], v[220:221], v[98:99]
	ds_read_b128 v[210:213], v208 offset:20480
	ds_read_b128 v[214:217], v208 offset:21504
	ds_read_b128 v[218:221], v208 offset:22528
	s_waitcnt vmcnt(9)
	v_lshlrev_b32_e32 v124, 16, v246
	v_and_b32_e32 v125, 0xffff0000, v246
	v_lshlrev_b32_e32 v126, 16, v247
	v_and_b32_e32 v127, 0xffff0000, v247
	v_lshlrev_b32_e32 v128, 16, v248
	v_and_b32_e32 v129, 0xffff0000, v248
	v_lshlrev_b32_e32 v130, 16, v249
	v_and_b32_e32 v131, 0xffff0000, v249
	v_lshlrev_b32_e32 v132, 16, v250
	v_and_b32_e32 v133, 0xffff0000, v250
	v_lshlrev_b32_e32 v134, 16, v251
	v_and_b32_e32 v135, 0xffff0000, v251
	s_waitcnt lgkmcnt(3)
	v_pk_fma_f32 v[4:5], v[136:137], v[222:223], v[4:5]
	v_pk_fma_f32 v[6:7], v[138:139], v[224:225], v[6:7]
	v_pk_fma_f32 v[8:9], v[140:141], v[226:227], v[8:9]
	v_pk_fma_f32 v[10:11], v[142:143], v[228:229], v[10:11]
	v_pk_fma_f32 v[12:13], v[144:145], v[230:231], v[12:13]
	v_pk_fma_f32 v[14:15], v[146:147], v[232:233], v[14:15]
	v_pk_fma_f32 v[16:17], v[148:149], v[222:223], v[16:17]
	v_pk_fma_f32 v[18:19], v[150:151], v[224:225], v[18:19]
	v_pk_fma_f32 v[20:21], v[152:153], v[226:227], v[20:21]
	v_pk_fma_f32 v[22:23], v[154:155], v[228:229], v[22:23]
	v_pk_fma_f32 v[24:25], v[156:157], v[230:231], v[24:25]
	v_pk_fma_f32 v[26:27], v[158:159], v[232:233], v[26:27]
	v_pk_fma_f32 v[28:29], v[160:161], v[222:223], v[28:29]
	v_pk_fma_f32 v[30:31], v[162:163], v[224:225], v[30:31]
	v_pk_fma_f32 v[32:33], v[164:165], v[226:227], v[32:33]
	v_pk_fma_f32 v[34:35], v[166:167], v[228:229], v[34:35]
	v_pk_fma_f32 v[36:37], v[168:169], v[230:231], v[36:37]
	v_pk_fma_f32 v[38:39], v[170:171], v[232:233], v[38:39]
	v_pk_fma_f32 v[40:41], v[172:173], v[222:223], v[40:41]
	v_pk_fma_f32 v[42:43], v[174:175], v[224:225], v[42:43]
	v_pk_fma_f32 v[44:45], v[176:177], v[226:227], v[44:45]
	v_pk_fma_f32 v[46:47], v[178:179], v[228:229], v[46:47]
	v_pk_fma_f32 v[48:49], v[180:181], v[230:231], v[48:49]
	v_pk_fma_f32 v[50:51], v[182:183], v[232:233], v[50:51]
	v_pk_fma_f32 v[52:53], v[184:185], v[222:223], v[52:53]
	v_pk_fma_f32 v[54:55], v[186:187], v[224:225], v[54:55]
	v_pk_fma_f32 v[56:57], v[188:189], v[226:227], v[56:57]
	v_pk_fma_f32 v[58:59], v[190:191], v[228:229], v[58:59]
	v_pk_fma_f32 v[60:61], v[192:193], v[230:231], v[60:61]
	v_pk_fma_f32 v[62:63], v[194:195], v[232:233], v[62:63]
	v_pk_fma_f32 v[64:65], v[100:101], v[222:223], v[64:65]
	v_pk_fma_f32 v[66:67], v[102:103], v[224:225], v[66:67]
	v_pk_fma_f32 v[68:69], v[104:105], v[226:227], v[68:69]
	v_pk_fma_f32 v[70:71], v[106:107], v[228:229], v[70:71]
	v_pk_fma_f32 v[72:73], v[108:109], v[230:231], v[72:73]
	v_pk_fma_f32 v[74:75], v[110:111], v[232:233], v[74:75]
	v_pk_fma_f32 v[76:77], v[112:113], v[222:223], v[76:77]
	v_pk_fma_f32 v[78:79], v[114:115], v[224:225], v[78:79]
	v_pk_fma_f32 v[80:81], v[116:117], v[226:227], v[80:81]
	v_pk_fma_f32 v[82:83], v[118:119], v[228:229], v[82:83]
	v_pk_fma_f32 v[84:85], v[120:121], v[230:231], v[84:85]
	v_pk_fma_f32 v[86:87], v[122:123], v[232:233], v[86:87]
	v_pk_fma_f32 v[88:89], v[124:125], v[222:223], v[88:89]
	v_pk_fma_f32 v[90:91], v[126:127], v[224:225], v[90:91]
	v_pk_fma_f32 v[92:93], v[128:129], v[226:227], v[92:93]
	v_pk_fma_f32 v[94:95], v[130:131], v[228:229], v[94:95]
	v_pk_fma_f32 v[96:97], v[132:133], v[230:231], v[96:97]
	v_pk_fma_f32 v[98:99], v[134:135], v[232:233], v[98:99]
	ds_read_b128 v[222:225], v208 offset:23552
	ds_read_b128 v[226:229], v208 offset:24576
	ds_read_b128 v[230:233], v208 offset:25600
	s_waitcnt vmcnt(6)
	v_lshlrev_b32_e32 v136, 16, v204
	v_and_b32_e32 v137, 0xffff0000, v204
	v_lshlrev_b32_e32 v138, 16, v205
	v_and_b32_e32 v139, 0xffff0000, v205
	v_lshlrev_b32_e32 v140, 16, v206
	v_and_b32_e32 v141, 0xffff0000, v206
	v_lshlrev_b32_e32 v142, 16, v207
	v_and_b32_e32 v143, 0xffff0000, v207
	v_lshlrev_b32_e32 v144, 16, v252
	v_and_b32_e32 v145, 0xffff0000, v252
	v_lshlrev_b32_e32 v146, 16, v253
	v_and_b32_e32 v147, 0xffff0000, v253
	s_waitcnt lgkmcnt(3)
	v_pk_fma_f32 v[4:5], v[148:149], v[210:211], v[4:5]
	v_pk_fma_f32 v[6:7], v[150:151], v[212:213], v[6:7]
	v_pk_fma_f32 v[8:9], v[152:153], v[214:215], v[8:9]
	v_pk_fma_f32 v[10:11], v[154:155], v[216:217], v[10:11]
	v_pk_fma_f32 v[12:13], v[156:157], v[218:219], v[12:13]
	v_pk_fma_f32 v[14:15], v[158:159], v[220:221], v[14:15]
	v_pk_fma_f32 v[16:17], v[160:161], v[210:211], v[16:17]
	v_pk_fma_f32 v[18:19], v[162:163], v[212:213], v[18:19]
	v_pk_fma_f32 v[20:21], v[164:165], v[214:215], v[20:21]
	v_pk_fma_f32 v[22:23], v[166:167], v[216:217], v[22:23]
	v_pk_fma_f32 v[24:25], v[168:169], v[218:219], v[24:25]
	v_pk_fma_f32 v[26:27], v[170:171], v[220:221], v[26:27]
	v_pk_fma_f32 v[28:29], v[172:173], v[210:211], v[28:29]
	v_pk_fma_f32 v[30:31], v[174:175], v[212:213], v[30:31]
	v_pk_fma_f32 v[32:33], v[176:177], v[214:215], v[32:33]
	v_pk_fma_f32 v[34:35], v[178:179], v[216:217], v[34:35]
	v_pk_fma_f32 v[36:37], v[180:181], v[218:219], v[36:37]
	v_pk_fma_f32 v[38:39], v[182:183], v[220:221], v[38:39]
	v_pk_fma_f32 v[40:41], v[184:185], v[210:211], v[40:41]
	v_pk_fma_f32 v[42:43], v[186:187], v[212:213], v[42:43]
	v_pk_fma_f32 v[44:45], v[188:189], v[214:215], v[44:45]
	v_pk_fma_f32 v[46:47], v[190:191], v[216:217], v[46:47]
	v_pk_fma_f32 v[48:49], v[192:193], v[218:219], v[48:49]
	v_pk_fma_f32 v[50:51], v[194:195], v[220:221], v[50:51]
	v_pk_fma_f32 v[52:53], v[100:101], v[210:211], v[52:53]
	v_pk_fma_f32 v[54:55], v[102:103], v[212:213], v[54:55]
	v_pk_fma_f32 v[56:57], v[104:105], v[214:215], v[56:57]
	v_pk_fma_f32 v[58:59], v[106:107], v[216:217], v[58:59]
	v_pk_fma_f32 v[60:61], v[108:109], v[218:219], v[60:61]
	v_pk_fma_f32 v[62:63], v[110:111], v[220:221], v[62:63]
	v_pk_fma_f32 v[64:65], v[112:113], v[210:211], v[64:65]
	v_pk_fma_f32 v[66:67], v[114:115], v[212:213], v[66:67]
	v_pk_fma_f32 v[68:69], v[116:117], v[214:215], v[68:69]
	v_pk_fma_f32 v[70:71], v[118:119], v[216:217], v[70:71]
	v_pk_fma_f32 v[72:73], v[120:121], v[218:219], v[72:73]
	v_pk_fma_f32 v[74:75], v[122:123], v[220:221], v[74:75]
	v_pk_fma_f32 v[76:77], v[124:125], v[210:211], v[76:77]
	v_pk_fma_f32 v[78:79], v[126:127], v[212:213], v[78:79]
	v_pk_fma_f32 v[80:81], v[128:129], v[214:215], v[80:81]
	v_pk_fma_f32 v[82:83], v[130:131], v[216:217], v[82:83]
	v_pk_fma_f32 v[84:85], v[132:133], v[218:219], v[84:85]
	v_pk_fma_f32 v[86:87], v[134:135], v[220:221], v[86:87]
	v_pk_fma_f32 v[88:89], v[136:137], v[210:211], v[88:89]
	v_pk_fma_f32 v[90:91], v[138:139], v[212:213], v[90:91]
	v_pk_fma_f32 v[92:93], v[140:141], v[214:215], v[92:93]
	v_pk_fma_f32 v[94:95], v[142:143], v[216:217], v[94:95]
	v_pk_fma_f32 v[96:97], v[144:145], v[218:219], v[96:97]
	v_pk_fma_f32 v[98:99], v[146:147], v[220:221], v[98:99]
	ds_read_b128 v[210:213], v208 offset:26624
	ds_read_b128 v[214:217], v208 offset:27648
	ds_read_b128 v[218:221], v208 offset:28672
	s_waitcnt vmcnt(3)
	v_lshlrev_b32_e32 v148, 16, v234
	v_and_b32_e32 v149, 0xffff0000, v234
	v_lshlrev_b32_e32 v150, 16, v235
	v_and_b32_e32 v151, 0xffff0000, v235
	v_lshlrev_b32_e32 v152, 16, v236
	v_and_b32_e32 v153, 0xffff0000, v236
	v_lshlrev_b32_e32 v154, 16, v237
	v_and_b32_e32 v155, 0xffff0000, v237
	v_lshlrev_b32_e32 v156, 16, v238
	v_and_b32_e32 v157, 0xffff0000, v238
	v_lshlrev_b32_e32 v158, 16, v239
	v_and_b32_e32 v159, 0xffff0000, v239
	s_waitcnt lgkmcnt(3)
	v_pk_fma_f32 v[4:5], v[160:161], v[222:223], v[4:5]
	v_pk_fma_f32 v[6:7], v[162:163], v[224:225], v[6:7]
	v_pk_fma_f32 v[8:9], v[164:165], v[226:227], v[8:9]
	v_pk_fma_f32 v[10:11], v[166:167], v[228:229], v[10:11]
	v_pk_fma_f32 v[12:13], v[168:169], v[230:231], v[12:13]
	v_pk_fma_f32 v[14:15], v[170:171], v[232:233], v[14:15]
	v_pk_fma_f32 v[16:17], v[172:173], v[222:223], v[16:17]
	v_pk_fma_f32 v[18:19], v[174:175], v[224:225], v[18:19]
	v_pk_fma_f32 v[20:21], v[176:177], v[226:227], v[20:21]
	v_pk_fma_f32 v[22:23], v[178:179], v[228:229], v[22:23]
	v_pk_fma_f32 v[24:25], v[180:181], v[230:231], v[24:25]
	v_pk_fma_f32 v[26:27], v[182:183], v[232:233], v[26:27]
	v_pk_fma_f32 v[28:29], v[184:185], v[222:223], v[28:29]
	v_pk_fma_f32 v[30:31], v[186:187], v[224:225], v[30:31]
	v_pk_fma_f32 v[32:33], v[188:189], v[226:227], v[32:33]
	v_pk_fma_f32 v[34:35], v[190:191], v[228:229], v[34:35]
	v_pk_fma_f32 v[36:37], v[192:193], v[230:231], v[36:37]
	v_pk_fma_f32 v[38:39], v[194:195], v[232:233], v[38:39]
	v_pk_fma_f32 v[40:41], v[100:101], v[222:223], v[40:41]
	v_pk_fma_f32 v[42:43], v[102:103], v[224:225], v[42:43]
	v_pk_fma_f32 v[44:45], v[104:105], v[226:227], v[44:45]
	v_pk_fma_f32 v[46:47], v[106:107], v[228:229], v[46:47]
	v_pk_fma_f32 v[48:49], v[108:109], v[230:231], v[48:49]
	v_pk_fma_f32 v[50:51], v[110:111], v[232:233], v[50:51]
	v_pk_fma_f32 v[52:53], v[112:113], v[222:223], v[52:53]
	v_pk_fma_f32 v[54:55], v[114:115], v[224:225], v[54:55]
	v_pk_fma_f32 v[56:57], v[116:117], v[226:227], v[56:57]
	v_pk_fma_f32 v[58:59], v[118:119], v[228:229], v[58:59]
	v_pk_fma_f32 v[60:61], v[120:121], v[230:231], v[60:61]
	v_pk_fma_f32 v[62:63], v[122:123], v[232:233], v[62:63]
	v_pk_fma_f32 v[64:65], v[124:125], v[222:223], v[64:65]
	v_pk_fma_f32 v[66:67], v[126:127], v[224:225], v[66:67]
	v_pk_fma_f32 v[68:69], v[128:129], v[226:227], v[68:69]
	v_pk_fma_f32 v[70:71], v[130:131], v[228:229], v[70:71]
	v_pk_fma_f32 v[72:73], v[132:133], v[230:231], v[72:73]
	v_pk_fma_f32 v[74:75], v[134:135], v[232:233], v[74:75]
	v_pk_fma_f32 v[76:77], v[136:137], v[222:223], v[76:77]
	v_pk_fma_f32 v[78:79], v[138:139], v[224:225], v[78:79]
	v_pk_fma_f32 v[80:81], v[140:141], v[226:227], v[80:81]
	v_pk_fma_f32 v[82:83], v[142:143], v[228:229], v[82:83]
	v_pk_fma_f32 v[84:85], v[144:145], v[230:231], v[84:85]
	v_pk_fma_f32 v[86:87], v[146:147], v[232:233], v[86:87]
	v_pk_fma_f32 v[88:89], v[148:149], v[222:223], v[88:89]
	v_pk_fma_f32 v[90:91], v[150:151], v[224:225], v[90:91]
	v_pk_fma_f32 v[92:93], v[152:153], v[226:227], v[92:93]
	v_pk_fma_f32 v[94:95], v[154:155], v[228:229], v[94:95]
	v_pk_fma_f32 v[96:97], v[156:157], v[230:231], v[96:97]
	v_pk_fma_f32 v[98:99], v[158:159], v[232:233], v[98:99]
	s_waitcnt vmcnt(0)
	v_lshlrev_b32_e32 v160, 16, v240
	v_and_b32_e32 v161, 0xffff0000, v240
	v_lshlrev_b32_e32 v162, 16, v241
	v_and_b32_e32 v163, 0xffff0000, v241
	v_lshlrev_b32_e32 v164, 16, v242
	v_and_b32_e32 v165, 0xffff0000, v242
	v_lshlrev_b32_e32 v166, 16, v243
	v_and_b32_e32 v167, 0xffff0000, v243
	v_lshlrev_b32_e32 v168, 16, v244
	v_and_b32_e32 v169, 0xffff0000, v244
	v_lshlrev_b32_e32 v170, 16, v245
	v_and_b32_e32 v171, 0xffff0000, v245
	global_load_dwordx4 v[222:225], v2, s[66:67]
	global_load_dwordx4 v[226:229], v2, s[66:67] offset:1024
	global_load_dwordx4 v[230:233], v2, s[66:67] offset:2048
	global_load_dwordx4 v[234:237], v2, s[42:43]
	global_load_dwordx4 v[238:241], v2, s[42:43] offset:1024
	global_load_dwordx4 v[242:245], v2, s[42:43] offset:2048
	s_waitcnt lgkmcnt(0)
	v_pk_fma_f32 v[4:5], v[172:173], v[210:211], v[4:5]
	v_pk_fma_f32 v[6:7], v[174:175], v[212:213], v[6:7]
	v_pk_fma_f32 v[8:9], v[176:177], v[214:215], v[8:9]
	v_pk_fma_f32 v[10:11], v[178:179], v[216:217], v[10:11]
	v_pk_fma_f32 v[12:13], v[180:181], v[218:219], v[12:13]
	v_pk_fma_f32 v[14:15], v[182:183], v[220:221], v[14:15]
	v_pk_fma_f32 v[16:17], v[184:185], v[210:211], v[16:17]
	v_pk_fma_f32 v[18:19], v[186:187], v[212:213], v[18:19]
	v_pk_fma_f32 v[20:21], v[188:189], v[214:215], v[20:21]
	v_pk_fma_f32 v[22:23], v[190:191], v[216:217], v[22:23]
	v_pk_fma_f32 v[24:25], v[192:193], v[218:219], v[24:25]
	v_pk_fma_f32 v[26:27], v[194:195], v[220:221], v[26:27]
	v_pk_fma_f32 v[28:29], v[100:101], v[210:211], v[28:29]
	v_pk_fma_f32 v[30:31], v[102:103], v[212:213], v[30:31]
	v_pk_fma_f32 v[32:33], v[104:105], v[214:215], v[32:33]
	v_pk_fma_f32 v[34:35], v[106:107], v[216:217], v[34:35]
	v_pk_fma_f32 v[36:37], v[108:109], v[218:219], v[36:37]
	v_pk_fma_f32 v[38:39], v[110:111], v[220:221], v[38:39]
	v_pk_fma_f32 v[40:41], v[112:113], v[210:211], v[40:41]
	v_pk_fma_f32 v[42:43], v[114:115], v[212:213], v[42:43]
	v_pk_fma_f32 v[44:45], v[116:117], v[214:215], v[44:45]
	v_pk_fma_f32 v[46:47], v[118:119], v[216:217], v[46:47]
	v_pk_fma_f32 v[48:49], v[120:121], v[218:219], v[48:49]
	v_pk_fma_f32 v[50:51], v[122:123], v[220:221], v[50:51]
	v_pk_fma_f32 v[52:53], v[124:125], v[210:211], v[52:53]
	v_pk_fma_f32 v[54:55], v[126:127], v[212:213], v[54:55]
	v_pk_fma_f32 v[56:57], v[128:129], v[214:215], v[56:57]
	v_pk_fma_f32 v[58:59], v[130:131], v[216:217], v[58:59]
	v_pk_fma_f32 v[60:61], v[132:133], v[218:219], v[60:61]
	v_pk_fma_f32 v[62:63], v[134:135], v[220:221], v[62:63]
	v_pk_fma_f32 v[64:65], v[136:137], v[210:211], v[64:65]
	v_pk_fma_f32 v[66:67], v[138:139], v[212:213], v[66:67]
	v_pk_fma_f32 v[68:69], v[140:141], v[214:215], v[68:69]
	v_pk_fma_f32 v[70:71], v[142:143], v[216:217], v[70:71]
	v_pk_fma_f32 v[72:73], v[144:145], v[218:219], v[72:73]
	v_pk_fma_f32 v[74:75], v[146:147], v[220:221], v[74:75]
	v_pk_fma_f32 v[76:77], v[148:149], v[210:211], v[76:77]
	v_pk_fma_f32 v[78:79], v[150:151], v[212:213], v[78:79]
	v_pk_fma_f32 v[80:81], v[152:153], v[214:215], v[80:81]
	v_pk_fma_f32 v[82:83], v[154:155], v[216:217], v[82:83]
	v_pk_fma_f32 v[84:85], v[156:157], v[218:219], v[84:85]
	v_pk_fma_f32 v[86:87], v[158:159], v[220:221], v[86:87]
	v_pk_fma_f32 v[88:89], v[160:161], v[210:211], v[88:89]
	v_pk_fma_f32 v[90:91], v[162:163], v[212:213], v[90:91]
	v_pk_fma_f32 v[92:93], v[164:165], v[214:215], v[92:93]
	v_pk_fma_f32 v[94:95], v[166:167], v[216:217], v[94:95]
	v_pk_fma_f32 v[96:97], v[168:169], v[218:219], v[96:97]
	v_pk_fma_f32 v[98:99], v[170:171], v[220:221], v[98:99]
	s_waitcnt vmcnt(0)
	v_mov_b32_e32 v197, 0x3727c5ac
	v_add_f32_e32 v100, v4, v5
	v_add_f32_e32 v100, v100, v6
	v_add_f32_e32 v100, v100, v7
	v_add_f32_e32 v100, v100, v8
	v_add_f32_e32 v100, v100, v9
	v_add_f32_e32 v100, v100, v10
	v_add_f32_e32 v100, v100, v11
	v_add_f32_e32 v100, v100, v12
	v_add_f32_e32 v100, v100, v13
	v_add_f32_e32 v100, v100, v14
	v_add_f32_e32 v100, v100, v15
	s_nop 1
	v_add_f32_dpp v100, v100, v100 row_shr:1 row_mask:0xf bank_mask:0xf bound_ctrl:1
	s_nop 1
	v_add_f32_dpp v100, v100, v100 row_shr:2 row_mask:0xf bank_mask:0xf bound_ctrl:1
	s_nop 1
	v_add_f32_dpp v100, v100, v100 row_shr:4 row_mask:0xf bank_mask:0xf bound_ctrl:1
	s_nop 1
	v_add_f32_dpp v100, v100, v100 row_shr:8 row_mask:0xf bank_mask:0xf bound_ctrl:1
	s_nop 1
	v_add_f32_dpp v100, v100, v100 row_bcast:15 row_mask:0xa bank_mask:0xf
	s_nop 1
	v_add_f32_dpp v100, v100, v100 row_bcast:31 row_mask:0xc bank_mask:0xf
	s_nop 0
	v_readlane_b32 s53, v100, 63
	s_nop 1
	v_mov_b32_e32 v101, s53
	v_fmac_f32_e32 v4, 0xbaaaaaab, v101
	v_fmac_f32_e32 v5, 0xbaaaaaab, v101
	v_fmac_f32_e32 v6, 0xbaaaaaab, v101
	v_fmac_f32_e32 v7, 0xbaaaaaab, v101
	v_fmac_f32_e32 v8, 0xbaaaaaab, v101
	v_fmac_f32_e32 v9, 0xbaaaaaab, v101
	v_fmac_f32_e32 v10, 0xbaaaaaab, v101
	v_fmac_f32_e32 v11, 0xbaaaaaab, v101
	v_fmac_f32_e32 v12, 0xbaaaaaab, v101
	v_fmac_f32_e32 v13, 0xbaaaaaab, v101
	v_fmac_f32_e32 v14, 0xbaaaaaab, v101
	v_fmac_f32_e32 v15, 0xbaaaaaab, v101
	v_mul_f32_e32 v102, v4, v4
	v_fmac_f32_e32 v102, v5, v5
	v_fmac_f32_e32 v102, v6, v6
	v_fmac_f32_e32 v102, v7, v7
	v_fmac_f32_e32 v102, v8, v8
	v_fmac_f32_e32 v102, v9, v9
	v_fmac_f32_e32 v102, v10, v10
	v_fmac_f32_e32 v102, v11, v11
	v_fmac_f32_e32 v102, v12, v12
	v_fmac_f32_e32 v102, v13, v13
	v_fmac_f32_e32 v102, v14, v14
	v_fmac_f32_e32 v102, v15, v15
	s_nop 1
	v_add_f32_dpp v102, v102, v102 row_shr:1 row_mask:0xf bank_mask:0xf bound_ctrl:1
	s_nop 1
	v_add_f32_dpp v102, v102, v102 row_shr:2 row_mask:0xf bank_mask:0xf bound_ctrl:1
	s_nop 1
	v_add_f32_dpp v102, v102, v102 row_shr:4 row_mask:0xf bank_mask:0xf bound_ctrl:1
	s_nop 1
	v_add_f32_dpp v102, v102, v102 row_shr:8 row_mask:0xf bank_mask:0xf bound_ctrl:1
	s_nop 1
	v_add_f32_dpp v102, v102, v102 row_bcast:15 row_mask:0xa bank_mask:0xf
	s_nop 1
	v_add_f32_dpp v102, v102, v102 row_bcast:31 row_mask:0xc bank_mask:0xf
	s_nop 0
	v_readlane_b32 s53, v102, 63
	s_nop 1
	v_mov_b32_e32 v101, s53
	v_fmamk_f32 v101, v101, 0x3aaaaaab, v197
	v_rsq_f32_e32 v103, v101
	s_nop 0
	v_mul_f32_e32 v4, v4, v103
	v_mul_f32_e32 v5, v5, v103
	v_mul_f32_e32 v6, v6, v103
	v_mul_f32_e32 v7, v7, v103
	v_mul_f32_e32 v8, v8, v103
	v_mul_f32_e32 v9, v9, v103
	v_mul_f32_e32 v10, v10, v103
	v_mul_f32_e32 v11, v11, v103
	v_mul_f32_e32 v12, v12, v103
	v_mul_f32_e32 v13, v13, v103
	v_mul_f32_e32 v14, v14, v103
	v_mul_f32_e32 v15, v15, v103
	v_fma_f32 v4, v222, v4, v234
	v_fma_f32 v5, v223, v5, v235
	v_fma_f32 v6, v224, v6, v236
	v_fma_f32 v7, v225, v7, v237
	v_fma_f32 v8, v226, v8, v238
	v_fma_f32 v9, v227, v9, v239
	v_fma_f32 v10, v228, v10, v240
	v_fma_f32 v11, v229, v11, v241
	v_fma_f32 v12, v230, v12, v242
	v_fma_f32 v13, v231, v13, v243
	v_fma_f32 v14, v232, v14, v244
	v_fma_f32 v15, v233, v15, v245
	s_lshl_b32 s52, s41, 11
	s_add_i32 s52, s52, 0
	v_add_u32_e32 v196, s52, v3
	v_mul_f32_e32 v108, 0xbfb8aa3b, v4
	v_exp_f32_e32 v109, v108
	s_nop 0
	v_add_f32_e32 v110, 1.0, v109
	v_div_scale_f32 v111, s[54:55], v110, v110, 1.0
	v_rcp_f32_e32 v112, v111
	v_div_scale_f32 v113, vcc, 1.0, v110, 1.0
	v_fma_f32 v115, -v111, v112, 1.0
	v_fmac_f32_e32 v112, v115, v112
	v_mul_f32_e32 v114, v113, v112
	v_fma_f32 v115, -v111, v114, v113
	v_fmac_f32_e32 v114, v115, v112
	v_fma_f32 v115, -v111, v114, v113
	v_div_fmas_f32 v115, v115, v112, v114
	v_div_fixup_f32 v115, v115, v110, 1.0
	v_mul_f32_e32 v120, v4, v115
	v_mul_f32_e32 v108, 0xbfb8aa3b, v5
	v_exp_f32_e32 v109, v108
	s_nop 0
	v_add_f32_e32 v110, 1.0, v109
	v_div_scale_f32 v111, s[54:55], v110, v110, 1.0
	v_rcp_f32_e32 v112, v111
	v_div_scale_f32 v113, vcc, 1.0, v110, 1.0
	v_fma_f32 v115, -v111, v112, 1.0
	v_fmac_f32_e32 v112, v115, v112
	v_mul_f32_e32 v114, v113, v112
	v_fma_f32 v115, -v111, v114, v113
	v_fmac_f32_e32 v114, v115, v112
	v_fma_f32 v115, -v111, v114, v113
	v_div_fmas_f32 v115, v115, v112, v114
	v_div_fixup_f32 v115, v115, v110, 1.0
	v_mul_f32_e32 v121, v5, v115
	v_mul_f32_e32 v108, 0xbfb8aa3b, v6
	v_exp_f32_e32 v109, v108
	s_nop 0
	v_add_f32_e32 v110, 1.0, v109
	v_div_scale_f32 v111, s[54:55], v110, v110, 1.0
	v_rcp_f32_e32 v112, v111
	v_div_scale_f32 v113, vcc, 1.0, v110, 1.0
	v_fma_f32 v115, -v111, v112, 1.0
	v_fmac_f32_e32 v112, v115, v112
	v_mul_f32_e32 v114, v113, v112
	v_fma_f32 v115, -v111, v114, v113
	v_fmac_f32_e32 v114, v115, v112
	v_fma_f32 v115, -v111, v114, v113
	v_div_fmas_f32 v115, v115, v112, v114
	v_div_fixup_f32 v115, v115, v110, 1.0
	v_mul_f32_e32 v122, v6, v115
	v_mul_f32_e32 v108, 0xbfb8aa3b, v7
	v_exp_f32_e32 v109, v108
	s_nop 0
	v_add_f32_e32 v110, 1.0, v109
	v_div_scale_f32 v111, s[54:55], v110, v110, 1.0
	v_rcp_f32_e32 v112, v111
	v_div_scale_f32 v113, vcc, 1.0, v110, 1.0
	v_fma_f32 v115, -v111, v112, 1.0
	v_fmac_f32_e32 v112, v115, v112
	v_mul_f32_e32 v114, v113, v112
	v_fma_f32 v115, -v111, v114, v113
	v_fmac_f32_e32 v114, v115, v112
	v_fma_f32 v115, -v111, v114, v113
	v_div_fmas_f32 v115, v115, v112, v114
	v_div_fixup_f32 v115, v115, v110, 1.0
	v_mul_f32_e32 v123, v7, v115
	v_cvt_pk_bf16_f32 v124, v120, v121
	v_cvt_pk_bf16_f32 v125, v122, v123
	global_store_dwordx2 v196, v[124:125], s[44:45]
	v_mul_f32_e32 v108, 0xbfb8aa3b, v8
	v_exp_f32_e32 v109, v108
	s_nop 0
	v_add_f32_e32 v110, 1.0, v109
	v_div_scale_f32 v111, s[54:55], v110, v110, 1.0
	v_rcp_f32_e32 v112, v111
	v_div_scale_f32 v113, vcc, 1.0, v110, 1.0
	v_fma_f32 v115, -v111, v112, 1.0
	v_fmac_f32_e32 v112, v115, v112
	v_mul_f32_e32 v114, v113, v112
	v_fma_f32 v115, -v111, v114, v113
	v_fmac_f32_e32 v114, v115, v112
	v_fma_f32 v115, -v111, v114, v113
	v_div_fmas_f32 v115, v115, v112, v114
	v_div_fixup_f32 v115, v115, v110, 1.0
	v_mul_f32_e32 v120, v8, v115
	v_mul_f32_e32 v108, 0xbfb8aa3b, v9
	v_exp_f32_e32 v109, v108
	s_nop 0
	v_add_f32_e32 v110, 1.0, v109
	v_div_scale_f32 v111, s[54:55], v110, v110, 1.0
	v_rcp_f32_e32 v112, v111
	v_div_scale_f32 v113, vcc, 1.0, v110, 1.0
	v_fma_f32 v115, -v111, v112, 1.0
	v_fmac_f32_e32 v112, v115, v112
	v_mul_f32_e32 v114, v113, v112
	v_fma_f32 v115, -v111, v114, v113
	v_fmac_f32_e32 v114, v115, v112
	v_fma_f32 v115, -v111, v114, v113
	v_div_fmas_f32 v115, v115, v112, v114
	v_div_fixup_f32 v115, v115, v110, 1.0
	v_mul_f32_e32 v121, v9, v115
	v_mul_f32_e32 v108, 0xbfb8aa3b, v10
	v_exp_f32_e32 v109, v108
	s_nop 0
	v_add_f32_e32 v110, 1.0, v109
	v_div_scale_f32 v111, s[54:55], v110, v110, 1.0
	v_rcp_f32_e32 v112, v111
	v_div_scale_f32 v113, vcc, 1.0, v110, 1.0
	v_fma_f32 v115, -v111, v112, 1.0
	v_fmac_f32_e32 v112, v115, v112
	v_mul_f32_e32 v114, v113, v112
	v_fma_f32 v115, -v111, v114, v113
	v_fmac_f32_e32 v114, v115, v112
	v_fma_f32 v115, -v111, v114, v113
	v_div_fmas_f32 v115, v115, v112, v114
	v_div_fixup_f32 v115, v115, v110, 1.0
	v_mul_f32_e32 v122, v10, v115
	v_mul_f32_e32 v108, 0xbfb8aa3b, v11
	v_exp_f32_e32 v109, v108
	s_nop 0
	v_add_f32_e32 v110, 1.0, v109
	v_div_scale_f32 v111, s[54:55], v110, v110, 1.0
	v_rcp_f32_e32 v112, v111
	v_div_scale_f32 v113, vcc, 1.0, v110, 1.0
	v_fma_f32 v115, -v111, v112, 1.0
	v_fmac_f32_e32 v112, v115, v112
	v_mul_f32_e32 v114, v113, v112
	v_fma_f32 v115, -v111, v114, v113
	v_fmac_f32_e32 v114, v115, v112
	v_fma_f32 v115, -v111, v114, v113
	v_div_fmas_f32 v115, v115, v112, v114
	v_div_fixup_f32 v115, v115, v110, 1.0
	v_mul_f32_e32 v123, v11, v115
	v_cvt_pk_bf16_f32 v124, v120, v121
	v_cvt_pk_bf16_f32 v125, v122, v123
	global_store_dwordx2 v196, v[124:125], s[44:45] offset:512
	v_mul_f32_e32 v108, 0xbfb8aa3b, v12
	v_exp_f32_e32 v109, v108
	s_nop 0
	v_add_f32_e32 v110, 1.0, v109
	v_div_scale_f32 v111, s[54:55], v110, v110, 1.0
	v_rcp_f32_e32 v112, v111
	v_div_scale_f32 v113, vcc, 1.0, v110, 1.0
	v_fma_f32 v115, -v111, v112, 1.0
	v_fmac_f32_e32 v112, v115, v112
	v_mul_f32_e32 v114, v113, v112
	v_fma_f32 v115, -v111, v114, v113
	v_fmac_f32_e32 v114, v115, v112
	v_fma_f32 v115, -v111, v114, v113
	v_div_fmas_f32 v115, v115, v112, v114
	v_div_fixup_f32 v115, v115, v110, 1.0
	v_mul_f32_e32 v120, v12, v115
	v_mul_f32_e32 v108, 0xbfb8aa3b, v13
	v_exp_f32_e32 v109, v108
	s_nop 0
	v_add_f32_e32 v110, 1.0, v109
	v_div_scale_f32 v111, s[54:55], v110, v110, 1.0
	v_rcp_f32_e32 v112, v111
	v_div_scale_f32 v113, vcc, 1.0, v110, 1.0
	v_fma_f32 v115, -v111, v112, 1.0
	v_fmac_f32_e32 v112, v115, v112
	v_mul_f32_e32 v114, v113, v112
	v_fma_f32 v115, -v111, v114, v113
	v_fmac_f32_e32 v114, v115, v112
	v_fma_f32 v115, -v111, v114, v113
	v_div_fmas_f32 v115, v115, v112, v114
	v_div_fixup_f32 v115, v115, v110, 1.0
	v_mul_f32_e32 v121, v13, v115
	v_mul_f32_e32 v108, 0xbfb8aa3b, v14
	v_exp_f32_e32 v109, v108
	s_nop 0
	v_add_f32_e32 v110, 1.0, v109
	v_div_scale_f32 v111, s[54:55], v110, v110, 1.0
	v_rcp_f32_e32 v112, v111
	v_div_scale_f32 v113, vcc, 1.0, v110, 1.0
	v_fma_f32 v115, -v111, v112, 1.0
	v_fmac_f32_e32 v112, v115, v112
	v_mul_f32_e32 v114, v113, v112
	v_fma_f32 v115, -v111, v114, v113
	v_fmac_f32_e32 v114, v115, v112
	v_fma_f32 v115, -v111, v114, v113
	v_div_fmas_f32 v115, v115, v112, v114
	v_div_fixup_f32 v115, v115, v110, 1.0
	v_mul_f32_e32 v122, v14, v115
	v_mul_f32_e32 v108, 0xbfb8aa3b, v15
	v_exp_f32_e32 v109, v108
	s_nop 0
	v_add_f32_e32 v110, 1.0, v109
	v_div_scale_f32 v111, s[54:55], v110, v110, 1.0
	v_rcp_f32_e32 v112, v111
	v_div_scale_f32 v113, vcc, 1.0, v110, 1.0
	v_fma_f32 v115, -v111, v112, 1.0
	v_fmac_f32_e32 v112, v115, v112
	v_mul_f32_e32 v114, v113, v112
	v_fma_f32 v115, -v111, v114, v113
	v_fmac_f32_e32 v114, v115, v112
	v_fma_f32 v115, -v111, v114, v113
	v_div_fmas_f32 v115, v115, v112, v114
	v_div_fixup_f32 v115, v115, v110, 1.0
	v_mul_f32_e32 v123, v15, v115
	v_cvt_pk_bf16_f32 v124, v120, v121
	v_cvt_pk_bf16_f32 v125, v122, v123
	global_store_dwordx2 v196, v[124:125], s[44:45] offset:1024
	v_add_f32_e32 v100, v16, v17
	v_add_f32_e32 v100, v100, v18
	v_add_f32_e32 v100, v100, v19
	v_add_f32_e32 v100, v100, v20
	v_add_f32_e32 v100, v100, v21
	v_add_f32_e32 v100, v100, v22
	v_add_f32_e32 v100, v100, v23
	v_add_f32_e32 v100, v100, v24
	v_add_f32_e32 v100, v100, v25
	v_add_f32_e32 v100, v100, v26
	v_add_f32_e32 v100, v100, v27
	s_nop 1
	v_add_f32_dpp v100, v100, v100 row_shr:1 row_mask:0xf bank_mask:0xf bound_ctrl:1
	s_nop 1
	v_add_f32_dpp v100, v100, v100 row_shr:2 row_mask:0xf bank_mask:0xf bound_ctrl:1
	s_nop 1
	v_add_f32_dpp v100, v100, v100 row_shr:4 row_mask:0xf bank_mask:0xf bound_ctrl:1
	s_nop 1
	v_add_f32_dpp v100, v100, v100 row_shr:8 row_mask:0xf bank_mask:0xf bound_ctrl:1
	s_nop 1
	v_add_f32_dpp v100, v100, v100 row_bcast:15 row_mask:0xa bank_mask:0xf
	s_nop 1
	v_add_f32_dpp v100, v100, v100 row_bcast:31 row_mask:0xc bank_mask:0xf
	s_nop 0
	v_readlane_b32 s53, v100, 63
	s_nop 1
	v_mov_b32_e32 v101, s53
	v_fmac_f32_e32 v16, 0xbaaaaaab, v101
	v_fmac_f32_e32 v17, 0xbaaaaaab, v101
	v_fmac_f32_e32 v18, 0xbaaaaaab, v101
	v_fmac_f32_e32 v19, 0xbaaaaaab, v101
	v_fmac_f32_e32 v20, 0xbaaaaaab, v101
	v_fmac_f32_e32 v21, 0xbaaaaaab, v101
	v_fmac_f32_e32 v22, 0xbaaaaaab, v101
	v_fmac_f32_e32 v23, 0xbaaaaaab, v101
	v_fmac_f32_e32 v24, 0xbaaaaaab, v101
	v_fmac_f32_e32 v25, 0xbaaaaaab, v101
	v_fmac_f32_e32 v26, 0xbaaaaaab, v101
	v_fmac_f32_e32 v27, 0xbaaaaaab, v101
	v_mul_f32_e32 v102, v16, v16
	v_fmac_f32_e32 v102, v17, v17
	v_fmac_f32_e32 v102, v18, v18
	v_fmac_f32_e32 v102, v19, v19
	v_fmac_f32_e32 v102, v20, v20
	v_fmac_f32_e32 v102, v21, v21
	v_fmac_f32_e32 v102, v22, v22
	v_fmac_f32_e32 v102, v23, v23
	v_fmac_f32_e32 v102, v24, v24
	v_fmac_f32_e32 v102, v25, v25
	v_fmac_f32_e32 v102, v26, v26
	v_fmac_f32_e32 v102, v27, v27
	s_nop 1
	v_add_f32_dpp v102, v102, v102 row_shr:1 row_mask:0xf bank_mask:0xf bound_ctrl:1
	s_nop 1
	v_add_f32_dpp v102, v102, v102 row_shr:2 row_mask:0xf bank_mask:0xf bound_ctrl:1
	s_nop 1
	v_add_f32_dpp v102, v102, v102 row_shr:4 row_mask:0xf bank_mask:0xf bound_ctrl:1
	s_nop 1
	v_add_f32_dpp v102, v102, v102 row_shr:8 row_mask:0xf bank_mask:0xf bound_ctrl:1
	s_nop 1
	v_add_f32_dpp v102, v102, v102 row_bcast:15 row_mask:0xa bank_mask:0xf
	s_nop 1
	v_add_f32_dpp v102, v102, v102 row_bcast:31 row_mask:0xc bank_mask:0xf
	s_nop 0
	v_readlane_b32 s53, v102, 63
	s_nop 1
	v_mov_b32_e32 v101, s53
	v_fmamk_f32 v101, v101, 0x3aaaaaab, v197
	v_rsq_f32_e32 v103, v101
	s_nop 0
	v_mul_f32_e32 v16, v16, v103
	v_mul_f32_e32 v17, v17, v103
	v_mul_f32_e32 v18, v18, v103
	v_mul_f32_e32 v19, v19, v103
	v_mul_f32_e32 v20, v20, v103
	v_mul_f32_e32 v21, v21, v103
	v_mul_f32_e32 v22, v22, v103
	v_mul_f32_e32 v23, v23, v103
	v_mul_f32_e32 v24, v24, v103
	v_mul_f32_e32 v25, v25, v103
	v_mul_f32_e32 v26, v26, v103
	v_mul_f32_e32 v27, v27, v103
	v_fma_f32 v16, v222, v16, v234
	v_fma_f32 v17, v223, v17, v235
	v_fma_f32 v18, v224, v18, v236
	v_fma_f32 v19, v225, v19, v237
	v_fma_f32 v20, v226, v20, v238
	v_fma_f32 v21, v227, v21, v239
	v_fma_f32 v22, v228, v22, v240
	v_fma_f32 v23, v229, v23, v241
	v_fma_f32 v24, v230, v24, v242
	v_fma_f32 v25, v231, v25, v243
	v_fma_f32 v26, v232, v26, v244
	v_fma_f32 v27, v233, v27, v245
	s_lshl_b32 s52, s41, 11
	s_add_i32 s52, s52, 2048
	v_add_u32_e32 v196, s52, v3
	v_mul_f32_e32 v108, 0xbfb8aa3b, v16
	v_exp_f32_e32 v109, v108
	s_nop 0
	v_add_f32_e32 v110, 1.0, v109
	v_div_scale_f32 v111, s[54:55], v110, v110, 1.0
	v_rcp_f32_e32 v112, v111
	v_div_scale_f32 v113, vcc, 1.0, v110, 1.0
	v_fma_f32 v115, -v111, v112, 1.0
	v_fmac_f32_e32 v112, v115, v112
	v_mul_f32_e32 v114, v113, v112
	v_fma_f32 v115, -v111, v114, v113
	v_fmac_f32_e32 v114, v115, v112
	v_fma_f32 v115, -v111, v114, v113
	v_div_fmas_f32 v115, v115, v112, v114
	v_div_fixup_f32 v115, v115, v110, 1.0
	v_mul_f32_e32 v120, v16, v115
	v_mul_f32_e32 v108, 0xbfb8aa3b, v17
	v_exp_f32_e32 v109, v108
	s_nop 0
	v_add_f32_e32 v110, 1.0, v109
	v_div_scale_f32 v111, s[54:55], v110, v110, 1.0
	v_rcp_f32_e32 v112, v111
	v_div_scale_f32 v113, vcc, 1.0, v110, 1.0
	v_fma_f32 v115, -v111, v112, 1.0
	v_fmac_f32_e32 v112, v115, v112
	v_mul_f32_e32 v114, v113, v112
	v_fma_f32 v115, -v111, v114, v113
	v_fmac_f32_e32 v114, v115, v112
	v_fma_f32 v115, -v111, v114, v113
	v_div_fmas_f32 v115, v115, v112, v114
	v_div_fixup_f32 v115, v115, v110, 1.0
	v_mul_f32_e32 v121, v17, v115
	v_mul_f32_e32 v108, 0xbfb8aa3b, v18
	v_exp_f32_e32 v109, v108
	s_nop 0
	v_add_f32_e32 v110, 1.0, v109
	v_div_scale_f32 v111, s[54:55], v110, v110, 1.0
	v_rcp_f32_e32 v112, v111
	v_div_scale_f32 v113, vcc, 1.0, v110, 1.0
	v_fma_f32 v115, -v111, v112, 1.0
	v_fmac_f32_e32 v112, v115, v112
	v_mul_f32_e32 v114, v113, v112
	v_fma_f32 v115, -v111, v114, v113
	v_fmac_f32_e32 v114, v115, v112
	v_fma_f32 v115, -v111, v114, v113
	v_div_fmas_f32 v115, v115, v112, v114
	v_div_fixup_f32 v115, v115, v110, 1.0
	v_mul_f32_e32 v122, v18, v115
	v_mul_f32_e32 v108, 0xbfb8aa3b, v19
	v_exp_f32_e32 v109, v108
	s_nop 0
	v_add_f32_e32 v110, 1.0, v109
	v_div_scale_f32 v111, s[54:55], v110, v110, 1.0
	v_rcp_f32_e32 v112, v111
	v_div_scale_f32 v113, vcc, 1.0, v110, 1.0
	v_fma_f32 v115, -v111, v112, 1.0
	v_fmac_f32_e32 v112, v115, v112
	v_mul_f32_e32 v114, v113, v112
	v_fma_f32 v115, -v111, v114, v113
	v_fmac_f32_e32 v114, v115, v112
	v_fma_f32 v115, -v111, v114, v113
	v_div_fmas_f32 v115, v115, v112, v114
	v_div_fixup_f32 v115, v115, v110, 1.0
	v_mul_f32_e32 v123, v19, v115
	v_cvt_pk_bf16_f32 v124, v120, v121
	v_cvt_pk_bf16_f32 v125, v122, v123
	global_store_dwordx2 v196, v[124:125], s[44:45]
	v_mul_f32_e32 v108, 0xbfb8aa3b, v20
	v_exp_f32_e32 v109, v108
	s_nop 0
	v_add_f32_e32 v110, 1.0, v109
	v_div_scale_f32 v111, s[54:55], v110, v110, 1.0
	v_rcp_f32_e32 v112, v111
	v_div_scale_f32 v113, vcc, 1.0, v110, 1.0
	v_fma_f32 v115, -v111, v112, 1.0
	v_fmac_f32_e32 v112, v115, v112
	v_mul_f32_e32 v114, v113, v112
	v_fma_f32 v115, -v111, v114, v113
	v_fmac_f32_e32 v114, v115, v112
	v_fma_f32 v115, -v111, v114, v113
	v_div_fmas_f32 v115, v115, v112, v114
	v_div_fixup_f32 v115, v115, v110, 1.0
	v_mul_f32_e32 v120, v20, v115
	v_mul_f32_e32 v108, 0xbfb8aa3b, v21
	v_exp_f32_e32 v109, v108
	s_nop 0
	v_add_f32_e32 v110, 1.0, v109
	v_div_scale_f32 v111, s[54:55], v110, v110, 1.0
	v_rcp_f32_e32 v112, v111
	v_div_scale_f32 v113, vcc, 1.0, v110, 1.0
	v_fma_f32 v115, -v111, v112, 1.0
	v_fmac_f32_e32 v112, v115, v112
	v_mul_f32_e32 v114, v113, v112
	v_fma_f32 v115, -v111, v114, v113
	v_fmac_f32_e32 v114, v115, v112
	v_fma_f32 v115, -v111, v114, v113
	v_div_fmas_f32 v115, v115, v112, v114
	v_div_fixup_f32 v115, v115, v110, 1.0
	v_mul_f32_e32 v121, v21, v115
	v_mul_f32_e32 v108, 0xbfb8aa3b, v22
	v_exp_f32_e32 v109, v108
	s_nop 0
	v_add_f32_e32 v110, 1.0, v109
	v_div_scale_f32 v111, s[54:55], v110, v110, 1.0
	v_rcp_f32_e32 v112, v111
	v_div_scale_f32 v113, vcc, 1.0, v110, 1.0
	v_fma_f32 v115, -v111, v112, 1.0
	v_fmac_f32_e32 v112, v115, v112
	v_mul_f32_e32 v114, v113, v112
	v_fma_f32 v115, -v111, v114, v113
	v_fmac_f32_e32 v114, v115, v112
	v_fma_f32 v115, -v111, v114, v113
	v_div_fmas_f32 v115, v115, v112, v114
	v_div_fixup_f32 v115, v115, v110, 1.0
	v_mul_f32_e32 v122, v22, v115
	v_mul_f32_e32 v108, 0xbfb8aa3b, v23
	v_exp_f32_e32 v109, v108
	s_nop 0
	v_add_f32_e32 v110, 1.0, v109
	v_div_scale_f32 v111, s[54:55], v110, v110, 1.0
	v_rcp_f32_e32 v112, v111
	v_div_scale_f32 v113, vcc, 1.0, v110, 1.0
	v_fma_f32 v115, -v111, v112, 1.0
	v_fmac_f32_e32 v112, v115, v112
	v_mul_f32_e32 v114, v113, v112
	v_fma_f32 v115, -v111, v114, v113
	v_fmac_f32_e32 v114, v115, v112
	v_fma_f32 v115, -v111, v114, v113
	v_div_fmas_f32 v115, v115, v112, v114
	v_div_fixup_f32 v115, v115, v110, 1.0
	v_mul_f32_e32 v123, v23, v115
	v_cvt_pk_bf16_f32 v124, v120, v121
	v_cvt_pk_bf16_f32 v125, v122, v123
	global_store_dwordx2 v196, v[124:125], s[44:45] offset:512
	v_mul_f32_e32 v108, 0xbfb8aa3b, v24
	v_exp_f32_e32 v109, v108
	s_nop 0
	v_add_f32_e32 v110, 1.0, v109
	v_div_scale_f32 v111, s[54:55], v110, v110, 1.0
	v_rcp_f32_e32 v112, v111
	v_div_scale_f32 v113, vcc, 1.0, v110, 1.0
	v_fma_f32 v115, -v111, v112, 1.0
	v_fmac_f32_e32 v112, v115, v112
	v_mul_f32_e32 v114, v113, v112
	v_fma_f32 v115, -v111, v114, v113
	v_fmac_f32_e32 v114, v115, v112
	v_fma_f32 v115, -v111, v114, v113
	v_div_fmas_f32 v115, v115, v112, v114
	v_div_fixup_f32 v115, v115, v110, 1.0
	v_mul_f32_e32 v120, v24, v115
	v_mul_f32_e32 v108, 0xbfb8aa3b, v25
	v_exp_f32_e32 v109, v108
	s_nop 0
	v_add_f32_e32 v110, 1.0, v109
	v_div_scale_f32 v111, s[54:55], v110, v110, 1.0
	v_rcp_f32_e32 v112, v111
	v_div_scale_f32 v113, vcc, 1.0, v110, 1.0
	v_fma_f32 v115, -v111, v112, 1.0
	v_fmac_f32_e32 v112, v115, v112
	v_mul_f32_e32 v114, v113, v112
	v_fma_f32 v115, -v111, v114, v113
	v_fmac_f32_e32 v114, v115, v112
	v_fma_f32 v115, -v111, v114, v113
	v_div_fmas_f32 v115, v115, v112, v114
	v_div_fixup_f32 v115, v115, v110, 1.0
	v_mul_f32_e32 v121, v25, v115
	v_mul_f32_e32 v108, 0xbfb8aa3b, v26
	v_exp_f32_e32 v109, v108
	s_nop 0
	v_add_f32_e32 v110, 1.0, v109
	v_div_scale_f32 v111, s[54:55], v110, v110, 1.0
	v_rcp_f32_e32 v112, v111
	v_div_scale_f32 v113, vcc, 1.0, v110, 1.0
	v_fma_f32 v115, -v111, v112, 1.0
	v_fmac_f32_e32 v112, v115, v112
	v_mul_f32_e32 v114, v113, v112
	v_fma_f32 v115, -v111, v114, v113
	v_fmac_f32_e32 v114, v115, v112
	v_fma_f32 v115, -v111, v114, v113
	v_div_fmas_f32 v115, v115, v112, v114
	v_div_fixup_f32 v115, v115, v110, 1.0
	v_mul_f32_e32 v122, v26, v115
	v_mul_f32_e32 v108, 0xbfb8aa3b, v27
	v_exp_f32_e32 v109, v108
	s_nop 0
	v_add_f32_e32 v110, 1.0, v109
	v_div_scale_f32 v111, s[54:55], v110, v110, 1.0
	v_rcp_f32_e32 v112, v111
	v_div_scale_f32 v113, vcc, 1.0, v110, 1.0
	v_fma_f32 v115, -v111, v112, 1.0
	v_fmac_f32_e32 v112, v115, v112
	v_mul_f32_e32 v114, v113, v112
	v_fma_f32 v115, -v111, v114, v113
	v_fmac_f32_e32 v114, v115, v112
	v_fma_f32 v115, -v111, v114, v113
	v_div_fmas_f32 v115, v115, v112, v114
	v_div_fixup_f32 v115, v115, v110, 1.0
	v_mul_f32_e32 v123, v27, v115
	v_cvt_pk_bf16_f32 v124, v120, v121
	v_cvt_pk_bf16_f32 v125, v122, v123
	global_store_dwordx2 v196, v[124:125], s[44:45] offset:1024
	v_add_f32_e32 v100, v28, v29
	v_add_f32_e32 v100, v100, v30
	v_add_f32_e32 v100, v100, v31
	v_add_f32_e32 v100, v100, v32
	v_add_f32_e32 v100, v100, v33
	v_add_f32_e32 v100, v100, v34
	v_add_f32_e32 v100, v100, v35
	v_add_f32_e32 v100, v100, v36
	v_add_f32_e32 v100, v100, v37
	v_add_f32_e32 v100, v100, v38
	v_add_f32_e32 v100, v100, v39
	s_nop 1
	v_add_f32_dpp v100, v100, v100 row_shr:1 row_mask:0xf bank_mask:0xf bound_ctrl:1
	s_nop 1
	v_add_f32_dpp v100, v100, v100 row_shr:2 row_mask:0xf bank_mask:0xf bound_ctrl:1
	s_nop 1
	v_add_f32_dpp v100, v100, v100 row_shr:4 row_mask:0xf bank_mask:0xf bound_ctrl:1
	s_nop 1
	v_add_f32_dpp v100, v100, v100 row_shr:8 row_mask:0xf bank_mask:0xf bound_ctrl:1
	s_nop 1
	v_add_f32_dpp v100, v100, v100 row_bcast:15 row_mask:0xa bank_mask:0xf
	s_nop 1
	v_add_f32_dpp v100, v100, v100 row_bcast:31 row_mask:0xc bank_mask:0xf
	s_nop 0
	v_readlane_b32 s53, v100, 63
	s_nop 1
	v_mov_b32_e32 v101, s53
	v_fmac_f32_e32 v28, 0xbaaaaaab, v101
	v_fmac_f32_e32 v29, 0xbaaaaaab, v101
	v_fmac_f32_e32 v30, 0xbaaaaaab, v101
	v_fmac_f32_e32 v31, 0xbaaaaaab, v101
	v_fmac_f32_e32 v32, 0xbaaaaaab, v101
	v_fmac_f32_e32 v33, 0xbaaaaaab, v101
	v_fmac_f32_e32 v34, 0xbaaaaaab, v101
	v_fmac_f32_e32 v35, 0xbaaaaaab, v101
	v_fmac_f32_e32 v36, 0xbaaaaaab, v101
	v_fmac_f32_e32 v37, 0xbaaaaaab, v101
	v_fmac_f32_e32 v38, 0xbaaaaaab, v101
	v_fmac_f32_e32 v39, 0xbaaaaaab, v101
	v_mul_f32_e32 v102, v28, v28
	v_fmac_f32_e32 v102, v29, v29
	v_fmac_f32_e32 v102, v30, v30
	v_fmac_f32_e32 v102, v31, v31
	v_fmac_f32_e32 v102, v32, v32
	v_fmac_f32_e32 v102, v33, v33
	v_fmac_f32_e32 v102, v34, v34
	v_fmac_f32_e32 v102, v35, v35
	v_fmac_f32_e32 v102, v36, v36
	v_fmac_f32_e32 v102, v37, v37
	v_fmac_f32_e32 v102, v38, v38
	v_fmac_f32_e32 v102, v39, v39
	s_nop 1
	v_add_f32_dpp v102, v102, v102 row_shr:1 row_mask:0xf bank_mask:0xf bound_ctrl:1
	s_nop 1
	v_add_f32_dpp v102, v102, v102 row_shr:2 row_mask:0xf bank_mask:0xf bound_ctrl:1
	s_nop 1
	v_add_f32_dpp v102, v102, v102 row_shr:4 row_mask:0xf bank_mask:0xf bound_ctrl:1
	s_nop 1
	v_add_f32_dpp v102, v102, v102 row_shr:8 row_mask:0xf bank_mask:0xf bound_ctrl:1
	s_nop 1
	v_add_f32_dpp v102, v102, v102 row_bcast:15 row_mask:0xa bank_mask:0xf
	s_nop 1
	v_add_f32_dpp v102, v102, v102 row_bcast:31 row_mask:0xc bank_mask:0xf
	s_nop 0
	v_readlane_b32 s53, v102, 63
	s_nop 1
	v_mov_b32_e32 v101, s53
	v_fmamk_f32 v101, v101, 0x3aaaaaab, v197
	v_rsq_f32_e32 v103, v101
	s_nop 0
	v_mul_f32_e32 v28, v28, v103
	v_mul_f32_e32 v29, v29, v103
	v_mul_f32_e32 v30, v30, v103
	v_mul_f32_e32 v31, v31, v103
	v_mul_f32_e32 v32, v32, v103
	v_mul_f32_e32 v33, v33, v103
	v_mul_f32_e32 v34, v34, v103
	v_mul_f32_e32 v35, v35, v103
	v_mul_f32_e32 v36, v36, v103
	v_mul_f32_e32 v37, v37, v103
	v_mul_f32_e32 v38, v38, v103
	v_mul_f32_e32 v39, v39, v103
	v_fma_f32 v28, v222, v28, v234
	v_fma_f32 v29, v223, v29, v235
	v_fma_f32 v30, v224, v30, v236
	v_fma_f32 v31, v225, v31, v237
	v_fma_f32 v32, v226, v32, v238
	v_fma_f32 v33, v227, v33, v239
	v_fma_f32 v34, v228, v34, v240
	v_fma_f32 v35, v229, v35, v241
	v_fma_f32 v36, v230, v36, v242
	v_fma_f32 v37, v231, v37, v243
	v_fma_f32 v38, v232, v38, v244
	v_fma_f32 v39, v233, v39, v245
	s_lshl_b32 s52, s41, 11
	s_add_i32 s52, s52, 4096
	v_add_u32_e32 v196, s52, v3
	v_mul_f32_e32 v108, 0xbfb8aa3b, v28
	v_exp_f32_e32 v109, v108
	s_nop 0
	v_add_f32_e32 v110, 1.0, v109
	v_div_scale_f32 v111, s[54:55], v110, v110, 1.0
	v_rcp_f32_e32 v112, v111
	v_div_scale_f32 v113, vcc, 1.0, v110, 1.0
	v_fma_f32 v115, -v111, v112, 1.0
	v_fmac_f32_e32 v112, v115, v112
	v_mul_f32_e32 v114, v113, v112
	v_fma_f32 v115, -v111, v114, v113
	v_fmac_f32_e32 v114, v115, v112
	v_fma_f32 v115, -v111, v114, v113
	v_div_fmas_f32 v115, v115, v112, v114
	v_div_fixup_f32 v115, v115, v110, 1.0
	v_mul_f32_e32 v120, v28, v115
	v_mul_f32_e32 v108, 0xbfb8aa3b, v29
	v_exp_f32_e32 v109, v108
	s_nop 0
	v_add_f32_e32 v110, 1.0, v109
	v_div_scale_f32 v111, s[54:55], v110, v110, 1.0
	v_rcp_f32_e32 v112, v111
	v_div_scale_f32 v113, vcc, 1.0, v110, 1.0
	v_fma_f32 v115, -v111, v112, 1.0
	v_fmac_f32_e32 v112, v115, v112
	v_mul_f32_e32 v114, v113, v112
	v_fma_f32 v115, -v111, v114, v113
	v_fmac_f32_e32 v114, v115, v112
	v_fma_f32 v115, -v111, v114, v113
	v_div_fmas_f32 v115, v115, v112, v114
	v_div_fixup_f32 v115, v115, v110, 1.0
	v_mul_f32_e32 v121, v29, v115
	v_mul_f32_e32 v108, 0xbfb8aa3b, v30
	v_exp_f32_e32 v109, v108
	s_nop 0
	v_add_f32_e32 v110, 1.0, v109
	v_div_scale_f32 v111, s[54:55], v110, v110, 1.0
	v_rcp_f32_e32 v112, v111
	v_div_scale_f32 v113, vcc, 1.0, v110, 1.0
	v_fma_f32 v115, -v111, v112, 1.0
	v_fmac_f32_e32 v112, v115, v112
	v_mul_f32_e32 v114, v113, v112
	v_fma_f32 v115, -v111, v114, v113
	v_fmac_f32_e32 v114, v115, v112
	v_fma_f32 v115, -v111, v114, v113
	v_div_fmas_f32 v115, v115, v112, v114
	v_div_fixup_f32 v115, v115, v110, 1.0
	v_mul_f32_e32 v122, v30, v115
	v_mul_f32_e32 v108, 0xbfb8aa3b, v31
	v_exp_f32_e32 v109, v108
	s_nop 0
	v_add_f32_e32 v110, 1.0, v109
	v_div_scale_f32 v111, s[54:55], v110, v110, 1.0
	v_rcp_f32_e32 v112, v111
	v_div_scale_f32 v113, vcc, 1.0, v110, 1.0
	v_fma_f32 v115, -v111, v112, 1.0
	v_fmac_f32_e32 v112, v115, v112
	v_mul_f32_e32 v114, v113, v112
	v_fma_f32 v115, -v111, v114, v113
	v_fmac_f32_e32 v114, v115, v112
	v_fma_f32 v115, -v111, v114, v113
	v_div_fmas_f32 v115, v115, v112, v114
	v_div_fixup_f32 v115, v115, v110, 1.0
	v_mul_f32_e32 v123, v31, v115
	v_cvt_pk_bf16_f32 v124, v120, v121
	v_cvt_pk_bf16_f32 v125, v122, v123
	global_store_dwordx2 v196, v[124:125], s[44:45]
	v_mul_f32_e32 v108, 0xbfb8aa3b, v32
	v_exp_f32_e32 v109, v108
	s_nop 0
	v_add_f32_e32 v110, 1.0, v109
	v_div_scale_f32 v111, s[54:55], v110, v110, 1.0
	v_rcp_f32_e32 v112, v111
	v_div_scale_f32 v113, vcc, 1.0, v110, 1.0
	v_fma_f32 v115, -v111, v112, 1.0
	v_fmac_f32_e32 v112, v115, v112
	v_mul_f32_e32 v114, v113, v112
	v_fma_f32 v115, -v111, v114, v113
	v_fmac_f32_e32 v114, v115, v112
	v_fma_f32 v115, -v111, v114, v113
	v_div_fmas_f32 v115, v115, v112, v114
	v_div_fixup_f32 v115, v115, v110, 1.0
	v_mul_f32_e32 v120, v32, v115
	v_mul_f32_e32 v108, 0xbfb8aa3b, v33
	v_exp_f32_e32 v109, v108
	s_nop 0
	v_add_f32_e32 v110, 1.0, v109
	v_div_scale_f32 v111, s[54:55], v110, v110, 1.0
	v_rcp_f32_e32 v112, v111
	v_div_scale_f32 v113, vcc, 1.0, v110, 1.0
	v_fma_f32 v115, -v111, v112, 1.0
	v_fmac_f32_e32 v112, v115, v112
	v_mul_f32_e32 v114, v113, v112
	v_fma_f32 v115, -v111, v114, v113
	v_fmac_f32_e32 v114, v115, v112
	v_fma_f32 v115, -v111, v114, v113
	v_div_fmas_f32 v115, v115, v112, v114
	v_div_fixup_f32 v115, v115, v110, 1.0
	v_mul_f32_e32 v121, v33, v115
	v_mul_f32_e32 v108, 0xbfb8aa3b, v34
	v_exp_f32_e32 v109, v108
	s_nop 0
	v_add_f32_e32 v110, 1.0, v109
	v_div_scale_f32 v111, s[54:55], v110, v110, 1.0
	v_rcp_f32_e32 v112, v111
	v_div_scale_f32 v113, vcc, 1.0, v110, 1.0
	v_fma_f32 v115, -v111, v112, 1.0
	v_fmac_f32_e32 v112, v115, v112
	v_mul_f32_e32 v114, v113, v112
	v_fma_f32 v115, -v111, v114, v113
	v_fmac_f32_e32 v114, v115, v112
	v_fma_f32 v115, -v111, v114, v113
	v_div_fmas_f32 v115, v115, v112, v114
	v_div_fixup_f32 v115, v115, v110, 1.0
	v_mul_f32_e32 v122, v34, v115
	v_mul_f32_e32 v108, 0xbfb8aa3b, v35
	v_exp_f32_e32 v109, v108
	s_nop 0
	v_add_f32_e32 v110, 1.0, v109
	v_div_scale_f32 v111, s[54:55], v110, v110, 1.0
	v_rcp_f32_e32 v112, v111
	v_div_scale_f32 v113, vcc, 1.0, v110, 1.0
	v_fma_f32 v115, -v111, v112, 1.0
	v_fmac_f32_e32 v112, v115, v112
	v_mul_f32_e32 v114, v113, v112
	v_fma_f32 v115, -v111, v114, v113
	v_fmac_f32_e32 v114, v115, v112
	v_fma_f32 v115, -v111, v114, v113
	v_div_fmas_f32 v115, v115, v112, v114
	v_div_fixup_f32 v115, v115, v110, 1.0
	v_mul_f32_e32 v123, v35, v115
	v_cvt_pk_bf16_f32 v124, v120, v121
	v_cvt_pk_bf16_f32 v125, v122, v123
	global_store_dwordx2 v196, v[124:125], s[44:45] offset:512
	v_mul_f32_e32 v108, 0xbfb8aa3b, v36
	v_exp_f32_e32 v109, v108
	s_nop 0
	v_add_f32_e32 v110, 1.0, v109
	v_div_scale_f32 v111, s[54:55], v110, v110, 1.0
	v_rcp_f32_e32 v112, v111
	v_div_scale_f32 v113, vcc, 1.0, v110, 1.0
	v_fma_f32 v115, -v111, v112, 1.0
	v_fmac_f32_e32 v112, v115, v112
	v_mul_f32_e32 v114, v113, v112
	v_fma_f32 v115, -v111, v114, v113
	v_fmac_f32_e32 v114, v115, v112
	v_fma_f32 v115, -v111, v114, v113
	v_div_fmas_f32 v115, v115, v112, v114
	v_div_fixup_f32 v115, v115, v110, 1.0
	v_mul_f32_e32 v120, v36, v115
	v_mul_f32_e32 v108, 0xbfb8aa3b, v37
	v_exp_f32_e32 v109, v108
	s_nop 0
	v_add_f32_e32 v110, 1.0, v109
	v_div_scale_f32 v111, s[54:55], v110, v110, 1.0
	v_rcp_f32_e32 v112, v111
	v_div_scale_f32 v113, vcc, 1.0, v110, 1.0
	v_fma_f32 v115, -v111, v112, 1.0
	v_fmac_f32_e32 v112, v115, v112
	v_mul_f32_e32 v114, v113, v112
	v_fma_f32 v115, -v111, v114, v113
	v_fmac_f32_e32 v114, v115, v112
	v_fma_f32 v115, -v111, v114, v113
	v_div_fmas_f32 v115, v115, v112, v114
	v_div_fixup_f32 v115, v115, v110, 1.0
	v_mul_f32_e32 v121, v37, v115
	v_mul_f32_e32 v108, 0xbfb8aa3b, v38
	v_exp_f32_e32 v109, v108
	s_nop 0
	v_add_f32_e32 v110, 1.0, v109
	v_div_scale_f32 v111, s[54:55], v110, v110, 1.0
	v_rcp_f32_e32 v112, v111
	v_div_scale_f32 v113, vcc, 1.0, v110, 1.0
	v_fma_f32 v115, -v111, v112, 1.0
	v_fmac_f32_e32 v112, v115, v112
	v_mul_f32_e32 v114, v113, v112
	v_fma_f32 v115, -v111, v114, v113
	v_fmac_f32_e32 v114, v115, v112
	v_fma_f32 v115, -v111, v114, v113
	v_div_fmas_f32 v115, v115, v112, v114
	v_div_fixup_f32 v115, v115, v110, 1.0
	v_mul_f32_e32 v122, v38, v115
	v_mul_f32_e32 v108, 0xbfb8aa3b, v39
	v_exp_f32_e32 v109, v108
	s_nop 0
	v_add_f32_e32 v110, 1.0, v109
	v_div_scale_f32 v111, s[54:55], v110, v110, 1.0
	v_rcp_f32_e32 v112, v111
	v_div_scale_f32 v113, vcc, 1.0, v110, 1.0
	v_fma_f32 v115, -v111, v112, 1.0
	v_fmac_f32_e32 v112, v115, v112
	v_mul_f32_e32 v114, v113, v112
	v_fma_f32 v115, -v111, v114, v113
	v_fmac_f32_e32 v114, v115, v112
	v_fma_f32 v115, -v111, v114, v113
	v_div_fmas_f32 v115, v115, v112, v114
	v_div_fixup_f32 v115, v115, v110, 1.0
	v_mul_f32_e32 v123, v39, v115
	v_cvt_pk_bf16_f32 v124, v120, v121
	v_cvt_pk_bf16_f32 v125, v122, v123
	global_store_dwordx2 v196, v[124:125], s[44:45] offset:1024
	v_add_f32_e32 v100, v40, v41
	v_add_f32_e32 v100, v100, v42
	v_add_f32_e32 v100, v100, v43
	v_add_f32_e32 v100, v100, v44
	v_add_f32_e32 v100, v100, v45
	v_add_f32_e32 v100, v100, v46
	v_add_f32_e32 v100, v100, v47
	v_add_f32_e32 v100, v100, v48
	v_add_f32_e32 v100, v100, v49
	v_add_f32_e32 v100, v100, v50
	v_add_f32_e32 v100, v100, v51
	s_nop 1
	v_add_f32_dpp v100, v100, v100 row_shr:1 row_mask:0xf bank_mask:0xf bound_ctrl:1
	s_nop 1
	v_add_f32_dpp v100, v100, v100 row_shr:2 row_mask:0xf bank_mask:0xf bound_ctrl:1
	s_nop 1
	v_add_f32_dpp v100, v100, v100 row_shr:4 row_mask:0xf bank_mask:0xf bound_ctrl:1
	s_nop 1
	v_add_f32_dpp v100, v100, v100 row_shr:8 row_mask:0xf bank_mask:0xf bound_ctrl:1
	s_nop 1
	v_add_f32_dpp v100, v100, v100 row_bcast:15 row_mask:0xa bank_mask:0xf
	s_nop 1
	v_add_f32_dpp v100, v100, v100 row_bcast:31 row_mask:0xc bank_mask:0xf
	s_nop 0
	v_readlane_b32 s53, v100, 63
	s_nop 1
	v_mov_b32_e32 v101, s53
	v_fmac_f32_e32 v40, 0xbaaaaaab, v101
	v_fmac_f32_e32 v41, 0xbaaaaaab, v101
	v_fmac_f32_e32 v42, 0xbaaaaaab, v101
	v_fmac_f32_e32 v43, 0xbaaaaaab, v101
	v_fmac_f32_e32 v44, 0xbaaaaaab, v101
	v_fmac_f32_e32 v45, 0xbaaaaaab, v101
	v_fmac_f32_e32 v46, 0xbaaaaaab, v101
	v_fmac_f32_e32 v47, 0xbaaaaaab, v101
	v_fmac_f32_e32 v48, 0xbaaaaaab, v101
	v_fmac_f32_e32 v49, 0xbaaaaaab, v101
	v_fmac_f32_e32 v50, 0xbaaaaaab, v101
	v_fmac_f32_e32 v51, 0xbaaaaaab, v101
	v_mul_f32_e32 v102, v40, v40
	v_fmac_f32_e32 v102, v41, v41
	v_fmac_f32_e32 v102, v42, v42
	v_fmac_f32_e32 v102, v43, v43
	v_fmac_f32_e32 v102, v44, v44
	v_fmac_f32_e32 v102, v45, v45
	v_fmac_f32_e32 v102, v46, v46
	v_fmac_f32_e32 v102, v47, v47
	v_fmac_f32_e32 v102, v48, v48
	v_fmac_f32_e32 v102, v49, v49
	v_fmac_f32_e32 v102, v50, v50
	v_fmac_f32_e32 v102, v51, v51
	s_nop 1
	v_add_f32_dpp v102, v102, v102 row_shr:1 row_mask:0xf bank_mask:0xf bound_ctrl:1
	s_nop 1
	v_add_f32_dpp v102, v102, v102 row_shr:2 row_mask:0xf bank_mask:0xf bound_ctrl:1
	s_nop 1
	v_add_f32_dpp v102, v102, v102 row_shr:4 row_mask:0xf bank_mask:0xf bound_ctrl:1
	s_nop 1
	v_add_f32_dpp v102, v102, v102 row_shr:8 row_mask:0xf bank_mask:0xf bound_ctrl:1
	s_nop 1
	v_add_f32_dpp v102, v102, v102 row_bcast:15 row_mask:0xa bank_mask:0xf
	s_nop 1
	v_add_f32_dpp v102, v102, v102 row_bcast:31 row_mask:0xc bank_mask:0xf
	s_nop 0
	v_readlane_b32 s53, v102, 63
	s_nop 1
	v_mov_b32_e32 v101, s53
	v_fmamk_f32 v101, v101, 0x3aaaaaab, v197
	v_rsq_f32_e32 v103, v101
	s_nop 0
	v_mul_f32_e32 v40, v40, v103
	v_mul_f32_e32 v41, v41, v103
	v_mul_f32_e32 v42, v42, v103
	v_mul_f32_e32 v43, v43, v103
	v_mul_f32_e32 v44, v44, v103
	v_mul_f32_e32 v45, v45, v103
	v_mul_f32_e32 v46, v46, v103
	v_mul_f32_e32 v47, v47, v103
	v_mul_f32_e32 v48, v48, v103
	v_mul_f32_e32 v49, v49, v103
	v_mul_f32_e32 v50, v50, v103
	v_mul_f32_e32 v51, v51, v103
	v_fma_f32 v40, v222, v40, v234
	v_fma_f32 v41, v223, v41, v235
	v_fma_f32 v42, v224, v42, v236
	v_fma_f32 v43, v225, v43, v237
	v_fma_f32 v44, v226, v44, v238
	v_fma_f32 v45, v227, v45, v239
	v_fma_f32 v46, v228, v46, v240
	v_fma_f32 v47, v229, v47, v241
	v_fma_f32 v48, v230, v48, v242
	v_fma_f32 v49, v231, v49, v243
	v_fma_f32 v50, v232, v50, v244
	v_fma_f32 v51, v233, v51, v245
	s_lshl_b32 s52, s41, 11
	s_add_i32 s52, s52, 6144
	v_add_u32_e32 v196, s52, v3
	v_mul_f32_e32 v108, 0xbfb8aa3b, v40
	v_exp_f32_e32 v109, v108
	s_nop 0
	v_add_f32_e32 v110, 1.0, v109
	v_div_scale_f32 v111, s[54:55], v110, v110, 1.0
	v_rcp_f32_e32 v112, v111
	v_div_scale_f32 v113, vcc, 1.0, v110, 1.0
	v_fma_f32 v115, -v111, v112, 1.0
	v_fmac_f32_e32 v112, v115, v112
	v_mul_f32_e32 v114, v113, v112
	v_fma_f32 v115, -v111, v114, v113
	v_fmac_f32_e32 v114, v115, v112
	v_fma_f32 v115, -v111, v114, v113
	v_div_fmas_f32 v115, v115, v112, v114
	v_div_fixup_f32 v115, v115, v110, 1.0
	v_mul_f32_e32 v120, v40, v115
	v_mul_f32_e32 v108, 0xbfb8aa3b, v41
	v_exp_f32_e32 v109, v108
	s_nop 0
	v_add_f32_e32 v110, 1.0, v109
	v_div_scale_f32 v111, s[54:55], v110, v110, 1.0
	v_rcp_f32_e32 v112, v111
	v_div_scale_f32 v113, vcc, 1.0, v110, 1.0
	v_fma_f32 v115, -v111, v112, 1.0
	v_fmac_f32_e32 v112, v115, v112
	v_mul_f32_e32 v114, v113, v112
	v_fma_f32 v115, -v111, v114, v113
	v_fmac_f32_e32 v114, v115, v112
	v_fma_f32 v115, -v111, v114, v113
	v_div_fmas_f32 v115, v115, v112, v114
	v_div_fixup_f32 v115, v115, v110, 1.0
	v_mul_f32_e32 v121, v41, v115
	v_mul_f32_e32 v108, 0xbfb8aa3b, v42
	v_exp_f32_e32 v109, v108
	s_nop 0
	v_add_f32_e32 v110, 1.0, v109
	v_div_scale_f32 v111, s[54:55], v110, v110, 1.0
	v_rcp_f32_e32 v112, v111
	v_div_scale_f32 v113, vcc, 1.0, v110, 1.0
	v_fma_f32 v115, -v111, v112, 1.0
	v_fmac_f32_e32 v112, v115, v112
	v_mul_f32_e32 v114, v113, v112
	v_fma_f32 v115, -v111, v114, v113
	v_fmac_f32_e32 v114, v115, v112
	v_fma_f32 v115, -v111, v114, v113
	v_div_fmas_f32 v115, v115, v112, v114
	v_div_fixup_f32 v115, v115, v110, 1.0
	v_mul_f32_e32 v122, v42, v115
	v_mul_f32_e32 v108, 0xbfb8aa3b, v43
	v_exp_f32_e32 v109, v108
	s_nop 0
	v_add_f32_e32 v110, 1.0, v109
	v_div_scale_f32 v111, s[54:55], v110, v110, 1.0
	v_rcp_f32_e32 v112, v111
	v_div_scale_f32 v113, vcc, 1.0, v110, 1.0
	v_fma_f32 v115, -v111, v112, 1.0
	v_fmac_f32_e32 v112, v115, v112
	v_mul_f32_e32 v114, v113, v112
	v_fma_f32 v115, -v111, v114, v113
	v_fmac_f32_e32 v114, v115, v112
	v_fma_f32 v115, -v111, v114, v113
	v_div_fmas_f32 v115, v115, v112, v114
	v_div_fixup_f32 v115, v115, v110, 1.0
	v_mul_f32_e32 v123, v43, v115
	v_cvt_pk_bf16_f32 v124, v120, v121
	v_cvt_pk_bf16_f32 v125, v122, v123
	global_store_dwordx2 v196, v[124:125], s[44:45]
	v_mul_f32_e32 v108, 0xbfb8aa3b, v44
	v_exp_f32_e32 v109, v108
	s_nop 0
	v_add_f32_e32 v110, 1.0, v109
	v_div_scale_f32 v111, s[54:55], v110, v110, 1.0
	v_rcp_f32_e32 v112, v111
	v_div_scale_f32 v113, vcc, 1.0, v110, 1.0
	v_fma_f32 v115, -v111, v112, 1.0
	v_fmac_f32_e32 v112, v115, v112
	v_mul_f32_e32 v114, v113, v112
	v_fma_f32 v115, -v111, v114, v113
	v_fmac_f32_e32 v114, v115, v112
	v_fma_f32 v115, -v111, v114, v113
	v_div_fmas_f32 v115, v115, v112, v114
	v_div_fixup_f32 v115, v115, v110, 1.0
	v_mul_f32_e32 v120, v44, v115
	v_mul_f32_e32 v108, 0xbfb8aa3b, v45
	v_exp_f32_e32 v109, v108
	s_nop 0
	v_add_f32_e32 v110, 1.0, v109
	v_div_scale_f32 v111, s[54:55], v110, v110, 1.0
	v_rcp_f32_e32 v112, v111
	v_div_scale_f32 v113, vcc, 1.0, v110, 1.0
	v_fma_f32 v115, -v111, v112, 1.0
	v_fmac_f32_e32 v112, v115, v112
	v_mul_f32_e32 v114, v113, v112
	v_fma_f32 v115, -v111, v114, v113
	v_fmac_f32_e32 v114, v115, v112
	v_fma_f32 v115, -v111, v114, v113
	v_div_fmas_f32 v115, v115, v112, v114
	v_div_fixup_f32 v115, v115, v110, 1.0
	v_mul_f32_e32 v121, v45, v115
	v_mul_f32_e32 v108, 0xbfb8aa3b, v46
	v_exp_f32_e32 v109, v108
	s_nop 0
	v_add_f32_e32 v110, 1.0, v109
	v_div_scale_f32 v111, s[54:55], v110, v110, 1.0
	v_rcp_f32_e32 v112, v111
	v_div_scale_f32 v113, vcc, 1.0, v110, 1.0
	v_fma_f32 v115, -v111, v112, 1.0
	v_fmac_f32_e32 v112, v115, v112
	v_mul_f32_e32 v114, v113, v112
	v_fma_f32 v115, -v111, v114, v113
	v_fmac_f32_e32 v114, v115, v112
	v_fma_f32 v115, -v111, v114, v113
	v_div_fmas_f32 v115, v115, v112, v114
	v_div_fixup_f32 v115, v115, v110, 1.0
	v_mul_f32_e32 v122, v46, v115
	v_mul_f32_e32 v108, 0xbfb8aa3b, v47
	v_exp_f32_e32 v109, v108
	s_nop 0
	v_add_f32_e32 v110, 1.0, v109
	v_div_scale_f32 v111, s[54:55], v110, v110, 1.0
	v_rcp_f32_e32 v112, v111
	v_div_scale_f32 v113, vcc, 1.0, v110, 1.0
	v_fma_f32 v115, -v111, v112, 1.0
	v_fmac_f32_e32 v112, v115, v112
	v_mul_f32_e32 v114, v113, v112
	v_fma_f32 v115, -v111, v114, v113
	v_fmac_f32_e32 v114, v115, v112
	v_fma_f32 v115, -v111, v114, v113
	v_div_fmas_f32 v115, v115, v112, v114
	v_div_fixup_f32 v115, v115, v110, 1.0
	v_mul_f32_e32 v123, v47, v115
	v_cvt_pk_bf16_f32 v124, v120, v121
	v_cvt_pk_bf16_f32 v125, v122, v123
	global_store_dwordx2 v196, v[124:125], s[44:45] offset:512
	v_mul_f32_e32 v108, 0xbfb8aa3b, v48
	v_exp_f32_e32 v109, v108
	s_nop 0
	v_add_f32_e32 v110, 1.0, v109
	v_div_scale_f32 v111, s[54:55], v110, v110, 1.0
	v_rcp_f32_e32 v112, v111
	v_div_scale_f32 v113, vcc, 1.0, v110, 1.0
	v_fma_f32 v115, -v111, v112, 1.0
	v_fmac_f32_e32 v112, v115, v112
	v_mul_f32_e32 v114, v113, v112
	v_fma_f32 v115, -v111, v114, v113
	v_fmac_f32_e32 v114, v115, v112
	v_fma_f32 v115, -v111, v114, v113
	v_div_fmas_f32 v115, v115, v112, v114
	v_div_fixup_f32 v115, v115, v110, 1.0
	v_mul_f32_e32 v120, v48, v115
	v_mul_f32_e32 v108, 0xbfb8aa3b, v49
	v_exp_f32_e32 v109, v108
	s_nop 0
	v_add_f32_e32 v110, 1.0, v109
	v_div_scale_f32 v111, s[54:55], v110, v110, 1.0
	v_rcp_f32_e32 v112, v111
	v_div_scale_f32 v113, vcc, 1.0, v110, 1.0
	v_fma_f32 v115, -v111, v112, 1.0
	v_fmac_f32_e32 v112, v115, v112
	v_mul_f32_e32 v114, v113, v112
	v_fma_f32 v115, -v111, v114, v113
	v_fmac_f32_e32 v114, v115, v112
	v_fma_f32 v115, -v111, v114, v113
	v_div_fmas_f32 v115, v115, v112, v114
	v_div_fixup_f32 v115, v115, v110, 1.0
	v_mul_f32_e32 v121, v49, v115
	v_mul_f32_e32 v108, 0xbfb8aa3b, v50
	v_exp_f32_e32 v109, v108
	s_nop 0
	v_add_f32_e32 v110, 1.0, v109
	v_div_scale_f32 v111, s[54:55], v110, v110, 1.0
	v_rcp_f32_e32 v112, v111
	v_div_scale_f32 v113, vcc, 1.0, v110, 1.0
	v_fma_f32 v115, -v111, v112, 1.0
	v_fmac_f32_e32 v112, v115, v112
	v_mul_f32_e32 v114, v113, v112
	v_fma_f32 v115, -v111, v114, v113
	v_fmac_f32_e32 v114, v115, v112
	v_fma_f32 v115, -v111, v114, v113
	v_div_fmas_f32 v115, v115, v112, v114
	v_div_fixup_f32 v115, v115, v110, 1.0
	v_mul_f32_e32 v122, v50, v115
	v_mul_f32_e32 v108, 0xbfb8aa3b, v51
	v_exp_f32_e32 v109, v108
	s_nop 0
	v_add_f32_e32 v110, 1.0, v109
	v_div_scale_f32 v111, s[54:55], v110, v110, 1.0
	v_rcp_f32_e32 v112, v111
	v_div_scale_f32 v113, vcc, 1.0, v110, 1.0
	v_fma_f32 v115, -v111, v112, 1.0
	v_fmac_f32_e32 v112, v115, v112
	v_mul_f32_e32 v114, v113, v112
	v_fma_f32 v115, -v111, v114, v113
	v_fmac_f32_e32 v114, v115, v112
	v_fma_f32 v115, -v111, v114, v113
	v_div_fmas_f32 v115, v115, v112, v114
	v_div_fixup_f32 v115, v115, v110, 1.0
	v_mul_f32_e32 v123, v51, v115
	v_cvt_pk_bf16_f32 v124, v120, v121
	v_cvt_pk_bf16_f32 v125, v122, v123
	global_store_dwordx2 v196, v[124:125], s[44:45] offset:1024
	v_add_f32_e32 v100, v52, v53
	v_add_f32_e32 v100, v100, v54
	v_add_f32_e32 v100, v100, v55
	v_add_f32_e32 v100, v100, v56
	v_add_f32_e32 v100, v100, v57
	v_add_f32_e32 v100, v100, v58
	v_add_f32_e32 v100, v100, v59
	v_add_f32_e32 v100, v100, v60
	v_add_f32_e32 v100, v100, v61
	v_add_f32_e32 v100, v100, v62
	v_add_f32_e32 v100, v100, v63
	s_nop 1
	v_add_f32_dpp v100, v100, v100 row_shr:1 row_mask:0xf bank_mask:0xf bound_ctrl:1
	s_nop 1
	v_add_f32_dpp v100, v100, v100 row_shr:2 row_mask:0xf bank_mask:0xf bound_ctrl:1
	s_nop 1
	v_add_f32_dpp v100, v100, v100 row_shr:4 row_mask:0xf bank_mask:0xf bound_ctrl:1
	s_nop 1
	v_add_f32_dpp v100, v100, v100 row_shr:8 row_mask:0xf bank_mask:0xf bound_ctrl:1
	s_nop 1
	v_add_f32_dpp v100, v100, v100 row_bcast:15 row_mask:0xa bank_mask:0xf
	s_nop 1
	v_add_f32_dpp v100, v100, v100 row_bcast:31 row_mask:0xc bank_mask:0xf
	s_nop 0
	v_readlane_b32 s53, v100, 63
	s_nop 1
	v_mov_b32_e32 v101, s53
	v_fmac_f32_e32 v52, 0xbaaaaaab, v101
	v_fmac_f32_e32 v53, 0xbaaaaaab, v101
	v_fmac_f32_e32 v54, 0xbaaaaaab, v101
	v_fmac_f32_e32 v55, 0xbaaaaaab, v101
	v_fmac_f32_e32 v56, 0xbaaaaaab, v101
	v_fmac_f32_e32 v57, 0xbaaaaaab, v101
	v_fmac_f32_e32 v58, 0xbaaaaaab, v101
	v_fmac_f32_e32 v59, 0xbaaaaaab, v101
	v_fmac_f32_e32 v60, 0xbaaaaaab, v101
	v_fmac_f32_e32 v61, 0xbaaaaaab, v101
	v_fmac_f32_e32 v62, 0xbaaaaaab, v101
	v_fmac_f32_e32 v63, 0xbaaaaaab, v101
	v_mul_f32_e32 v102, v52, v52
	v_fmac_f32_e32 v102, v53, v53
	v_fmac_f32_e32 v102, v54, v54
	v_fmac_f32_e32 v102, v55, v55
	v_fmac_f32_e32 v102, v56, v56
	v_fmac_f32_e32 v102, v57, v57
	v_fmac_f32_e32 v102, v58, v58
	v_fmac_f32_e32 v102, v59, v59
	v_fmac_f32_e32 v102, v60, v60
	v_fmac_f32_e32 v102, v61, v61
	v_fmac_f32_e32 v102, v62, v62
	v_fmac_f32_e32 v102, v63, v63
	s_nop 1
	v_add_f32_dpp v102, v102, v102 row_shr:1 row_mask:0xf bank_mask:0xf bound_ctrl:1
	s_nop 1
	v_add_f32_dpp v102, v102, v102 row_shr:2 row_mask:0xf bank_mask:0xf bound_ctrl:1
	s_nop 1
	v_add_f32_dpp v102, v102, v102 row_shr:4 row_mask:0xf bank_mask:0xf bound_ctrl:1
	s_nop 1
	v_add_f32_dpp v102, v102, v102 row_shr:8 row_mask:0xf bank_mask:0xf bound_ctrl:1
	s_nop 1
	v_add_f32_dpp v102, v102, v102 row_bcast:15 row_mask:0xa bank_mask:0xf
	s_nop 1
	v_add_f32_dpp v102, v102, v102 row_bcast:31 row_mask:0xc bank_mask:0xf
	s_nop 0
	v_readlane_b32 s53, v102, 63
	s_nop 1
	v_mov_b32_e32 v101, s53
	v_fmamk_f32 v101, v101, 0x3aaaaaab, v197
	v_rsq_f32_e32 v103, v101
	s_nop 0
	v_mul_f32_e32 v52, v52, v103
	v_mul_f32_e32 v53, v53, v103
	v_mul_f32_e32 v54, v54, v103
	v_mul_f32_e32 v55, v55, v103
	v_mul_f32_e32 v56, v56, v103
	v_mul_f32_e32 v57, v57, v103
	v_mul_f32_e32 v58, v58, v103
	v_mul_f32_e32 v59, v59, v103
	v_mul_f32_e32 v60, v60, v103
	v_mul_f32_e32 v61, v61, v103
	v_mul_f32_e32 v62, v62, v103
	v_mul_f32_e32 v63, v63, v103
	v_fma_f32 v52, v222, v52, v234
	v_fma_f32 v53, v223, v53, v235
	v_fma_f32 v54, v224, v54, v236
	v_fma_f32 v55, v225, v55, v237
	v_fma_f32 v56, v226, v56, v238
	v_fma_f32 v57, v227, v57, v239
	v_fma_f32 v58, v228, v58, v240
	v_fma_f32 v59, v229, v59, v241
	v_fma_f32 v60, v230, v60, v242
	v_fma_f32 v61, v231, v61, v243
	v_fma_f32 v62, v232, v62, v244
	v_fma_f32 v63, v233, v63, v245
	s_lshl_b32 s52, s41, 11
	s_add_i32 s52, s52, 8192
	v_add_u32_e32 v196, s52, v3
	v_mul_f32_e32 v108, 0xbfb8aa3b, v52
	v_exp_f32_e32 v109, v108
	s_nop 0
	v_add_f32_e32 v110, 1.0, v109
	v_div_scale_f32 v111, s[54:55], v110, v110, 1.0
	v_rcp_f32_e32 v112, v111
	v_div_scale_f32 v113, vcc, 1.0, v110, 1.0
	v_fma_f32 v115, -v111, v112, 1.0
	v_fmac_f32_e32 v112, v115, v112
	v_mul_f32_e32 v114, v113, v112
	v_fma_f32 v115, -v111, v114, v113
	v_fmac_f32_e32 v114, v115, v112
	v_fma_f32 v115, -v111, v114, v113
	v_div_fmas_f32 v115, v115, v112, v114
	v_div_fixup_f32 v115, v115, v110, 1.0
	v_mul_f32_e32 v120, v52, v115
	v_mul_f32_e32 v108, 0xbfb8aa3b, v53
	v_exp_f32_e32 v109, v108
	s_nop 0
	v_add_f32_e32 v110, 1.0, v109
	v_div_scale_f32 v111, s[54:55], v110, v110, 1.0
	v_rcp_f32_e32 v112, v111
	v_div_scale_f32 v113, vcc, 1.0, v110, 1.0
	v_fma_f32 v115, -v111, v112, 1.0
	v_fmac_f32_e32 v112, v115, v112
	v_mul_f32_e32 v114, v113, v112
	v_fma_f32 v115, -v111, v114, v113
	v_fmac_f32_e32 v114, v115, v112
	v_fma_f32 v115, -v111, v114, v113
	v_div_fmas_f32 v115, v115, v112, v114
	v_div_fixup_f32 v115, v115, v110, 1.0
	v_mul_f32_e32 v121, v53, v115
	v_mul_f32_e32 v108, 0xbfb8aa3b, v54
	v_exp_f32_e32 v109, v108
	s_nop 0
	v_add_f32_e32 v110, 1.0, v109
	v_div_scale_f32 v111, s[54:55], v110, v110, 1.0
	v_rcp_f32_e32 v112, v111
	v_div_scale_f32 v113, vcc, 1.0, v110, 1.0
	v_fma_f32 v115, -v111, v112, 1.0
	v_fmac_f32_e32 v112, v115, v112
	v_mul_f32_e32 v114, v113, v112
	v_fma_f32 v115, -v111, v114, v113
	v_fmac_f32_e32 v114, v115, v112
	v_fma_f32 v115, -v111, v114, v113
	v_div_fmas_f32 v115, v115, v112, v114
	v_div_fixup_f32 v115, v115, v110, 1.0
	v_mul_f32_e32 v122, v54, v115
	v_mul_f32_e32 v108, 0xbfb8aa3b, v55
	v_exp_f32_e32 v109, v108
	s_nop 0
	v_add_f32_e32 v110, 1.0, v109
	v_div_scale_f32 v111, s[54:55], v110, v110, 1.0
	v_rcp_f32_e32 v112, v111
	v_div_scale_f32 v113, vcc, 1.0, v110, 1.0
	v_fma_f32 v115, -v111, v112, 1.0
	v_fmac_f32_e32 v112, v115, v112
	v_mul_f32_e32 v114, v113, v112
	v_fma_f32 v115, -v111, v114, v113
	v_fmac_f32_e32 v114, v115, v112
	v_fma_f32 v115, -v111, v114, v113
	v_div_fmas_f32 v115, v115, v112, v114
	v_div_fixup_f32 v115, v115, v110, 1.0
	v_mul_f32_e32 v123, v55, v115
	v_cvt_pk_bf16_f32 v124, v120, v121
	v_cvt_pk_bf16_f32 v125, v122, v123
	global_store_dwordx2 v196, v[124:125], s[44:45]
	v_mul_f32_e32 v108, 0xbfb8aa3b, v56
	v_exp_f32_e32 v109, v108
	s_nop 0
	v_add_f32_e32 v110, 1.0, v109
	v_div_scale_f32 v111, s[54:55], v110, v110, 1.0
	v_rcp_f32_e32 v112, v111
	v_div_scale_f32 v113, vcc, 1.0, v110, 1.0
	v_fma_f32 v115, -v111, v112, 1.0
	v_fmac_f32_e32 v112, v115, v112
	v_mul_f32_e32 v114, v113, v112
	v_fma_f32 v115, -v111, v114, v113
	v_fmac_f32_e32 v114, v115, v112
	v_fma_f32 v115, -v111, v114, v113
	v_div_fmas_f32 v115, v115, v112, v114
	v_div_fixup_f32 v115, v115, v110, 1.0
	v_mul_f32_e32 v120, v56, v115
	v_mul_f32_e32 v108, 0xbfb8aa3b, v57
	v_exp_f32_e32 v109, v108
	s_nop 0
	v_add_f32_e32 v110, 1.0, v109
	v_div_scale_f32 v111, s[54:55], v110, v110, 1.0
	v_rcp_f32_e32 v112, v111
	v_div_scale_f32 v113, vcc, 1.0, v110, 1.0
	v_fma_f32 v115, -v111, v112, 1.0
	v_fmac_f32_e32 v112, v115, v112
	v_mul_f32_e32 v114, v113, v112
	v_fma_f32 v115, -v111, v114, v113
	v_fmac_f32_e32 v114, v115, v112
	v_fma_f32 v115, -v111, v114, v113
	v_div_fmas_f32 v115, v115, v112, v114
	v_div_fixup_f32 v115, v115, v110, 1.0
	v_mul_f32_e32 v121, v57, v115
	v_mul_f32_e32 v108, 0xbfb8aa3b, v58
	v_exp_f32_e32 v109, v108
	s_nop 0
	v_add_f32_e32 v110, 1.0, v109
	v_div_scale_f32 v111, s[54:55], v110, v110, 1.0
	v_rcp_f32_e32 v112, v111
	v_div_scale_f32 v113, vcc, 1.0, v110, 1.0
	v_fma_f32 v115, -v111, v112, 1.0
	v_fmac_f32_e32 v112, v115, v112
	v_mul_f32_e32 v114, v113, v112
	v_fma_f32 v115, -v111, v114, v113
	v_fmac_f32_e32 v114, v115, v112
	v_fma_f32 v115, -v111, v114, v113
	v_div_fmas_f32 v115, v115, v112, v114
	v_div_fixup_f32 v115, v115, v110, 1.0
	v_mul_f32_e32 v122, v58, v115
	v_mul_f32_e32 v108, 0xbfb8aa3b, v59
	v_exp_f32_e32 v109, v108
	s_nop 0
	v_add_f32_e32 v110, 1.0, v109
	v_div_scale_f32 v111, s[54:55], v110, v110, 1.0
	v_rcp_f32_e32 v112, v111
	v_div_scale_f32 v113, vcc, 1.0, v110, 1.0
	v_fma_f32 v115, -v111, v112, 1.0
	v_fmac_f32_e32 v112, v115, v112
	v_mul_f32_e32 v114, v113, v112
	v_fma_f32 v115, -v111, v114, v113
	v_fmac_f32_e32 v114, v115, v112
	v_fma_f32 v115, -v111, v114, v113
	v_div_fmas_f32 v115, v115, v112, v114
	v_div_fixup_f32 v115, v115, v110, 1.0
	v_mul_f32_e32 v123, v59, v115
	v_cvt_pk_bf16_f32 v124, v120, v121
	v_cvt_pk_bf16_f32 v125, v122, v123
	global_store_dwordx2 v196, v[124:125], s[44:45] offset:512
	v_mul_f32_e32 v108, 0xbfb8aa3b, v60
	v_exp_f32_e32 v109, v108
	s_nop 0
	v_add_f32_e32 v110, 1.0, v109
	v_div_scale_f32 v111, s[54:55], v110, v110, 1.0
	v_rcp_f32_e32 v112, v111
	v_div_scale_f32 v113, vcc, 1.0, v110, 1.0
	v_fma_f32 v115, -v111, v112, 1.0
	v_fmac_f32_e32 v112, v115, v112
	v_mul_f32_e32 v114, v113, v112
	v_fma_f32 v115, -v111, v114, v113
	v_fmac_f32_e32 v114, v115, v112
	v_fma_f32 v115, -v111, v114, v113
	v_div_fmas_f32 v115, v115, v112, v114
	v_div_fixup_f32 v115, v115, v110, 1.0
	v_mul_f32_e32 v120, v60, v115
	v_mul_f32_e32 v108, 0xbfb8aa3b, v61
	v_exp_f32_e32 v109, v108
	s_nop 0
	v_add_f32_e32 v110, 1.0, v109
	v_div_scale_f32 v111, s[54:55], v110, v110, 1.0
	v_rcp_f32_e32 v112, v111
	v_div_scale_f32 v113, vcc, 1.0, v110, 1.0
	v_fma_f32 v115, -v111, v112, 1.0
	v_fmac_f32_e32 v112, v115, v112
	v_mul_f32_e32 v114, v113, v112
	v_fma_f32 v115, -v111, v114, v113
	v_fmac_f32_e32 v114, v115, v112
	v_fma_f32 v115, -v111, v114, v113
	v_div_fmas_f32 v115, v115, v112, v114
	v_div_fixup_f32 v115, v115, v110, 1.0
	v_mul_f32_e32 v121, v61, v115
	v_mul_f32_e32 v108, 0xbfb8aa3b, v62
	v_exp_f32_e32 v109, v108
	s_nop 0
	v_add_f32_e32 v110, 1.0, v109
	v_div_scale_f32 v111, s[54:55], v110, v110, 1.0
	v_rcp_f32_e32 v112, v111
	v_div_scale_f32 v113, vcc, 1.0, v110, 1.0
	v_fma_f32 v115, -v111, v112, 1.0
	v_fmac_f32_e32 v112, v115, v112
	v_mul_f32_e32 v114, v113, v112
	v_fma_f32 v115, -v111, v114, v113
	v_fmac_f32_e32 v114, v115, v112
	v_fma_f32 v115, -v111, v114, v113
	v_div_fmas_f32 v115, v115, v112, v114
	v_div_fixup_f32 v115, v115, v110, 1.0
	v_mul_f32_e32 v122, v62, v115
	v_mul_f32_e32 v108, 0xbfb8aa3b, v63
	v_exp_f32_e32 v109, v108
	s_nop 0
	v_add_f32_e32 v110, 1.0, v109
	v_div_scale_f32 v111, s[54:55], v110, v110, 1.0
	v_rcp_f32_e32 v112, v111
	v_div_scale_f32 v113, vcc, 1.0, v110, 1.0
	v_fma_f32 v115, -v111, v112, 1.0
	v_fmac_f32_e32 v112, v115, v112
	v_mul_f32_e32 v114, v113, v112
	v_fma_f32 v115, -v111, v114, v113
	v_fmac_f32_e32 v114, v115, v112
	v_fma_f32 v115, -v111, v114, v113
	v_div_fmas_f32 v115, v115, v112, v114
	v_div_fixup_f32 v115, v115, v110, 1.0
	v_mul_f32_e32 v123, v63, v115
	v_cvt_pk_bf16_f32 v124, v120, v121
	v_cvt_pk_bf16_f32 v125, v122, v123
	global_store_dwordx2 v196, v[124:125], s[44:45] offset:1024
	v_add_f32_e32 v100, v64, v65
	v_add_f32_e32 v100, v100, v66
	v_add_f32_e32 v100, v100, v67
	v_add_f32_e32 v100, v100, v68
	v_add_f32_e32 v100, v100, v69
	v_add_f32_e32 v100, v100, v70
	v_add_f32_e32 v100, v100, v71
	v_add_f32_e32 v100, v100, v72
	v_add_f32_e32 v100, v100, v73
	v_add_f32_e32 v100, v100, v74
	v_add_f32_e32 v100, v100, v75
	s_nop 1
	v_add_f32_dpp v100, v100, v100 row_shr:1 row_mask:0xf bank_mask:0xf bound_ctrl:1
	s_nop 1
	v_add_f32_dpp v100, v100, v100 row_shr:2 row_mask:0xf bank_mask:0xf bound_ctrl:1
	s_nop 1
	v_add_f32_dpp v100, v100, v100 row_shr:4 row_mask:0xf bank_mask:0xf bound_ctrl:1
	s_nop 1
	v_add_f32_dpp v100, v100, v100 row_shr:8 row_mask:0xf bank_mask:0xf bound_ctrl:1
	s_nop 1
	v_add_f32_dpp v100, v100, v100 row_bcast:15 row_mask:0xa bank_mask:0xf
	s_nop 1
	v_add_f32_dpp v100, v100, v100 row_bcast:31 row_mask:0xc bank_mask:0xf
	s_nop 0
	v_readlane_b32 s53, v100, 63
	s_nop 1
	v_mov_b32_e32 v101, s53
	v_fmac_f32_e32 v64, 0xbaaaaaab, v101
	v_fmac_f32_e32 v65, 0xbaaaaaab, v101
	v_fmac_f32_e32 v66, 0xbaaaaaab, v101
	v_fmac_f32_e32 v67, 0xbaaaaaab, v101
	v_fmac_f32_e32 v68, 0xbaaaaaab, v101
	v_fmac_f32_e32 v69, 0xbaaaaaab, v101
	v_fmac_f32_e32 v70, 0xbaaaaaab, v101
	v_fmac_f32_e32 v71, 0xbaaaaaab, v101
	v_fmac_f32_e32 v72, 0xbaaaaaab, v101
	v_fmac_f32_e32 v73, 0xbaaaaaab, v101
	v_fmac_f32_e32 v74, 0xbaaaaaab, v101
	v_fmac_f32_e32 v75, 0xbaaaaaab, v101
	v_mul_f32_e32 v102, v64, v64
	v_fmac_f32_e32 v102, v65, v65
	v_fmac_f32_e32 v102, v66, v66
	v_fmac_f32_e32 v102, v67, v67
	v_fmac_f32_e32 v102, v68, v68
	v_fmac_f32_e32 v102, v69, v69
	v_fmac_f32_e32 v102, v70, v70
	v_fmac_f32_e32 v102, v71, v71
	v_fmac_f32_e32 v102, v72, v72
	v_fmac_f32_e32 v102, v73, v73
	v_fmac_f32_e32 v102, v74, v74
	v_fmac_f32_e32 v102, v75, v75
	s_nop 1
	v_add_f32_dpp v102, v102, v102 row_shr:1 row_mask:0xf bank_mask:0xf bound_ctrl:1
	s_nop 1
	v_add_f32_dpp v102, v102, v102 row_shr:2 row_mask:0xf bank_mask:0xf bound_ctrl:1
	s_nop 1
	v_add_f32_dpp v102, v102, v102 row_shr:4 row_mask:0xf bank_mask:0xf bound_ctrl:1
	s_nop 1
	v_add_f32_dpp v102, v102, v102 row_shr:8 row_mask:0xf bank_mask:0xf bound_ctrl:1
	s_nop 1
	v_add_f32_dpp v102, v102, v102 row_bcast:15 row_mask:0xa bank_mask:0xf
	s_nop 1
	v_add_f32_dpp v102, v102, v102 row_bcast:31 row_mask:0xc bank_mask:0xf
	s_nop 0
	v_readlane_b32 s53, v102, 63
	s_nop 1
	v_mov_b32_e32 v101, s53
	v_fmamk_f32 v101, v101, 0x3aaaaaab, v197
	v_rsq_f32_e32 v103, v101
	s_nop 0
	v_mul_f32_e32 v64, v64, v103
	v_mul_f32_e32 v65, v65, v103
	v_mul_f32_e32 v66, v66, v103
	v_mul_f32_e32 v67, v67, v103
	v_mul_f32_e32 v68, v68, v103
	v_mul_f32_e32 v69, v69, v103
	v_mul_f32_e32 v70, v70, v103
	v_mul_f32_e32 v71, v71, v103
	v_mul_f32_e32 v72, v72, v103
	v_mul_f32_e32 v73, v73, v103
	v_mul_f32_e32 v74, v74, v103
	v_mul_f32_e32 v75, v75, v103
	v_fma_f32 v64, v222, v64, v234
	v_fma_f32 v65, v223, v65, v235
	v_fma_f32 v66, v224, v66, v236
	v_fma_f32 v67, v225, v67, v237
	v_fma_f32 v68, v226, v68, v238
	v_fma_f32 v69, v227, v69, v239
	v_fma_f32 v70, v228, v70, v240
	v_fma_f32 v71, v229, v71, v241
	v_fma_f32 v72, v230, v72, v242
	v_fma_f32 v73, v231, v73, v243
	v_fma_f32 v74, v232, v74, v244
	v_fma_f32 v75, v233, v75, v245
	s_lshl_b32 s52, s41, 11
	s_add_i32 s52, s52, 10240
	v_add_u32_e32 v196, s52, v3
	v_mul_f32_e32 v108, 0xbfb8aa3b, v64
	v_exp_f32_e32 v109, v108
	s_nop 0
	v_add_f32_e32 v110, 1.0, v109
	v_div_scale_f32 v111, s[54:55], v110, v110, 1.0
	v_rcp_f32_e32 v112, v111
	v_div_scale_f32 v113, vcc, 1.0, v110, 1.0
	v_fma_f32 v115, -v111, v112, 1.0
	v_fmac_f32_e32 v112, v115, v112
	v_mul_f32_e32 v114, v113, v112
	v_fma_f32 v115, -v111, v114, v113
	v_fmac_f32_e32 v114, v115, v112
	v_fma_f32 v115, -v111, v114, v113
	v_div_fmas_f32 v115, v115, v112, v114
	v_div_fixup_f32 v115, v115, v110, 1.0
	v_mul_f32_e32 v120, v64, v115
	v_mul_f32_e32 v108, 0xbfb8aa3b, v65
	v_exp_f32_e32 v109, v108
	s_nop 0
	v_add_f32_e32 v110, 1.0, v109
	v_div_scale_f32 v111, s[54:55], v110, v110, 1.0
	v_rcp_f32_e32 v112, v111
	v_div_scale_f32 v113, vcc, 1.0, v110, 1.0
	v_fma_f32 v115, -v111, v112, 1.0
	v_fmac_f32_e32 v112, v115, v112
	v_mul_f32_e32 v114, v113, v112
	v_fma_f32 v115, -v111, v114, v113
	v_fmac_f32_e32 v114, v115, v112
	v_fma_f32 v115, -v111, v114, v113
	v_div_fmas_f32 v115, v115, v112, v114
	v_div_fixup_f32 v115, v115, v110, 1.0
	v_mul_f32_e32 v121, v65, v115
	v_mul_f32_e32 v108, 0xbfb8aa3b, v66
	v_exp_f32_e32 v109, v108
	s_nop 0
	v_add_f32_e32 v110, 1.0, v109
	v_div_scale_f32 v111, s[54:55], v110, v110, 1.0
	v_rcp_f32_e32 v112, v111
	v_div_scale_f32 v113, vcc, 1.0, v110, 1.0
	v_fma_f32 v115, -v111, v112, 1.0
	v_fmac_f32_e32 v112, v115, v112
	v_mul_f32_e32 v114, v113, v112
	v_fma_f32 v115, -v111, v114, v113
	v_fmac_f32_e32 v114, v115, v112
	v_fma_f32 v115, -v111, v114, v113
	v_div_fmas_f32 v115, v115, v112, v114
	v_div_fixup_f32 v115, v115, v110, 1.0
	v_mul_f32_e32 v122, v66, v115
	v_mul_f32_e32 v108, 0xbfb8aa3b, v67
	v_exp_f32_e32 v109, v108
	s_nop 0
	v_add_f32_e32 v110, 1.0, v109
	v_div_scale_f32 v111, s[54:55], v110, v110, 1.0
	v_rcp_f32_e32 v112, v111
	v_div_scale_f32 v113, vcc, 1.0, v110, 1.0
	v_fma_f32 v115, -v111, v112, 1.0
	v_fmac_f32_e32 v112, v115, v112
	v_mul_f32_e32 v114, v113, v112
	v_fma_f32 v115, -v111, v114, v113
	v_fmac_f32_e32 v114, v115, v112
	v_fma_f32 v115, -v111, v114, v113
	v_div_fmas_f32 v115, v115, v112, v114
	v_div_fixup_f32 v115, v115, v110, 1.0
	v_mul_f32_e32 v123, v67, v115
	v_cvt_pk_bf16_f32 v124, v120, v121
	v_cvt_pk_bf16_f32 v125, v122, v123
	global_store_dwordx2 v196, v[124:125], s[44:45]
	v_mul_f32_e32 v108, 0xbfb8aa3b, v68
	v_exp_f32_e32 v109, v108
	s_nop 0
	v_add_f32_e32 v110, 1.0, v109
	v_div_scale_f32 v111, s[54:55], v110, v110, 1.0
	v_rcp_f32_e32 v112, v111
	v_div_scale_f32 v113, vcc, 1.0, v110, 1.0
	v_fma_f32 v115, -v111, v112, 1.0
	v_fmac_f32_e32 v112, v115, v112
	v_mul_f32_e32 v114, v113, v112
	v_fma_f32 v115, -v111, v114, v113
	v_fmac_f32_e32 v114, v115, v112
	v_fma_f32 v115, -v111, v114, v113
	v_div_fmas_f32 v115, v115, v112, v114
	v_div_fixup_f32 v115, v115, v110, 1.0
	v_mul_f32_e32 v120, v68, v115
	v_mul_f32_e32 v108, 0xbfb8aa3b, v69
	v_exp_f32_e32 v109, v108
	s_nop 0
	v_add_f32_e32 v110, 1.0, v109
	v_div_scale_f32 v111, s[54:55], v110, v110, 1.0
	v_rcp_f32_e32 v112, v111
	v_div_scale_f32 v113, vcc, 1.0, v110, 1.0
	v_fma_f32 v115, -v111, v112, 1.0
	v_fmac_f32_e32 v112, v115, v112
	v_mul_f32_e32 v114, v113, v112
	v_fma_f32 v115, -v111, v114, v113
	v_fmac_f32_e32 v114, v115, v112
	v_fma_f32 v115, -v111, v114, v113
	v_div_fmas_f32 v115, v115, v112, v114
	v_div_fixup_f32 v115, v115, v110, 1.0
	v_mul_f32_e32 v121, v69, v115
	v_mul_f32_e32 v108, 0xbfb8aa3b, v70
	v_exp_f32_e32 v109, v108
	s_nop 0
	v_add_f32_e32 v110, 1.0, v109
	v_div_scale_f32 v111, s[54:55], v110, v110, 1.0
	v_rcp_f32_e32 v112, v111
	v_div_scale_f32 v113, vcc, 1.0, v110, 1.0
	v_fma_f32 v115, -v111, v112, 1.0
	v_fmac_f32_e32 v112, v115, v112
	v_mul_f32_e32 v114, v113, v112
	v_fma_f32 v115, -v111, v114, v113
	v_fmac_f32_e32 v114, v115, v112
	v_fma_f32 v115, -v111, v114, v113
	v_div_fmas_f32 v115, v115, v112, v114
	v_div_fixup_f32 v115, v115, v110, 1.0
	v_mul_f32_e32 v122, v70, v115
	v_mul_f32_e32 v108, 0xbfb8aa3b, v71
	v_exp_f32_e32 v109, v108
	s_nop 0
	v_add_f32_e32 v110, 1.0, v109
	v_div_scale_f32 v111, s[54:55], v110, v110, 1.0
	v_rcp_f32_e32 v112, v111
	v_div_scale_f32 v113, vcc, 1.0, v110, 1.0
	v_fma_f32 v115, -v111, v112, 1.0
	v_fmac_f32_e32 v112, v115, v112
	v_mul_f32_e32 v114, v113, v112
	v_fma_f32 v115, -v111, v114, v113
	v_fmac_f32_e32 v114, v115, v112
	v_fma_f32 v115, -v111, v114, v113
	v_div_fmas_f32 v115, v115, v112, v114
	v_div_fixup_f32 v115, v115, v110, 1.0
	v_mul_f32_e32 v123, v71, v115
	v_cvt_pk_bf16_f32 v124, v120, v121
	v_cvt_pk_bf16_f32 v125, v122, v123
	global_store_dwordx2 v196, v[124:125], s[44:45] offset:512
	v_mul_f32_e32 v108, 0xbfb8aa3b, v72
	v_exp_f32_e32 v109, v108
	s_nop 0
	v_add_f32_e32 v110, 1.0, v109
	v_div_scale_f32 v111, s[54:55], v110, v110, 1.0
	v_rcp_f32_e32 v112, v111
	v_div_scale_f32 v113, vcc, 1.0, v110, 1.0
	v_fma_f32 v115, -v111, v112, 1.0
	v_fmac_f32_e32 v112, v115, v112
	v_mul_f32_e32 v114, v113, v112
	v_fma_f32 v115, -v111, v114, v113
	v_fmac_f32_e32 v114, v115, v112
	v_fma_f32 v115, -v111, v114, v113
	v_div_fmas_f32 v115, v115, v112, v114
	v_div_fixup_f32 v115, v115, v110, 1.0
	v_mul_f32_e32 v120, v72, v115
	v_mul_f32_e32 v108, 0xbfb8aa3b, v73
	v_exp_f32_e32 v109, v108
	s_nop 0
	v_add_f32_e32 v110, 1.0, v109
	v_div_scale_f32 v111, s[54:55], v110, v110, 1.0
	v_rcp_f32_e32 v112, v111
	v_div_scale_f32 v113, vcc, 1.0, v110, 1.0
	v_fma_f32 v115, -v111, v112, 1.0
	v_fmac_f32_e32 v112, v115, v112
	v_mul_f32_e32 v114, v113, v112
	v_fma_f32 v115, -v111, v114, v113
	v_fmac_f32_e32 v114, v115, v112
	v_fma_f32 v115, -v111, v114, v113
	v_div_fmas_f32 v115, v115, v112, v114
	v_div_fixup_f32 v115, v115, v110, 1.0
	v_mul_f32_e32 v121, v73, v115
	v_mul_f32_e32 v108, 0xbfb8aa3b, v74
	v_exp_f32_e32 v109, v108
	s_nop 0
	v_add_f32_e32 v110, 1.0, v109
	v_div_scale_f32 v111, s[54:55], v110, v110, 1.0
	v_rcp_f32_e32 v112, v111
	v_div_scale_f32 v113, vcc, 1.0, v110, 1.0
	v_fma_f32 v115, -v111, v112, 1.0
	v_fmac_f32_e32 v112, v115, v112
	v_mul_f32_e32 v114, v113, v112
	v_fma_f32 v115, -v111, v114, v113
	v_fmac_f32_e32 v114, v115, v112
	v_fma_f32 v115, -v111, v114, v113
	v_div_fmas_f32 v115, v115, v112, v114
	v_div_fixup_f32 v115, v115, v110, 1.0
	v_mul_f32_e32 v122, v74, v115
	v_mul_f32_e32 v108, 0xbfb8aa3b, v75
	v_exp_f32_e32 v109, v108
	s_nop 0
	v_add_f32_e32 v110, 1.0, v109
	v_div_scale_f32 v111, s[54:55], v110, v110, 1.0
	v_rcp_f32_e32 v112, v111
	v_div_scale_f32 v113, vcc, 1.0, v110, 1.0
	v_fma_f32 v115, -v111, v112, 1.0
	v_fmac_f32_e32 v112, v115, v112
	v_mul_f32_e32 v114, v113, v112
	v_fma_f32 v115, -v111, v114, v113
	v_fmac_f32_e32 v114, v115, v112
	v_fma_f32 v115, -v111, v114, v113
	v_div_fmas_f32 v115, v115, v112, v114
	v_div_fixup_f32 v115, v115, v110, 1.0
	v_mul_f32_e32 v123, v75, v115
	v_cvt_pk_bf16_f32 v124, v120, v121
	v_cvt_pk_bf16_f32 v125, v122, v123
	global_store_dwordx2 v196, v[124:125], s[44:45] offset:1024
	v_add_f32_e32 v100, v76, v77
	v_add_f32_e32 v100, v100, v78
	v_add_f32_e32 v100, v100, v79
	v_add_f32_e32 v100, v100, v80
	v_add_f32_e32 v100, v100, v81
	v_add_f32_e32 v100, v100, v82
	v_add_f32_e32 v100, v100, v83
	v_add_f32_e32 v100, v100, v84
	v_add_f32_e32 v100, v100, v85
	v_add_f32_e32 v100, v100, v86
	v_add_f32_e32 v100, v100, v87
	s_nop 1
	v_add_f32_dpp v100, v100, v100 row_shr:1 row_mask:0xf bank_mask:0xf bound_ctrl:1
	s_nop 1
	v_add_f32_dpp v100, v100, v100 row_shr:2 row_mask:0xf bank_mask:0xf bound_ctrl:1
	s_nop 1
	v_add_f32_dpp v100, v100, v100 row_shr:4 row_mask:0xf bank_mask:0xf bound_ctrl:1
	s_nop 1
	v_add_f32_dpp v100, v100, v100 row_shr:8 row_mask:0xf bank_mask:0xf bound_ctrl:1
	s_nop 1
	v_add_f32_dpp v100, v100, v100 row_bcast:15 row_mask:0xa bank_mask:0xf
	s_nop 1
	v_add_f32_dpp v100, v100, v100 row_bcast:31 row_mask:0xc bank_mask:0xf
	s_nop 0
	v_readlane_b32 s53, v100, 63
	s_nop 1
	v_mov_b32_e32 v101, s53
	v_fmac_f32_e32 v76, 0xbaaaaaab, v101
	v_fmac_f32_e32 v77, 0xbaaaaaab, v101
	v_fmac_f32_e32 v78, 0xbaaaaaab, v101
	v_fmac_f32_e32 v79, 0xbaaaaaab, v101
	v_fmac_f32_e32 v80, 0xbaaaaaab, v101
	v_fmac_f32_e32 v81, 0xbaaaaaab, v101
	v_fmac_f32_e32 v82, 0xbaaaaaab, v101
	v_fmac_f32_e32 v83, 0xbaaaaaab, v101
	v_fmac_f32_e32 v84, 0xbaaaaaab, v101
	v_fmac_f32_e32 v85, 0xbaaaaaab, v101
	v_fmac_f32_e32 v86, 0xbaaaaaab, v101
	v_fmac_f32_e32 v87, 0xbaaaaaab, v101
	v_mul_f32_e32 v102, v76, v76
	v_fmac_f32_e32 v102, v77, v77
	v_fmac_f32_e32 v102, v78, v78
	v_fmac_f32_e32 v102, v79, v79
	v_fmac_f32_e32 v102, v80, v80
	v_fmac_f32_e32 v102, v81, v81
	v_fmac_f32_e32 v102, v82, v82
	v_fmac_f32_e32 v102, v83, v83
	v_fmac_f32_e32 v102, v84, v84
	v_fmac_f32_e32 v102, v85, v85
	v_fmac_f32_e32 v102, v86, v86
	v_fmac_f32_e32 v102, v87, v87
	s_nop 1
	v_add_f32_dpp v102, v102, v102 row_shr:1 row_mask:0xf bank_mask:0xf bound_ctrl:1
	s_nop 1
	v_add_f32_dpp v102, v102, v102 row_shr:2 row_mask:0xf bank_mask:0xf bound_ctrl:1
	s_nop 1
	v_add_f32_dpp v102, v102, v102 row_shr:4 row_mask:0xf bank_mask:0xf bound_ctrl:1
	s_nop 1
	v_add_f32_dpp v102, v102, v102 row_shr:8 row_mask:0xf bank_mask:0xf bound_ctrl:1
	s_nop 1
	v_add_f32_dpp v102, v102, v102 row_bcast:15 row_mask:0xa bank_mask:0xf
	s_nop 1
	v_add_f32_dpp v102, v102, v102 row_bcast:31 row_mask:0xc bank_mask:0xf
	s_nop 0
	v_readlane_b32 s53, v102, 63
	s_nop 1
	v_mov_b32_e32 v101, s53
	v_fmamk_f32 v101, v101, 0x3aaaaaab, v197
	v_rsq_f32_e32 v103, v101
	s_nop 0
	v_mul_f32_e32 v76, v76, v103
	v_mul_f32_e32 v77, v77, v103
	v_mul_f32_e32 v78, v78, v103
	v_mul_f32_e32 v79, v79, v103
	v_mul_f32_e32 v80, v80, v103
	v_mul_f32_e32 v81, v81, v103
	v_mul_f32_e32 v82, v82, v103
	v_mul_f32_e32 v83, v83, v103
	v_mul_f32_e32 v84, v84, v103
	v_mul_f32_e32 v85, v85, v103
	v_mul_f32_e32 v86, v86, v103
	v_mul_f32_e32 v87, v87, v103
	v_fma_f32 v76, v222, v76, v234
	v_fma_f32 v77, v223, v77, v235
	v_fma_f32 v78, v224, v78, v236
	v_fma_f32 v79, v225, v79, v237
	v_fma_f32 v80, v226, v80, v238
	v_fma_f32 v81, v227, v81, v239
	v_fma_f32 v82, v228, v82, v240
	v_fma_f32 v83, v229, v83, v241
	v_fma_f32 v84, v230, v84, v242
	v_fma_f32 v85, v231, v85, v243
	v_fma_f32 v86, v232, v86, v244
	v_fma_f32 v87, v233, v87, v245
	s_lshl_b32 s52, s41, 11
	s_add_i32 s52, s52, 12288
	v_add_u32_e32 v196, s52, v3
	v_mul_f32_e32 v108, 0xbfb8aa3b, v76
	v_exp_f32_e32 v109, v108
	s_nop 0
	v_add_f32_e32 v110, 1.0, v109
	v_div_scale_f32 v111, s[54:55], v110, v110, 1.0
	v_rcp_f32_e32 v112, v111
	v_div_scale_f32 v113, vcc, 1.0, v110, 1.0
	v_fma_f32 v115, -v111, v112, 1.0
	v_fmac_f32_e32 v112, v115, v112
	v_mul_f32_e32 v114, v113, v112
	v_fma_f32 v115, -v111, v114, v113
	v_fmac_f32_e32 v114, v115, v112
	v_fma_f32 v115, -v111, v114, v113
	v_div_fmas_f32 v115, v115, v112, v114
	v_div_fixup_f32 v115, v115, v110, 1.0
	v_mul_f32_e32 v120, v76, v115
	v_mul_f32_e32 v108, 0xbfb8aa3b, v77
	v_exp_f32_e32 v109, v108
	s_nop 0
	v_add_f32_e32 v110, 1.0, v109
	v_div_scale_f32 v111, s[54:55], v110, v110, 1.0
	v_rcp_f32_e32 v112, v111
	v_div_scale_f32 v113, vcc, 1.0, v110, 1.0
	v_fma_f32 v115, -v111, v112, 1.0
	v_fmac_f32_e32 v112, v115, v112
	v_mul_f32_e32 v114, v113, v112
	v_fma_f32 v115, -v111, v114, v113
	v_fmac_f32_e32 v114, v115, v112
	v_fma_f32 v115, -v111, v114, v113
	v_div_fmas_f32 v115, v115, v112, v114
	v_div_fixup_f32 v115, v115, v110, 1.0
	v_mul_f32_e32 v121, v77, v115
	v_mul_f32_e32 v108, 0xbfb8aa3b, v78
	v_exp_f32_e32 v109, v108
	s_nop 0
	v_add_f32_e32 v110, 1.0, v109
	v_div_scale_f32 v111, s[54:55], v110, v110, 1.0
	v_rcp_f32_e32 v112, v111
	v_div_scale_f32 v113, vcc, 1.0, v110, 1.0
	v_fma_f32 v115, -v111, v112, 1.0
	v_fmac_f32_e32 v112, v115, v112
	v_mul_f32_e32 v114, v113, v112
	v_fma_f32 v115, -v111, v114, v113
	v_fmac_f32_e32 v114, v115, v112
	v_fma_f32 v115, -v111, v114, v113
	v_div_fmas_f32 v115, v115, v112, v114
	v_div_fixup_f32 v115, v115, v110, 1.0
	v_mul_f32_e32 v122, v78, v115
	v_mul_f32_e32 v108, 0xbfb8aa3b, v79
	v_exp_f32_e32 v109, v108
	s_nop 0
	v_add_f32_e32 v110, 1.0, v109
	v_div_scale_f32 v111, s[54:55], v110, v110, 1.0
	v_rcp_f32_e32 v112, v111
	v_div_scale_f32 v113, vcc, 1.0, v110, 1.0
	v_fma_f32 v115, -v111, v112, 1.0
	v_fmac_f32_e32 v112, v115, v112
	v_mul_f32_e32 v114, v113, v112
	v_fma_f32 v115, -v111, v114, v113
	v_fmac_f32_e32 v114, v115, v112
	v_fma_f32 v115, -v111, v114, v113
	v_div_fmas_f32 v115, v115, v112, v114
	v_div_fixup_f32 v115, v115, v110, 1.0
	v_mul_f32_e32 v123, v79, v115
	v_cvt_pk_bf16_f32 v124, v120, v121
	v_cvt_pk_bf16_f32 v125, v122, v123
	global_store_dwordx2 v196, v[124:125], s[44:45]
	v_mul_f32_e32 v108, 0xbfb8aa3b, v80
	v_exp_f32_e32 v109, v108
	s_nop 0
	v_add_f32_e32 v110, 1.0, v109
	v_div_scale_f32 v111, s[54:55], v110, v110, 1.0
	v_rcp_f32_e32 v112, v111
	v_div_scale_f32 v113, vcc, 1.0, v110, 1.0
	v_fma_f32 v115, -v111, v112, 1.0
	v_fmac_f32_e32 v112, v115, v112
	v_mul_f32_e32 v114, v113, v112
	v_fma_f32 v115, -v111, v114, v113
	v_fmac_f32_e32 v114, v115, v112
	v_fma_f32 v115, -v111, v114, v113
	v_div_fmas_f32 v115, v115, v112, v114
	v_div_fixup_f32 v115, v115, v110, 1.0
	v_mul_f32_e32 v120, v80, v115
	v_mul_f32_e32 v108, 0xbfb8aa3b, v81
	v_exp_f32_e32 v109, v108
	s_nop 0
	v_add_f32_e32 v110, 1.0, v109
	v_div_scale_f32 v111, s[54:55], v110, v110, 1.0
	v_rcp_f32_e32 v112, v111
	v_div_scale_f32 v113, vcc, 1.0, v110, 1.0
	v_fma_f32 v115, -v111, v112, 1.0
	v_fmac_f32_e32 v112, v115, v112
	v_mul_f32_e32 v114, v113, v112
	v_fma_f32 v115, -v111, v114, v113
	v_fmac_f32_e32 v114, v115, v112
	v_fma_f32 v115, -v111, v114, v113
	v_div_fmas_f32 v115, v115, v112, v114
	v_div_fixup_f32 v115, v115, v110, 1.0
	v_mul_f32_e32 v121, v81, v115
	v_mul_f32_e32 v108, 0xbfb8aa3b, v82
	v_exp_f32_e32 v109, v108
	s_nop 0
	v_add_f32_e32 v110, 1.0, v109
	v_div_scale_f32 v111, s[54:55], v110, v110, 1.0
	v_rcp_f32_e32 v112, v111
	v_div_scale_f32 v113, vcc, 1.0, v110, 1.0
	v_fma_f32 v115, -v111, v112, 1.0
	v_fmac_f32_e32 v112, v115, v112
	v_mul_f32_e32 v114, v113, v112
	v_fma_f32 v115, -v111, v114, v113
	v_fmac_f32_e32 v114, v115, v112
	v_fma_f32 v115, -v111, v114, v113
	v_div_fmas_f32 v115, v115, v112, v114
	v_div_fixup_f32 v115, v115, v110, 1.0
	v_mul_f32_e32 v122, v82, v115
	v_mul_f32_e32 v108, 0xbfb8aa3b, v83
	v_exp_f32_e32 v109, v108
	s_nop 0
	v_add_f32_e32 v110, 1.0, v109
	v_div_scale_f32 v111, s[54:55], v110, v110, 1.0
	v_rcp_f32_e32 v112, v111
	v_div_scale_f32 v113, vcc, 1.0, v110, 1.0
	v_fma_f32 v115, -v111, v112, 1.0
	v_fmac_f32_e32 v112, v115, v112
	v_mul_f32_e32 v114, v113, v112
	v_fma_f32 v115, -v111, v114, v113
	v_fmac_f32_e32 v114, v115, v112
	v_fma_f32 v115, -v111, v114, v113
	v_div_fmas_f32 v115, v115, v112, v114
	v_div_fixup_f32 v115, v115, v110, 1.0
	v_mul_f32_e32 v123, v83, v115
	v_cvt_pk_bf16_f32 v124, v120, v121
	v_cvt_pk_bf16_f32 v125, v122, v123
	global_store_dwordx2 v196, v[124:125], s[44:45] offset:512
	v_mul_f32_e32 v108, 0xbfb8aa3b, v84
	v_exp_f32_e32 v109, v108
	s_nop 0
	v_add_f32_e32 v110, 1.0, v109
	v_div_scale_f32 v111, s[54:55], v110, v110, 1.0
	v_rcp_f32_e32 v112, v111
	v_div_scale_f32 v113, vcc, 1.0, v110, 1.0
	v_fma_f32 v115, -v111, v112, 1.0
	v_fmac_f32_e32 v112, v115, v112
	v_mul_f32_e32 v114, v113, v112
	v_fma_f32 v115, -v111, v114, v113
	v_fmac_f32_e32 v114, v115, v112
	v_fma_f32 v115, -v111, v114, v113
	v_div_fmas_f32 v115, v115, v112, v114
	v_div_fixup_f32 v115, v115, v110, 1.0
	v_mul_f32_e32 v120, v84, v115
	v_mul_f32_e32 v108, 0xbfb8aa3b, v85
	v_exp_f32_e32 v109, v108
	s_nop 0
	v_add_f32_e32 v110, 1.0, v109
	v_div_scale_f32 v111, s[54:55], v110, v110, 1.0
	v_rcp_f32_e32 v112, v111
	v_div_scale_f32 v113, vcc, 1.0, v110, 1.0
	v_fma_f32 v115, -v111, v112, 1.0
	v_fmac_f32_e32 v112, v115, v112
	v_mul_f32_e32 v114, v113, v112
	v_fma_f32 v115, -v111, v114, v113
	v_fmac_f32_e32 v114, v115, v112
	v_fma_f32 v115, -v111, v114, v113
	v_div_fmas_f32 v115, v115, v112, v114
	v_div_fixup_f32 v115, v115, v110, 1.0
	v_mul_f32_e32 v121, v85, v115
	v_mul_f32_e32 v108, 0xbfb8aa3b, v86
	v_exp_f32_e32 v109, v108
	s_nop 0
	v_add_f32_e32 v110, 1.0, v109
	v_div_scale_f32 v111, s[54:55], v110, v110, 1.0
	v_rcp_f32_e32 v112, v111
	v_div_scale_f32 v113, vcc, 1.0, v110, 1.0
	v_fma_f32 v115, -v111, v112, 1.0
	v_fmac_f32_e32 v112, v115, v112
	v_mul_f32_e32 v114, v113, v112
	v_fma_f32 v115, -v111, v114, v113
	v_fmac_f32_e32 v114, v115, v112
	v_fma_f32 v115, -v111, v114, v113
	v_div_fmas_f32 v115, v115, v112, v114
	v_div_fixup_f32 v115, v115, v110, 1.0
	v_mul_f32_e32 v122, v86, v115
	v_mul_f32_e32 v108, 0xbfb8aa3b, v87
	v_exp_f32_e32 v109, v108
	s_nop 0
	v_add_f32_e32 v110, 1.0, v109
	v_div_scale_f32 v111, s[54:55], v110, v110, 1.0
	v_rcp_f32_e32 v112, v111
	v_div_scale_f32 v113, vcc, 1.0, v110, 1.0
	v_fma_f32 v115, -v111, v112, 1.0
	v_fmac_f32_e32 v112, v115, v112
	v_mul_f32_e32 v114, v113, v112
	v_fma_f32 v115, -v111, v114, v113
	v_fmac_f32_e32 v114, v115, v112
	v_fma_f32 v115, -v111, v114, v113
	v_div_fmas_f32 v115, v115, v112, v114
	v_div_fixup_f32 v115, v115, v110, 1.0
	v_mul_f32_e32 v123, v87, v115
	v_cvt_pk_bf16_f32 v124, v120, v121
	v_cvt_pk_bf16_f32 v125, v122, v123
	global_store_dwordx2 v196, v[124:125], s[44:45] offset:1024
	v_add_f32_e32 v100, v88, v89
	v_add_f32_e32 v100, v100, v90
	v_add_f32_e32 v100, v100, v91
	v_add_f32_e32 v100, v100, v92
	v_add_f32_e32 v100, v100, v93
	v_add_f32_e32 v100, v100, v94
	v_add_f32_e32 v100, v100, v95
	v_add_f32_e32 v100, v100, v96
	v_add_f32_e32 v100, v100, v97
	v_add_f32_e32 v100, v100, v98
	v_add_f32_e32 v100, v100, v99
	s_nop 1
	v_add_f32_dpp v100, v100, v100 row_shr:1 row_mask:0xf bank_mask:0xf bound_ctrl:1
	s_nop 1
	v_add_f32_dpp v100, v100, v100 row_shr:2 row_mask:0xf bank_mask:0xf bound_ctrl:1
	s_nop 1
	v_add_f32_dpp v100, v100, v100 row_shr:4 row_mask:0xf bank_mask:0xf bound_ctrl:1
	s_nop 1
	v_add_f32_dpp v100, v100, v100 row_shr:8 row_mask:0xf bank_mask:0xf bound_ctrl:1
	s_nop 1
	v_add_f32_dpp v100, v100, v100 row_bcast:15 row_mask:0xa bank_mask:0xf
	s_nop 1
	v_add_f32_dpp v100, v100, v100 row_bcast:31 row_mask:0xc bank_mask:0xf
	s_nop 0
	v_readlane_b32 s53, v100, 63
	s_nop 1
	v_mov_b32_e32 v101, s53
	v_fmac_f32_e32 v88, 0xbaaaaaab, v101
	v_fmac_f32_e32 v89, 0xbaaaaaab, v101
	v_fmac_f32_e32 v90, 0xbaaaaaab, v101
	v_fmac_f32_e32 v91, 0xbaaaaaab, v101
	v_fmac_f32_e32 v92, 0xbaaaaaab, v101
	v_fmac_f32_e32 v93, 0xbaaaaaab, v101
	v_fmac_f32_e32 v94, 0xbaaaaaab, v101
	v_fmac_f32_e32 v95, 0xbaaaaaab, v101
	v_fmac_f32_e32 v96, 0xbaaaaaab, v101
	v_fmac_f32_e32 v97, 0xbaaaaaab, v101
	v_fmac_f32_e32 v98, 0xbaaaaaab, v101
	v_fmac_f32_e32 v99, 0xbaaaaaab, v101
	v_mul_f32_e32 v102, v88, v88
	v_fmac_f32_e32 v102, v89, v89
	v_fmac_f32_e32 v102, v90, v90
	v_fmac_f32_e32 v102, v91, v91
	v_fmac_f32_e32 v102, v92, v92
	v_fmac_f32_e32 v102, v93, v93
	v_fmac_f32_e32 v102, v94, v94
	v_fmac_f32_e32 v102, v95, v95
	v_fmac_f32_e32 v102, v96, v96
	v_fmac_f32_e32 v102, v97, v97
	v_fmac_f32_e32 v102, v98, v98
	v_fmac_f32_e32 v102, v99, v99
	s_nop 1
	v_add_f32_dpp v102, v102, v102 row_shr:1 row_mask:0xf bank_mask:0xf bound_ctrl:1
	s_nop 1
	v_add_f32_dpp v102, v102, v102 row_shr:2 row_mask:0xf bank_mask:0xf bound_ctrl:1
	s_nop 1
	v_add_f32_dpp v102, v102, v102 row_shr:4 row_mask:0xf bank_mask:0xf bound_ctrl:1
	s_nop 1
	v_add_f32_dpp v102, v102, v102 row_shr:8 row_mask:0xf bank_mask:0xf bound_ctrl:1
	s_nop 1
	v_add_f32_dpp v102, v102, v102 row_bcast:15 row_mask:0xa bank_mask:0xf
	s_nop 1
	v_add_f32_dpp v102, v102, v102 row_bcast:31 row_mask:0xc bank_mask:0xf
	s_nop 0
	v_readlane_b32 s53, v102, 63
	s_nop 1
	v_mov_b32_e32 v101, s53
	v_fmamk_f32 v101, v101, 0x3aaaaaab, v197
	v_rsq_f32_e32 v103, v101
	s_nop 0
	v_mul_f32_e32 v88, v88, v103
	v_mul_f32_e32 v89, v89, v103
	v_mul_f32_e32 v90, v90, v103
	v_mul_f32_e32 v91, v91, v103
	v_mul_f32_e32 v92, v92, v103
	v_mul_f32_e32 v93, v93, v103
	v_mul_f32_e32 v94, v94, v103
	v_mul_f32_e32 v95, v95, v103
	v_mul_f32_e32 v96, v96, v103
	v_mul_f32_e32 v97, v97, v103
	v_mul_f32_e32 v98, v98, v103
	v_mul_f32_e32 v99, v99, v103
	v_fma_f32 v88, v222, v88, v234
	v_fma_f32 v89, v223, v89, v235
	v_fma_f32 v90, v224, v90, v236
	v_fma_f32 v91, v225, v91, v237
	v_fma_f32 v92, v226, v92, v238
	v_fma_f32 v93, v227, v93, v239
	v_fma_f32 v94, v228, v94, v240
	v_fma_f32 v95, v229, v95, v241
	v_fma_f32 v96, v230, v96, v242
	v_fma_f32 v97, v231, v97, v243
	v_fma_f32 v98, v232, v98, v244
	v_fma_f32 v99, v233, v99, v245
	s_lshl_b32 s52, s41, 11
	s_add_i32 s52, s52, 14336
	v_add_u32_e32 v196, s52, v3
	v_mul_f32_e32 v108, 0xbfb8aa3b, v88
	v_exp_f32_e32 v109, v108
	s_nop 0
	v_add_f32_e32 v110, 1.0, v109
	v_div_scale_f32 v111, s[54:55], v110, v110, 1.0
	v_rcp_f32_e32 v112, v111
	v_div_scale_f32 v113, vcc, 1.0, v110, 1.0
	v_fma_f32 v115, -v111, v112, 1.0
	v_fmac_f32_e32 v112, v115, v112
	v_mul_f32_e32 v114, v113, v112
	v_fma_f32 v115, -v111, v114, v113
	v_fmac_f32_e32 v114, v115, v112
	v_fma_f32 v115, -v111, v114, v113
	v_div_fmas_f32 v115, v115, v112, v114
	v_div_fixup_f32 v115, v115, v110, 1.0
	v_mul_f32_e32 v120, v88, v115
	v_mul_f32_e32 v108, 0xbfb8aa3b, v89
	v_exp_f32_e32 v109, v108
	s_nop 0
	v_add_f32_e32 v110, 1.0, v109
	v_div_scale_f32 v111, s[54:55], v110, v110, 1.0
	v_rcp_f32_e32 v112, v111
	v_div_scale_f32 v113, vcc, 1.0, v110, 1.0
	v_fma_f32 v115, -v111, v112, 1.0
	v_fmac_f32_e32 v112, v115, v112
	v_mul_f32_e32 v114, v113, v112
	v_fma_f32 v115, -v111, v114, v113
	v_fmac_f32_e32 v114, v115, v112
	v_fma_f32 v115, -v111, v114, v113
	v_div_fmas_f32 v115, v115, v112, v114
	v_div_fixup_f32 v115, v115, v110, 1.0
	v_mul_f32_e32 v121, v89, v115
	v_mul_f32_e32 v108, 0xbfb8aa3b, v90
	v_exp_f32_e32 v109, v108
	s_nop 0
	v_add_f32_e32 v110, 1.0, v109
	v_div_scale_f32 v111, s[54:55], v110, v110, 1.0
	v_rcp_f32_e32 v112, v111
	v_div_scale_f32 v113, vcc, 1.0, v110, 1.0
	v_fma_f32 v115, -v111, v112, 1.0
	v_fmac_f32_e32 v112, v115, v112
	v_mul_f32_e32 v114, v113, v112
	v_fma_f32 v115, -v111, v114, v113
	v_fmac_f32_e32 v114, v115, v112
	v_fma_f32 v115, -v111, v114, v113
	v_div_fmas_f32 v115, v115, v112, v114
	v_div_fixup_f32 v115, v115, v110, 1.0
	v_mul_f32_e32 v122, v90, v115
	v_mul_f32_e32 v108, 0xbfb8aa3b, v91
	v_exp_f32_e32 v109, v108
	s_nop 0
	v_add_f32_e32 v110, 1.0, v109
	v_div_scale_f32 v111, s[54:55], v110, v110, 1.0
	v_rcp_f32_e32 v112, v111
	v_div_scale_f32 v113, vcc, 1.0, v110, 1.0
	v_fma_f32 v115, -v111, v112, 1.0
	v_fmac_f32_e32 v112, v115, v112
	v_mul_f32_e32 v114, v113, v112
	v_fma_f32 v115, -v111, v114, v113
	v_fmac_f32_e32 v114, v115, v112
	v_fma_f32 v115, -v111, v114, v113
	v_div_fmas_f32 v115, v115, v112, v114
	v_div_fixup_f32 v115, v115, v110, 1.0
	v_mul_f32_e32 v123, v91, v115
	v_cvt_pk_bf16_f32 v124, v120, v121
	v_cvt_pk_bf16_f32 v125, v122, v123
	global_store_dwordx2 v196, v[124:125], s[44:45]
	v_mul_f32_e32 v108, 0xbfb8aa3b, v92
	v_exp_f32_e32 v109, v108
	s_nop 0
	v_add_f32_e32 v110, 1.0, v109
	v_div_scale_f32 v111, s[54:55], v110, v110, 1.0
	v_rcp_f32_e32 v112, v111
	v_div_scale_f32 v113, vcc, 1.0, v110, 1.0
	v_fma_f32 v115, -v111, v112, 1.0
	v_fmac_f32_e32 v112, v115, v112
	v_mul_f32_e32 v114, v113, v112
	v_fma_f32 v115, -v111, v114, v113
	v_fmac_f32_e32 v114, v115, v112
	v_fma_f32 v115, -v111, v114, v113
	v_div_fmas_f32 v115, v115, v112, v114
	v_div_fixup_f32 v115, v115, v110, 1.0
	v_mul_f32_e32 v120, v92, v115
	v_mul_f32_e32 v108, 0xbfb8aa3b, v93
	v_exp_f32_e32 v109, v108
	s_nop 0
	v_add_f32_e32 v110, 1.0, v109
	v_div_scale_f32 v111, s[54:55], v110, v110, 1.0
	v_rcp_f32_e32 v112, v111
	v_div_scale_f32 v113, vcc, 1.0, v110, 1.0
	v_fma_f32 v115, -v111, v112, 1.0
	v_fmac_f32_e32 v112, v115, v112
	v_mul_f32_e32 v114, v113, v112
	v_fma_f32 v115, -v111, v114, v113
	v_fmac_f32_e32 v114, v115, v112
	v_fma_f32 v115, -v111, v114, v113
	v_div_fmas_f32 v115, v115, v112, v114
	v_div_fixup_f32 v115, v115, v110, 1.0
	v_mul_f32_e32 v121, v93, v115
	v_mul_f32_e32 v108, 0xbfb8aa3b, v94
	v_exp_f32_e32 v109, v108
	s_nop 0
	v_add_f32_e32 v110, 1.0, v109
	v_div_scale_f32 v111, s[54:55], v110, v110, 1.0
	v_rcp_f32_e32 v112, v111
	v_div_scale_f32 v113, vcc, 1.0, v110, 1.0
	v_fma_f32 v115, -v111, v112, 1.0
	v_fmac_f32_e32 v112, v115, v112
	v_mul_f32_e32 v114, v113, v112
	v_fma_f32 v115, -v111, v114, v113
	v_fmac_f32_e32 v114, v115, v112
	v_fma_f32 v115, -v111, v114, v113
	v_div_fmas_f32 v115, v115, v112, v114
	v_div_fixup_f32 v115, v115, v110, 1.0
	v_mul_f32_e32 v122, v94, v115
	v_mul_f32_e32 v108, 0xbfb8aa3b, v95
	v_exp_f32_e32 v109, v108
	s_nop 0
	v_add_f32_e32 v110, 1.0, v109
	v_div_scale_f32 v111, s[54:55], v110, v110, 1.0
	v_rcp_f32_e32 v112, v111
	v_div_scale_f32 v113, vcc, 1.0, v110, 1.0
	v_fma_f32 v115, -v111, v112, 1.0
	v_fmac_f32_e32 v112, v115, v112
	v_mul_f32_e32 v114, v113, v112
	v_fma_f32 v115, -v111, v114, v113
	v_fmac_f32_e32 v114, v115, v112
	v_fma_f32 v115, -v111, v114, v113
	v_div_fmas_f32 v115, v115, v112, v114
	v_div_fixup_f32 v115, v115, v110, 1.0
	v_mul_f32_e32 v123, v95, v115
	v_cvt_pk_bf16_f32 v124, v120, v121
	v_cvt_pk_bf16_f32 v125, v122, v123
	global_store_dwordx2 v196, v[124:125], s[44:45] offset:512
	v_mul_f32_e32 v108, 0xbfb8aa3b, v96
	v_exp_f32_e32 v109, v108
	s_nop 0
	v_add_f32_e32 v110, 1.0, v109
	v_div_scale_f32 v111, s[54:55], v110, v110, 1.0
	v_rcp_f32_e32 v112, v111
	v_div_scale_f32 v113, vcc, 1.0, v110, 1.0
	v_fma_f32 v115, -v111, v112, 1.0
	v_fmac_f32_e32 v112, v115, v112
	v_mul_f32_e32 v114, v113, v112
	v_fma_f32 v115, -v111, v114, v113
	v_fmac_f32_e32 v114, v115, v112
	v_fma_f32 v115, -v111, v114, v113
	v_div_fmas_f32 v115, v115, v112, v114
	v_div_fixup_f32 v115, v115, v110, 1.0
	v_mul_f32_e32 v120, v96, v115
	v_mul_f32_e32 v108, 0xbfb8aa3b, v97
	v_exp_f32_e32 v109, v108
	s_nop 0
	v_add_f32_e32 v110, 1.0, v109
	v_div_scale_f32 v111, s[54:55], v110, v110, 1.0
	v_rcp_f32_e32 v112, v111
	v_div_scale_f32 v113, vcc, 1.0, v110, 1.0
	v_fma_f32 v115, -v111, v112, 1.0
	v_fmac_f32_e32 v112, v115, v112
	v_mul_f32_e32 v114, v113, v112
	v_fma_f32 v115, -v111, v114, v113
	v_fmac_f32_e32 v114, v115, v112
	v_fma_f32 v115, -v111, v114, v113
	v_div_fmas_f32 v115, v115, v112, v114
	v_div_fixup_f32 v115, v115, v110, 1.0
	v_mul_f32_e32 v121, v97, v115
	v_mul_f32_e32 v108, 0xbfb8aa3b, v98
	v_exp_f32_e32 v109, v108
	s_nop 0
	v_add_f32_e32 v110, 1.0, v109
	v_div_scale_f32 v111, s[54:55], v110, v110, 1.0
	v_rcp_f32_e32 v112, v111
	v_div_scale_f32 v113, vcc, 1.0, v110, 1.0
	v_fma_f32 v115, -v111, v112, 1.0
	v_fmac_f32_e32 v112, v115, v112
	v_mul_f32_e32 v114, v113, v112
	v_fma_f32 v115, -v111, v114, v113
	v_fmac_f32_e32 v114, v115, v112
	v_fma_f32 v115, -v111, v114, v113
	v_div_fmas_f32 v115, v115, v112, v114
	v_div_fixup_f32 v115, v115, v110, 1.0
	v_mul_f32_e32 v122, v98, v115
	v_mul_f32_e32 v108, 0xbfb8aa3b, v99
	v_exp_f32_e32 v109, v108
	s_nop 0
	v_add_f32_e32 v110, 1.0, v109
	v_div_scale_f32 v111, s[54:55], v110, v110, 1.0
	v_rcp_f32_e32 v112, v111
	v_div_scale_f32 v113, vcc, 1.0, v110, 1.0
	v_fma_f32 v115, -v111, v112, 1.0
	v_fmac_f32_e32 v112, v115, v112
	v_mul_f32_e32 v114, v113, v112
	v_fma_f32 v115, -v111, v114, v113
	v_fmac_f32_e32 v114, v115, v112
	v_fma_f32 v115, -v111, v114, v113
	v_div_fmas_f32 v115, v115, v112, v114
	v_div_fixup_f32 v115, v115, v110, 1.0
	v_mul_f32_e32 v123, v99, v115
	v_cvt_pk_bf16_f32 v124, v120, v121
	v_cvt_pk_bf16_f32 v125, v122, v123
	global_store_dwordx2 v196, v[124:125], s[44:45] offset:1024
	s_waitcnt vmcnt(0)
	s_branch .LBB0_280
.Lcv_notask:
	v_readlane_b32 s4, v254, 40
	s_waitcnt vmcnt(0)
	v_mov_b32_e32 v101, v100
	ds_write_b128 v101, v[104:107]
	v_add_u32_e32 v101, 0x2000, v100
	ds_write_b128 v101, v[108:111]
	v_add_u32_e32 v101, 0x4000, v100
	ds_write_b128 v101, v[112:115]
	v_add_u32_e32 v101, 0x6000, v100
	ds_write_b128 v101, v[116:119]
	v_add_u32_e32 v101, 0x8000, v100
	ds_write_b128 v101, v[120:123]
	v_add_u32_e32 v101, 0xa000, v100
	ds_write_b128 v101, v[124:127]
	v_add_u32_e32 v101, 0xc000, v100
	ds_write_b128 v101, v[128:131]
	v_add_u32_e32 v101, 0xe000, v100
	ds_write_b128 v101, v[132:135]
	v_add_u32_e32 v101, 0x10000, v100
	ds_write_b128 v101, v[136:139]
	v_add_u32_e32 v101, 0x12000, v100
	ds_write_b128 v101, v[140:143]
	v_add_u32_e32 v101, 0x14000, v100
	ds_write_b128 v101, v[144:147]
	s_cmp_lt_u32 s4, 5
	s_cbranch_scc0 .Lcv_pre_skip2_b
	v_add_u32_e32 v101, 0x16000, v100
	ds_write_b128 v101, v[148:151]
.Lcv_pre_skip2_b:
	s_waitcnt lgkmcnt(0)
	s_barrier
.LBB0_280:
	s_setprio 0
	v_readlane_b32 s0, v254, 41
	s_cmp_lt_i32 s0, 0
	s_cbranch_scc1 .LBB0_289
	v_readlane_b32 s4, v254, 7
	v_readlane_b32 s12, v254, 15
	v_readlane_b32 s13, v254, 16
	v_readlane_b32 s14, v254, 17
	v_readlane_b32 s15, v254, 18
	v_readlane_b32 s16, v254, 19
	v_readlane_b32 s17, v254, 20
	v_lshlrev_b32_e32 v1, 2, v199
	v_readlane_b32 s18, v254, 21
	v_readlane_b32 s19, v254, 22
	s_mov_b64 s[12:13], s[16:17]
	s_mov_b64 s[14:15], s[18:19]
	global_load_dword v2, v1, s[12:13]
	global_load_dword v3, v1, s[14:15]
	v_mbcnt_lo_u32_b32 v1, -1, 0
	v_mbcnt_hi_u32_b32 v1, -1, v1
	v_and_b32_e32 v4, 64, v1
	v_xor_b32_e32 v5, 1, v1
	v_add_u32_e32 v4, 64, v4
	v_cmp_lt_i32_e32 vcc, v5, v4
	v_xor_b32_e32 v6, 2, v1
	v_xor_b32_e32 v7, 4, v1
	v_cndmask_b32_e32 v5, v1, v5, vcc
	v_lshlrev_b32_e32 v5, 2, v5
	v_cmp_lt_i32_e32 vcc, v6, v4
	v_xor_b32_e32 v8, 8, v1
	v_xor_b32_e32 v9, 16, v1
	v_cndmask_b32_e32 v6, v1, v6, vcc
	v_lshlrev_b32_e32 v6, 2, v6
	v_cmp_lt_i32_e32 vcc, v7, v4
	v_xor_b32_e32 v10, 32, v1
	v_readlane_b32 s0, v254, 41
	v_cndmask_b32_e32 v7, v1, v7, vcc
	v_lshlrev_b32_e32 v7, 2, v7
	v_cmp_lt_i32_e32 vcc, v8, v4
	s_cmpk_gt_u32 s0, 0x7ff
	s_mov_b32 s1, 0
	v_readlane_b32 s5, v254, 8
	v_readlane_b32 s6, v254, 9
	v_readlane_b32 s7, v254, 10
	v_readlane_b32 s8, v254, 11
	v_readlane_b32 s9, v254, 12
	v_readlane_b32 s10, v254, 13
	v_readlane_b32 s11, v254, 14
	s_waitcnt vmcnt(0)
	v_and_b32_e32 v11, 0x7fffffff, v2
	v_and_b32_e32 v12, 0x7fffffff, v3
	ds_bpermute_b32 v11, v5, v11
	ds_bpermute_b32 v5, v5, v12
	v_max_f32_e64 v2, |v2|, |v2|
	v_max_f32_e64 v3, |v3|, |v3|
	s_waitcnt lgkmcnt(1)
	v_max_f32_e32 v11, v11, v11
	s_waitcnt lgkmcnt(0)
	v_max_f32_e32 v5, v5, v5
	v_max_f32_e32 v2, v2, v11
	v_max_f32_e32 v3, v3, v5
	ds_bpermute_b32 v5, v6, v2
	ds_bpermute_b32 v6, v6, v3
	s_waitcnt lgkmcnt(1)
	v_max_f32_e32 v5, v5, v5
	s_waitcnt lgkmcnt(0)
	v_max_f32_e32 v6, v6, v6
	v_max_f32_e32 v2, v2, v5
	v_max_f32_e32 v3, v3, v6
	ds_bpermute_b32 v5, v7, v2
	ds_bpermute_b32 v6, v7, v3
	v_cndmask_b32_e32 v7, v1, v8, vcc
	v_lshlrev_b32_e32 v7, 2, v7
	v_cmp_lt_i32_e32 vcc, v9, v4
	s_waitcnt lgkmcnt(1)
	v_max_f32_e32 v5, v5, v5
	s_waitcnt lgkmcnt(0)
	v_max_f32_e32 v6, v6, v6
	v_max_f32_e32 v2, v2, v5
	v_max_f32_e32 v3, v3, v6
	ds_bpermute_b32 v5, v7, v2
	ds_bpermute_b32 v6, v7, v3
	v_cndmask_b32_e32 v7, v1, v9, vcc
	v_lshlrev_b32_e32 v7, 2, v7
	v_cmp_lt_i32_e32 vcc, v10, v4
	s_waitcnt lgkmcnt(1)
	v_max_f32_e32 v5, v5, v5
	s_waitcnt lgkmcnt(0)
	v_max_f32_e32 v6, v6, v6
	v_max_f32_e32 v2, v2, v5
	v_max_f32_e32 v5, v3, v6
	ds_bpermute_b32 v3, v7, v2
	ds_bpermute_b32 v6, v7, v5
	v_cndmask_b32_e32 v1, v1, v10, vcc
	v_lshlrev_b32_e32 v1, 2, v1
	s_waitcnt lgkmcnt(1)
	v_max_f32_e32 v3, v3, v3
	s_waitcnt lgkmcnt(0)
	v_max_f32_e32 v4, v6, v6
	v_max_f32_e32 v3, v2, v3
	v_max_f32_e32 v2, v5, v4
	ds_bpermute_b32 v5, v1, v3
	ds_bpermute_b32 v4, v1, v2
	s_cbranch_scc1 .LBB0_289
	s_waitcnt lgkmcnt(1)
	v_max_f32_e32 v5, v5, v5
	v_max_f32_e32 v3, v3, v3
	v_readlane_b32 s0, v254, 39
	v_max_f32_e32 v3, v3, v5
	s_waitcnt lgkmcnt(0)
	v_max_f32_e32 v4, v4, v4
	v_max_f32_e32 v2, v2, v2
	s_bfe_u32 s0, s0, 0x20006
	v_mul_f32_e32 v3, 0x4138aa3b, v3
	v_max_f32_e32 v2, v2, v4
	s_lshl_b32 s12, s0, 6
	s_lshl_b32 s4, s0, 7
	v_mul_f32_e32 v2, v3, v2
	s_add_u32 s4, s72, s4
	v_mul_f32_e32 v180, 0x3f828f5c, v2
	v_lshrrev_b32_e32 v3, 5, v199
	v_mov_b32_e32 v2, 0
	s_addc_u32 s5, s73, 0
	s_lshl_b32 s0, s0, 15
	v_lshlrev_b32_e32 v8, 4, v3
	v_mov_b32_e32 v9, v2
	s_add_u32 s0, s72, s0
	v_lshl_add_u64 v[8:9], s[4:5], 0, v[8:9]
	s_mov_b64 s[4:5], 0x9200000
	s_addc_u32 s10, s73, 0
	v_lshl_add_u64 v[164:165], v[8:9], 0, s[4:5]
	s_add_u32 s4, s0, 0x80000
	s_addc_u32 s5, s10, 0
	s_add_u32 s6, s0, 0xc0000
	s_addc_u32 s7, s10, 0
	v_lshlrev_b32_e32 v8, 4, v199
	v_mov_b32_e32 v9, v2
	v_lshl_add_u64 v[166:167], s[4:5], 0, v[8:9]
	v_lshl_add_u64 v[168:169], s[6:7], 0, v[8:9]
	s_mov_b64 s[8:9], 0x1000
	v_lshl_add_u64 v[170:171], v[166:167], 0, s[8:9]
	v_lshl_add_u64 v[172:173], v[168:169], 0, s[8:9]
	s_add_u32 s8, s0, 0x82000
	v_lshlrev_b32_e32 v4, 3, v199
	v_lshlrev_b32_e32 v6, 2, v3
	s_addc_u32 s9, s10, 0
	s_mov_b64 s[10:11], 0x2000
	v_and_b32_e32 v181, 31, v198
	v_lshl_add_u64 v[174:175], v[168:169], 0, s[10:11]
	v_lshlrev_b32_e32 v182, 1, v4
	s_lshl_b32 s0, s12, 1
	v_lshlrev_b32_e32 v176, 1, v6
	s_mov_b64 s[10:11], 0x5a00600
	s_mov_b32 s16, 0x5a00000
	v_readlane_b32 s17, v254, 41
	s_branch .LBB0_284
